# attention PV phase: per-group lgkmcnt(0) replaced by per-MFMA counted waits (tr reads of the next group stay in flight); redundant setprio 0/1 pairs removed in GEMM loops
# speedup vs baseline: 1.0047x; 1.0032x over previous
; #define PG8_STAGE(bufoff, gbase, voff) do { _Pragma("unroll") for (int _i = 0; _i < 2; ++_i) \
;         __builtin_amdgcn_global_load_lds((const unsigned*)((const char*)(gbase) + (voff)[_i]), (PG8_LAS unsigned*)(lds + (bufoff) + ldsw + _i * 8192), 16, 0, 0); } while (0)
; #define PG8_LDA(dst, b, h) do { _Pragma("unroll") for (int m = 0; m < 4; ++m) _Pragma("unroll") for (int k = 0; k < 2; ++k) dst[m][k] = *(const PG8_LAS bf16x8*)(lds + PG8_SA(b, h) + aoff + m * 2048 + k * 1024); } while (0)
; #define PG8_LDB(dst, b, h) do { _Pragma("unroll") for (int n = 0; n < 2; ++n) _Pragma("unroll") for (int k = 0; k < 2; ++k) dst[n][k] = *(const PG8_LAS bf16x8*)(lds + PG8_SB(b, h) + boff + n * 2048 + k * 1024); } while (0)
; #define PG8_MMA(ai, bj, At, Bt) do { __builtin_amdgcn_s_setprio(1); _Pragma("unroll") for (int m = 0; m < 4; ++m) _Pragma("unroll") for (int n = 0; n < 2; ++n) _Pragma("unroll") for (int k = 0; k < 2; ++k) \
;         acc[ai][bj][m][n] = __builtin_amdgcn_mfma_f32_16x16x32_bf16(Bt[n][k], At[m][k], acc[ai][bj][m][n], 0, 0, 0); __builtin_amdgcn_s_setprio(0); } while (0)
; #define PG8_WAIT_V(n) asm volatile("s_waitcnt vmcnt(" #n ")" ::: "memory")
; #define PG8_WAIT_L(n) asm volatile("s_waitcnt lgkmcnt(" #n ")" ::: "memory")
; #define PG8_BAR __builtin_amdgcn_s_barrier()
; #define PG8_SCHED __builtin_amdgcn_sched_barrier(0)
; template <class Epi, class Sched, bool ALIGN_EPI = false, bool SP2 = false>
; __device__ __forceinline__ void gemm_phase(PG8_LAS unsigned char* lds, const Gemm g, const Sched& S, const Epi& E) {
;     ...
;             PG8_LDB(B0, 0, 0); PG8_LDB(B1, 0, 1); PG8_SCHED; PG8_LDA(At, 0, 0); PG8_STAGE(PG8_SA(1, 1), a1 + hstep, voffA);
;             PG8_WAIT_V(8); PG8_WAIT_L(0); PG8_BAR; PG8_MMA(0, 0, At, B0); PG8_MMA(0, 1, At, B1); PG8_BAR; PG8_SCHED;
;             PG8_LDA(At, 0, 1); PG8_STAGE(PG8_SB(0, 0), b2, voffB); PG8_STAGE(PG8_SB(0, 1), b2 + hstep, voffB); PG8_STAGE(PG8_SA(0, 0), a2, voffA);
;             PG8_WAIT_V(8); PG8_WAIT_L(0); PG8_BAR; if (full) { PG8_MMA(1, 0, At, B0); PG8_MMA(1, 1, At, B1); } PG8_BAR; PG8_SCHED;
.LBB0_166:
	s_add_u32 s2, s48, 0xfffc0080
	s_addc_u32 s3, s49, -1
	s_add_i32 s4, 0, 0x10000
	s_cmp_eq_u32 s12, 12
	s_cselect_b32 s35, s81, s3
	s_cselect_b32 s34, s94, s2
	v_add_u32_e32 v128, s4, v228
	s_cselect_b32 s29, s79, s51
	s_cselect_b32 s28, s95, s50
	s_add_i32 s5, 0, 0x14000
	ds_read_b128 v[146:149], v128
	ds_read_b128 v[150:153], v128 offset:1024
	ds_read_b128 v[154:157], v128 offset:2048
	ds_read_b128 v[158:161], v128 offset:3072
	v_add_u32_e32 v128, s5, v228
	ds_read_b128 v[130:133], v128
	ds_read_b128 v[134:137], v128 offset:1024
	ds_read_b128 v[138:141], v128 offset:2048
	ds_read_b128 v[142:145], v128 offset:3072
	v_lshl_add_u64 v[196:197], s[48:49], 0, v[216:217]
	s_add_i32 m0, s70, 0xc000
	s_waitcnt lgkmcnt(7)
	ds_read_b128 v[162:165], v248
	ds_read_b128 v[166:169], v248 offset:1024
	ds_read_b128 v[170:173], v248 offset:2048
	ds_read_b128 v[174:177], v248 offset:3072
	ds_read_b128 v[178:181], v248 offset:4096
	ds_read_b128 v[182:185], v248 offset:5120
	ds_read_b128 v[186:189], v248 offset:6144
	ds_read_b128 v[190:193], v248 offset:7168
	global_load_lds_dwordx4 v[196:197], off
	v_lshl_add_u64 v[196:197], s[48:49], 0, v[218:219]
	s_add_i32 m0, s70, 0xe000
	s_nop 0
	global_load_lds_dwordx4 v[196:197], off
	s_waitcnt vmcnt(8)
	s_waitcnt lgkmcnt(0)
	s_barrier
	s_setprio 1
	s_waitcnt lgkmcnt(0)
	v_mfma_f32_16x16x32_bf16 v[124:127], v[146:149], v[162:165], v[124:127]
	v_mfma_f32_16x16x32_bf16 v[120:123], v[154:157], v[162:165], v[120:123]
	v_mfma_f32_16x16x32_bf16 v[108:111], v[146:149], v[170:173], v[108:111]
	v_mfma_f32_16x16x32_bf16 v[104:107], v[154:157], v[170:173], v[104:107]
	v_mfma_f32_16x16x32_bf16 v[92:95], v[146:149], v[178:181], v[92:95]
	v_mfma_f32_16x16x32_bf16 v[88:91], v[154:157], v[178:181], v[88:91]
	v_mfma_f32_16x16x32_bf16 v[76:79], v[146:149], v[186:189], v[76:79]
	v_mfma_f32_16x16x32_bf16 v[72:75], v[154:157], v[186:189], v[72:75]
	v_mfma_f32_16x16x32_bf16 v[124:127], v[150:153], v[166:169], v[124:127]
	v_mfma_f32_16x16x32_bf16 v[120:123], v[158:161], v[166:169], v[120:123]
	v_mfma_f32_16x16x32_bf16 v[108:111], v[150:153], v[174:177], v[108:111]
	v_mfma_f32_16x16x32_bf16 v[104:107], v[158:161], v[174:177], v[104:107]
	v_mfma_f32_16x16x32_bf16 v[92:95], v[150:153], v[182:185], v[92:95]
	v_mfma_f32_16x16x32_bf16 v[88:91], v[158:161], v[182:185], v[88:91]
	v_mfma_f32_16x16x32_bf16 v[76:79], v[150:153], v[190:193], v[76:79]
	v_mfma_f32_16x16x32_bf16 v[72:75], v[158:161], v[190:193], v[72:75]
	v_mfma_f32_16x16x32_bf16 v[116:119], v[130:133], v[162:165], v[116:119]
	v_mfma_f32_16x16x32_bf16 v[112:115], v[138:141], v[162:165], v[112:115]
	v_mfma_f32_16x16x32_bf16 v[100:103], v[130:133], v[170:173], v[100:103]
	v_mfma_f32_16x16x32_bf16 v[96:99], v[138:141], v[170:173], v[96:99]
	v_mfma_f32_16x16x32_bf16 v[84:87], v[130:133], v[178:181], v[84:87]
	v_mfma_f32_16x16x32_bf16 v[80:83], v[138:141], v[178:181], v[80:83]
	v_mfma_f32_16x16x32_bf16 v[68:71], v[130:133], v[186:189], v[68:71]
	v_mfma_f32_16x16x32_bf16 v[64:67], v[138:141], v[186:189], v[64:67]
	v_mfma_f32_16x16x32_bf16 v[116:119], v[134:137], v[166:169], v[116:119]
	v_mfma_f32_16x16x32_bf16 v[112:115], v[142:145], v[166:169], v[112:115]
	v_mfma_f32_16x16x32_bf16 v[100:103], v[134:137], v[174:177], v[100:103]
	v_mfma_f32_16x16x32_bf16 v[96:99], v[142:145], v[174:177], v[96:99]
	v_mfma_f32_16x16x32_bf16 v[84:87], v[134:137], v[182:185], v[84:87]
	v_mfma_f32_16x16x32_bf16 v[80:83], v[142:145], v[182:185], v[80:83]
	v_mfma_f32_16x16x32_bf16 v[68:71], v[134:137], v[190:193], v[68:71]
	v_mfma_f32_16x16x32_bf16 v[64:67], v[142:145], v[190:193], v[64:67]
	s_setprio 0
	s_barrier
	s_add_i32 s2, s4, s65
	v_lshl_add_u64 v[220:221], s[28:29], 0, v[208:209]
	s_mov_b32 m0, s2
	ds_read_b128 v[186:189], v248 offset:16384
	ds_read_b128 v[190:193], v248 offset:17408
	ds_read_b128 v[178:181], v248 offset:18432
	ds_read_b128 v[182:185], v248 offset:19456
	ds_read_b128 v[170:173], v248 offset:20480
	ds_read_b128 v[174:177], v248 offset:21504
	ds_read_b128 v[162:165], v248 offset:22528
	ds_read_b128 v[166:169], v248 offset:23552
	global_load_lds_dwordx4 v[220:221], off
	s_add_i32 m0, s2, 0x2000
	s_add_u32 s2, s28, 0x40000
	v_lshl_add_u64 v[222:223], s[28:29], 0, v[212:213]
	s_addc_u32 s3, s29, 0
	s_add_i32 s4, s5, s65
	global_load_lds_dwordx4 v[222:223], off
	v_lshl_add_u64 v[196:197], s[2:3], 0, v[208:209]
	s_mov_b32 m0, s4
	v_lshl_add_u64 v[224:225], s[34:35], 0, v[206:207]
	global_load_lds_dwordx4 v[196:197], off
	v_lshl_add_u64 v[196:197], s[2:3], 0, v[212:213]
	s_add_i32 m0, s4, 0x2000
	v_lshl_add_u64 v[226:227], s[34:35], 0, v[210:211]
	global_load_lds_dwordx4 v[196:197], off
	s_mov_b32 m0, s70
	v_cndmask_b32_e64 v128, 0, 1, s[30:31]
	global_load_lds_dwordx4 v[224:225], off
	s_mov_b32 m0, s71
	v_cmp_ne_u32_e64 s[42:43], 1, v128
	global_load_lds_dwordx4 v[226:227], off
	s_waitcnt vmcnt(8)
	s_waitcnt lgkmcnt(0)
	s_andn2_b64 vcc, exec, s[30:31]
	s_barrier
	s_cbranch_vccnz .LBB0_168
; #define PG8_MMA(ai, bj, At, Bt) do { __builtin_amdgcn_s_setprio(1); _Pragma("unroll") for (int m = 0; m < 4; ++m) _Pragma("unroll") for (int n = 0; n < 2; ++n) _Pragma("unroll") for (int k = 0; k < 2; ++k) \
;         acc[ai][bj][m][n] = __builtin_amdgcn_mfma_f32_16x16x32_bf16(Bt[n][k], At[m][k], acc[ai][bj][m][n], 0, 0, 0); __builtin_amdgcn_s_setprio(0); } while (0)
; #define PG8_WAIT_V(n) asm volatile("s_waitcnt vmcnt(" #n ")" ::: "memory")
; #define PG8_WAIT_L(n) asm volatile("s_waitcnt lgkmcnt(" #n ")" ::: "memory")
; #define PG8_BAR __builtin_amdgcn_s_barrier()
; #define PG8_SCHED __builtin_amdgcn_sched_barrier(0)
; template <class Epi, class Sched, bool ALIGN_EPI = false, bool SP2 = false>
; __device__ __forceinline__ void gemm_phase(PG8_LAS unsigned char* lds, const Gemm g, const Sched& S, const Epi& E) {
;     ...
;             PG8_WAIT_V(8); PG8_WAIT_L(0); PG8_BAR; if (full) { PG8_MMA(1, 0, At, B0); PG8_MMA(1, 1, At, B1); } PG8_BAR; PG8_SCHED;
	s_setprio 1
	s_waitcnt lgkmcnt(0)
	v_mfma_f32_16x16x32_bf16 v[60:63], v[146:149], v[186:189], v[60:63]
	v_mfma_f32_16x16x32_bf16 v[56:59], v[154:157], v[186:189], v[56:59]
	v_mfma_f32_16x16x32_bf16 v[44:47], v[146:149], v[178:181], v[44:47]
	v_mfma_f32_16x16x32_bf16 v[40:43], v[154:157], v[178:181], v[40:43]
	v_mfma_f32_16x16x32_bf16 v[28:31], v[146:149], v[170:173], v[28:31]
	v_mfma_f32_16x16x32_bf16 v[24:27], v[154:157], v[170:173], v[24:27]
	v_mfma_f32_16x16x32_bf16 v[12:15], v[146:149], v[162:165], v[12:15]
	v_mfma_f32_16x16x32_bf16 v[8:11], v[154:157], v[162:165], v[8:11]
	v_mfma_f32_16x16x32_bf16 v[60:63], v[150:153], v[190:193], v[60:63]
	v_mfma_f32_16x16x32_bf16 v[56:59], v[158:161], v[190:193], v[56:59]
	v_mfma_f32_16x16x32_bf16 v[44:47], v[150:153], v[182:185], v[44:47]
	v_mfma_f32_16x16x32_bf16 v[40:43], v[158:161], v[182:185], v[40:43]
	v_mfma_f32_16x16x32_bf16 v[28:31], v[150:153], v[174:177], v[28:31]
	v_mfma_f32_16x16x32_bf16 v[24:27], v[158:161], v[174:177], v[24:27]
	v_mfma_f32_16x16x32_bf16 v[12:15], v[150:153], v[166:169], v[12:15]
	v_mfma_f32_16x16x32_bf16 v[8:11], v[158:161], v[166:169], v[8:11]
	v_mfma_f32_16x16x32_bf16 v[52:55], v[130:133], v[186:189], v[52:55]
	v_mfma_f32_16x16x32_bf16 v[48:51], v[138:141], v[186:189], v[48:51]
	v_mfma_f32_16x16x32_bf16 v[36:39], v[130:133], v[178:181], v[36:39]
	v_mfma_f32_16x16x32_bf16 v[32:35], v[138:141], v[178:181], v[32:35]
	v_mfma_f32_16x16x32_bf16 v[20:23], v[130:133], v[170:173], v[20:23]
	v_mfma_f32_16x16x32_bf16 v[16:19], v[138:141], v[170:173], v[16:19]
	v_mfma_f32_16x16x32_bf16 v[4:7], v[130:133], v[162:165], v[4:7]
	v_mfma_f32_16x16x32_bf16 v[0:3], v[138:141], v[162:165], v[0:3]
	v_mfma_f32_16x16x32_bf16 v[52:55], v[134:137], v[190:193], v[52:55]
	v_mfma_f32_16x16x32_bf16 v[48:51], v[142:145], v[190:193], v[48:51]
	v_mfma_f32_16x16x32_bf16 v[36:39], v[134:137], v[182:185], v[36:39]
	v_mfma_f32_16x16x32_bf16 v[32:35], v[142:145], v[182:185], v[32:35]
	v_mfma_f32_16x16x32_bf16 v[20:23], v[134:137], v[174:177], v[20:23]
	v_mfma_f32_16x16x32_bf16 v[16:19], v[142:145], v[174:177], v[16:19]
	v_mfma_f32_16x16x32_bf16 v[4:7], v[134:137], v[166:169], v[4:7]
	v_mfma_f32_16x16x32_bf16 v[0:3], v[142:145], v[166:169], v[0:3]
	s_setprio 0
; #define PG8_STAGE(bufoff, gbase, voff) do { _Pragma("unroll") for (int _i = 0; _i < 2; ++_i) \
;         __builtin_amdgcn_global_load_lds((const unsigned*)((const char*)(gbase) + (voff)[_i]), (PG8_LAS unsigned*)(lds + (bufoff) + ldsw + _i * 8192), 16, 0, 0); } while (0)
; #define PG8_LDA(dst, b, h) do { _Pragma("unroll") for (int m = 0; m < 4; ++m) _Pragma("unroll") for (int k = 0; k < 2; ++k) dst[m][k] = *(const PG8_LAS bf16x8*)(lds + PG8_SA(b, h) + aoff + m * 2048 + k * 1024); } while (0)
; #define PG8_LDB(dst, b, h) do { _Pragma("unroll") for (int n = 0; n < 2; ++n) _Pragma("unroll") for (int k = 0; k < 2; ++k) dst[n][k] = *(const PG8_LAS bf16x8*)(lds + PG8_SB(b, h) + boff + n * 2048 + k * 1024); } while (0)
; #define PG8_MMA(ai, bj, At, Bt) do { __builtin_amdgcn_s_setprio(1); _Pragma("unroll") for (int m = 0; m < 4; ++m) _Pragma("unroll") for (int n = 0; n < 2; ++n) _Pragma("unroll") for (int k = 0; k < 2; ++k) \
;         acc[ai][bj][m][n] = __builtin_amdgcn_mfma_f32_16x16x32_bf16(Bt[n][k], At[m][k], acc[ai][bj][m][n], 0, 0, 0); __builtin_amdgcn_s_setprio(0); } while (0)
; #define PG8_WAIT_V(n) asm volatile("s_waitcnt vmcnt(" #n ")" ::: "memory")
; #define PG8_WAIT_L(n) asm volatile("s_waitcnt lgkmcnt(" #n ")" ::: "memory")
; #define PG8_BAR __builtin_amdgcn_s_barrier()
; #define PG8_SCHED __builtin_amdgcn_sched_barrier(0)
; template <class Epi, class Sched, bool ALIGN_EPI = false, bool SP2 = false>
; __device__ __forceinline__ void gemm_phase(PG8_LAS unsigned char* lds, const Gemm g, const Sched& S, const Epi& E) {
;     ...
;             PG8_LDB(B0, 1, 0); PG8_LDB(B1, 1, 1); PG8_SCHED; PG8_LDA(At, 1, 0); PG8_STAGE(PG8_SA(0, 1), a2 + hstep, voffA);
;             PG8_WAIT_V(8); PG8_WAIT_L(0); PG8_BAR; PG8_MMA(0, 0, At, B0); PG8_MMA(0, 1, At, B1); PG8_BAR; PG8_SCHED;
;             PG8_LDA(At, 1, 1); PG8_STAGE(PG8_SB(1, 0), b3, voffB); PG8_STAGE(PG8_SB(1, 1), b3 + hstep, voffB); PG8_STAGE(PG8_SA(1, 0), a3, voffA);
;             PG8_WAIT_V(8); PG8_WAIT_L(0); PG8_BAR; if (full) { PG8_MMA(1, 0, At, B0); PG8_MMA(1, 1, At, B1); } PG8_BAR; PG8_SCHED;
.LBB0_168:
	s_barrier
	s_add_i32 s4, 0, 0x18000
	v_add_u32_e32 v128, s4, v228
	s_add_i32 s5, 0, 0x1c000
	ds_read_b128 v[146:149], v128
	ds_read_b128 v[150:153], v128 offset:1024
	ds_read_b128 v[154:157], v128 offset:2048
	ds_read_b128 v[158:161], v128 offset:3072
	v_add_u32_e32 v128, s5, v228
	ds_read_b128 v[130:133], v128
	ds_read_b128 v[134:137], v128 offset:1024
	ds_read_b128 v[138:141], v128 offset:2048
	ds_read_b128 v[142:145], v128 offset:3072
	s_add_u32 s2, s34, 0x40000
	s_addc_u32 s3, s35, 0
	s_mov_b32 m0, s73
	v_lshl_add_u64 v[196:197], s[2:3], 0, v[206:207]
	s_waitcnt lgkmcnt(7)
	ds_read_b128 v[162:165], v248 offset:32768
	ds_read_b128 v[166:169], v248 offset:33792
	ds_read_b128 v[170:173], v248 offset:34816
	ds_read_b128 v[174:177], v248 offset:35840
	ds_read_b128 v[178:181], v248 offset:36864
	ds_read_b128 v[182:185], v248 offset:37888
	ds_read_b128 v[186:189], v248 offset:38912
	ds_read_b128 v[190:193], v248 offset:39936
	global_load_lds_dwordx4 v[196:197], off
	v_lshl_add_u64 v[196:197], s[2:3], 0, v[210:211]
	s_mov_b32 m0, s87
	s_nop 0
	global_load_lds_dwordx4 v[196:197], off
	s_waitcnt vmcnt(8)
	s_waitcnt lgkmcnt(0)
	s_barrier
	s_setprio 1
	s_waitcnt lgkmcnt(0)
	v_mfma_f32_16x16x32_bf16 v[124:127], v[146:149], v[162:165], v[124:127]
	v_mfma_f32_16x16x32_bf16 v[120:123], v[154:157], v[162:165], v[120:123]
	v_mfma_f32_16x16x32_bf16 v[108:111], v[146:149], v[170:173], v[108:111]
	v_mfma_f32_16x16x32_bf16 v[104:107], v[154:157], v[170:173], v[104:107]
	v_mfma_f32_16x16x32_bf16 v[92:95], v[146:149], v[178:181], v[92:95]
	v_mfma_f32_16x16x32_bf16 v[88:91], v[154:157], v[178:181], v[88:91]
	v_mfma_f32_16x16x32_bf16 v[76:79], v[146:149], v[186:189], v[76:79]
	v_mfma_f32_16x16x32_bf16 v[72:75], v[154:157], v[186:189], v[72:75]
	v_mfma_f32_16x16x32_bf16 v[124:127], v[150:153], v[166:169], v[124:127]
	v_mfma_f32_16x16x32_bf16 v[120:123], v[158:161], v[166:169], v[120:123]
	v_mfma_f32_16x16x32_bf16 v[108:111], v[150:153], v[174:177], v[108:111]
	v_mfma_f32_16x16x32_bf16 v[104:107], v[158:161], v[174:177], v[104:107]
	v_mfma_f32_16x16x32_bf16 v[92:95], v[150:153], v[182:185], v[92:95]
	v_mfma_f32_16x16x32_bf16 v[88:91], v[158:161], v[182:185], v[88:91]
	v_mfma_f32_16x16x32_bf16 v[76:79], v[150:153], v[190:193], v[76:79]
	v_mfma_f32_16x16x32_bf16 v[72:75], v[158:161], v[190:193], v[72:75]
	v_mfma_f32_16x16x32_bf16 v[116:119], v[130:133], v[162:165], v[116:119]
	v_mfma_f32_16x16x32_bf16 v[112:115], v[138:141], v[162:165], v[112:115]
	v_mfma_f32_16x16x32_bf16 v[100:103], v[130:133], v[170:173], v[100:103]
	v_mfma_f32_16x16x32_bf16 v[96:99], v[138:141], v[170:173], v[96:99]
	v_mfma_f32_16x16x32_bf16 v[84:87], v[130:133], v[178:181], v[84:87]
	v_mfma_f32_16x16x32_bf16 v[80:83], v[138:141], v[178:181], v[80:83]
	v_mfma_f32_16x16x32_bf16 v[68:71], v[130:133], v[186:189], v[68:71]
	v_mfma_f32_16x16x32_bf16 v[64:67], v[138:141], v[186:189], v[64:67]
	v_mfma_f32_16x16x32_bf16 v[116:119], v[134:137], v[166:169], v[116:119]
	v_mfma_f32_16x16x32_bf16 v[112:115], v[142:145], v[166:169], v[112:115]
	v_mfma_f32_16x16x32_bf16 v[100:103], v[134:137], v[174:177], v[100:103]
	v_mfma_f32_16x16x32_bf16 v[96:99], v[142:145], v[174:177], v[96:99]
	v_mfma_f32_16x16x32_bf16 v[84:87], v[134:137], v[182:185], v[84:87]
	v_mfma_f32_16x16x32_bf16 v[80:83], v[142:145], v[182:185], v[80:83]
	v_mfma_f32_16x16x32_bf16 v[68:71], v[134:137], v[190:193], v[68:71]
	v_mfma_f32_16x16x32_bf16 v[64:67], v[142:145], v[190:193], v[64:67]
	s_setprio 0
	s_barrier
	s_add_i32 s2, s4, s65
	v_lshl_add_u64 v[196:197], v[220:221], 0, s[26:27]
	s_mov_b32 m0, s2
	ds_read_b128 v[186:189], v248 offset:49152
	ds_read_b128 v[190:193], v248 offset:50176
	ds_read_b128 v[178:181], v248 offset:51200
	ds_read_b128 v[182:185], v248 offset:52224
	ds_read_b128 v[170:173], v248 offset:53248
	ds_read_b128 v[174:177], v248 offset:54272
	ds_read_b128 v[162:165], v248 offset:55296
	ds_read_b128 v[166:169], v248 offset:56320
	global_load_lds_dwordx4 v[196:197], off
	s_add_i32 m0, s2, 0x2000
	s_add_u32 s2, s28, 0x40080
	v_lshl_add_u64 v[196:197], v[222:223], 0, s[26:27]
	s_addc_u32 s3, s29, 0
	s_add_i32 s4, s5, s65
	global_load_lds_dwordx4 v[196:197], off
	v_lshl_add_u64 v[196:197], s[2:3], 0, v[208:209]
	s_mov_b32 m0, s4
	s_and_b64 vcc, exec, s[42:43]
	global_load_lds_dwordx4 v[196:197], off
	v_lshl_add_u64 v[196:197], s[2:3], 0, v[212:213]
	s_add_i32 m0, s4, 0x2000
	s_nop 0
	global_load_lds_dwordx4 v[196:197], off
	v_lshl_add_u64 v[196:197], v[224:225], 0, s[26:27]
	s_mov_b32 m0, s88
	s_nop 0
	global_load_lds_dwordx4 v[196:197], off
	v_lshl_add_u64 v[196:197], v[226:227], 0, s[26:27]
	s_mov_b32 m0, s89
	s_nop 0
	global_load_lds_dwordx4 v[196:197], off
	s_waitcnt vmcnt(8)
	s_waitcnt lgkmcnt(0)
	s_barrier
	s_cbranch_vccnz .LBB0_165
	s_setprio 1
	s_waitcnt lgkmcnt(0)
	v_mfma_f32_16x16x32_bf16 v[60:63], v[146:149], v[186:189], v[60:63]
	v_mfma_f32_16x16x32_bf16 v[56:59], v[154:157], v[186:189], v[56:59]
	v_mfma_f32_16x16x32_bf16 v[44:47], v[146:149], v[178:181], v[44:47]
	v_mfma_f32_16x16x32_bf16 v[40:43], v[154:157], v[178:181], v[40:43]
	v_mfma_f32_16x16x32_bf16 v[28:31], v[146:149], v[170:173], v[28:31]
	v_mfma_f32_16x16x32_bf16 v[24:27], v[154:157], v[170:173], v[24:27]
	v_mfma_f32_16x16x32_bf16 v[12:15], v[146:149], v[162:165], v[12:15]
	v_mfma_f32_16x16x32_bf16 v[8:11], v[154:157], v[162:165], v[8:11]
	v_mfma_f32_16x16x32_bf16 v[60:63], v[150:153], v[190:193], v[60:63]
	v_mfma_f32_16x16x32_bf16 v[56:59], v[158:161], v[190:193], v[56:59]
	v_mfma_f32_16x16x32_bf16 v[44:47], v[150:153], v[182:185], v[44:47]
	v_mfma_f32_16x16x32_bf16 v[40:43], v[158:161], v[182:185], v[40:43]
	v_mfma_f32_16x16x32_bf16 v[28:31], v[150:153], v[174:177], v[28:31]
	v_mfma_f32_16x16x32_bf16 v[24:27], v[158:161], v[174:177], v[24:27]
	v_mfma_f32_16x16x32_bf16 v[12:15], v[150:153], v[166:169], v[12:15]
	v_mfma_f32_16x16x32_bf16 v[8:11], v[158:161], v[166:169], v[8:11]
	v_mfma_f32_16x16x32_bf16 v[52:55], v[130:133], v[186:189], v[52:55]
	v_mfma_f32_16x16x32_bf16 v[48:51], v[138:141], v[186:189], v[48:51]
	v_mfma_f32_16x16x32_bf16 v[36:39], v[130:133], v[178:181], v[36:39]
	v_mfma_f32_16x16x32_bf16 v[32:35], v[138:141], v[178:181], v[32:35]
	v_mfma_f32_16x16x32_bf16 v[20:23], v[130:133], v[170:173], v[20:23]
	v_mfma_f32_16x16x32_bf16 v[16:19], v[138:141], v[170:173], v[16:19]
	v_mfma_f32_16x16x32_bf16 v[4:7], v[130:133], v[162:165], v[4:7]
	v_mfma_f32_16x16x32_bf16 v[0:3], v[138:141], v[162:165], v[0:3]
	v_mfma_f32_16x16x32_bf16 v[52:55], v[134:137], v[190:193], v[52:55]
	v_mfma_f32_16x16x32_bf16 v[48:51], v[142:145], v[190:193], v[48:51]
	v_mfma_f32_16x16x32_bf16 v[36:39], v[134:137], v[182:185], v[36:39]
	v_mfma_f32_16x16x32_bf16 v[32:35], v[142:145], v[182:185], v[32:35]
	v_mfma_f32_16x16x32_bf16 v[20:23], v[134:137], v[174:177], v[20:23]
	v_mfma_f32_16x16x32_bf16 v[16:19], v[142:145], v[174:177], v[16:19]
	v_mfma_f32_16x16x32_bf16 v[4:7], v[134:137], v[166:169], v[4:7]
	v_mfma_f32_16x16x32_bf16 v[0:3], v[142:145], v[166:169], v[0:3]
	s_setprio 0
	s_branch .LBB0_165

; #define SBAR() __builtin_amdgcn_sched_barrier(0)
; __device__ __forceinline__ void finishSM(f32x16& p0, f32x16& p1, float alpha, float& l_reg, bf16x8& pa0, bf16x8& pa1, bf16x8& pa2, bf16x8& pa3) {
;   for (int r = 0; r < 16; ++r) p1[r] = __builtin_amdgcn_exp2f(p1[r]);
;   float ps = 0; for (int r = 0; r < 16; ++r) ps += p0[r]; for (int r = 0; r < 16; ++r) ps += p1[r];
;   { auto rr = __builtin_amdgcn_permlane32_swap(__float_as_uint(ps), __float_as_uint(ps), false, false);
;     ps = __uint_as_float(rr[0]) + __uint_as_float(rr[1]); }
;   l_reg = l_reg * alpha + ps;
;     ...
;   PK4(p0, 0, pa0); PK4(p0, 8, pa1); PK4(p1, 0, pa2); PK4(p1, 8, pa3);
;     ...
; }
; template <int BOFF> __device__ __forceinline__ void qkt_i(f32x16& p0, f32x16& p1, const int (&kb)[4], const bf16x8* qr) {
;   p0 = f32x16{}; p1 = f32x16{};
; #pragma unroll
;   for (int d0 = 0; d0 < 8; ++d0) { const int off = BOFF + (d0 >> 2) * 128;
;     const bf16x8 b0 = LDSV(kb[d0 & 3] + off), b1 = LDSV(kb[d0 & 3] + off + 8192);
;     p0 = __builtin_amdgcn_mfma_f32_32x32x16_bf16(b0, qr[d0], p0, 0, 0, 0);
;     p1 = __builtin_amdgcn_mfma_f32_32x32x16_bf16(b1, qr[d0], p1, 0, 0, 0); }
; }
; template <int D0, int BOFF> __device__ __forceinline__ void pv_one_i(f32x16& od, int vb, bf16x8 pa0, bf16x8 pa1, bf16x8 pa2, bf16x8 pa3) {
;   const s16x4 l0 = tr_read<BOFF + v_rd_off(D0, 0, 0)>(vb), h0 = tr_read<BOFF + v_rd_off(D0, 0, 1)>(vb), l1 = tr_read<BOFF + v_rd_off(D0, 1, 0)>(vb), h1 = tr_read<BOFF + v_rd_off(D0, 1, 1)>(vb);
;   const s16x4 l2 = tr_read<BOFF + v_rd_off(D0, 2, 0)>(vb), h2 = tr_read<BOFF + v_rd_off(D0, 2, 1)>(vb), l3 = tr_read<BOFF + v_rd_off(D0, 3, 0)>(vb), h3 = tr_read<BOFF + v_rd_off(D0, 3, 1)>(vb);
;   asm volatile("s_waitcnt lgkmcnt(0)" ::: "memory"); SBAR();
;     ...
;   od = __builtin_amdgcn_mfma_f32_32x32x16_bf16(pa0, PK(l0, h0), od, 0, 0, 0);
;   od = __builtin_amdgcn_mfma_f32_32x32x16_bf16(pa1, PK(l1, h1), od, 0, 0, 0);
;   od = __builtin_amdgcn_mfma_f32_32x32x16_bf16(pa2, PK(l2, h2), od, 0, 0, 0);
;   od = __builtin_amdgcn_mfma_f32_32x32x16_bf16(pa3, PK(l3, h3), od, 0, 0, 0);
;     ...
; }
; template <int BOFF> __device__ __forceinline__ void pv_i(f32x16* o, int vb, bf16x8 pa0, bf16x8 pa1, bf16x8 pa2, bf16x8 pa3) {
;   pv_one_i<0, BOFF>(o[0], vb, pa0, pa1, pa2, pa3); pv_one_i<1, BOFF>(o[1], vb, pa0, pa1, pa2, pa3); pv_one_i<2, BOFF>(o[2], vb, pa0, pa1, pa2, pa3); pv_one_i<3, BOFF>(o[3], vb, pa0, pa1, pa2, pa3);
; }
.LBB0_352:
	s_waitcnt lgkmcnt(0)
	s_barrier
	ds_read_b128 v[80:83], v207 offset:16384
	ds_read_b128 v[84:87], v207 offset:24576
	ds_read_b128 v[162:165], v208 offset:16384
	ds_read_b128 v[166:169], v208 offset:24576
	v_exp_f32_e32 v170, v72
	v_exp_f32_e32 v171, v73
	v_exp_f32_e32 v172, v74
	v_exp_f32_e32 v173, v75
	v_exp_f32_e32 v174, v76
	v_exp_f32_e32 v175, v77
	v_exp_f32_e32 v176, v78
	v_exp_f32_e32 v79, v79
	s_waitcnt lgkmcnt(3)
	v_mfma_f32_32x32x16_bf16 v[96:111], v[80:83], v[142:145], 0
	v_exp_f32_e32 v236, v64
	v_add_f32_e32 v64, 0, v229
	v_add_f32_e32 v64, v243, v64
	v_add_f32_e32 v64, v244, v64
	s_waitcnt lgkmcnt(2)
	v_mfma_f32_32x32x16_bf16 v[80:95], v[84:87], v[142:145], 0
	v_add_f32_e32 v64, v246, v64
	v_add_f32_e32 v64, v242, v64
	v_add_f32_e32 v64, v245, v64
	s_waitcnt lgkmcnt(1)
	v_mfma_f32_32x32x16_bf16 v[96:111], v[162:165], v[138:141], v[96:111]
	v_add_f32_e32 v64, v227, v64
	v_add_f32_e32 v64, v228, v64
	v_add_f32_e32 v64, v223, v64
	s_waitcnt lgkmcnt(0)
	v_mfma_f32_32x32x16_bf16 v[80:95], v[166:169], v[138:141], v[80:95]
	ds_read_b128 v[162:165], v209 offset:16384
	ds_read_b128 v[166:169], v209 offset:24576
	v_add_f32_e32 v64, v226, v64
	v_add_f32_e32 v64, v224, v64
	v_add_f32_e32 v64, v225, v64
	v_add_f32_e32 v64, v220, v64
	v_exp_f32_e32 v237, v65
	s_waitcnt lgkmcnt(1)
	v_mfma_f32_32x32x16_bf16 v[96:111], v[162:165], v[112:115], v[96:111]
	v_add_f32_e32 v64, v222, v64
	v_exp_f32_e32 v238, v66
	v_add_f32_e32 v64, v219, v64
	v_exp_f32_e32 v239, v67
	s_waitcnt lgkmcnt(0)
	v_mfma_f32_32x32x16_bf16 v[80:95], v[166:169], v[112:115], v[80:95]
	ds_read_b128 v[162:165], v210 offset:16384
	ds_read_b128 v[166:169], v210 offset:24576
	v_add_f32_e32 v64, v221, v64
	v_exp_f32_e32 v247, v68
	v_add_f32_e32 v64, v236, v64
	v_exp_f32_e32 v248, v69
	s_waitcnt lgkmcnt(1)
	v_mfma_f32_32x32x16_bf16 v[96:111], v[162:165], v[116:119], v[96:111]
	v_add_f32_e32 v64, v237, v64
	v_exp_f32_e32 v249, v70
	v_add_f32_e32 v64, v238, v64
	v_exp_f32_e32 v252, v71
	s_waitcnt lgkmcnt(0)
	v_mfma_f32_32x32x16_bf16 v[80:95], v[166:169], v[116:119], v[80:95]
	ds_read_b128 v[162:165], v190 offset:16384
	ds_read_b128 v[166:169], v190 offset:24576
	v_add_f32_e32 v64, v239, v64
	v_add_f32_e32 v64, v247, v64
	v_add_f32_e32 v64, v248, v64
	v_add_f32_e32 v64, v249, v64
	v_add_f32_e32 v64, v252, v64
	v_add_f32_e32 v64, v170, v64
	s_waitcnt lgkmcnt(1)
	v_mfma_f32_32x32x16_bf16 v[96:111], v[162:165], v[120:123], v[96:111]
	v_add_f32_e32 v64, v171, v64
	v_add_f32_e32 v64, v172, v64
	v_add_f32_e32 v64, v173, v64
	v_add_f32_e32 v64, v174, v64
	v_add_f32_e32 v64, v175, v64
	s_waitcnt lgkmcnt(0)
	v_mfma_f32_32x32x16_bf16 v[80:95], v[166:169], v[120:123], v[80:95]
	ds_read_b128 v[162:165], v191 offset:16384
	ds_read_b128 v[166:169], v191 offset:24576
	v_add_f32_e32 v64, v176, v64
	v_add_f32_e32 v64, v79, v64
	v_mov_b32_e32 v65, v64
	s_nop 1
	v_permlane32_swap_b32_e32 v64, v65
	v_add_f32_e32 v64, v64, v65
	s_waitcnt lgkmcnt(1)
	v_mfma_f32_32x32x16_bf16 v[96:111], v[162:165], v[124:127], v[96:111]
	v_add_f32_e32 v128, v215, v64
	v_cvt_pk_bf16_f32 v64, v229, v243
	v_cvt_pk_bf16_f32 v65, v244, v246
	v_cvt_pk_bf16_f32 v66, v242, v245
	v_cvt_pk_bf16_f32 v67, v227, v228
	s_waitcnt lgkmcnt(0)
	v_mfma_f32_32x32x16_bf16 v[80:95], v[166:169], v[124:127], v[80:95]
	ds_read_b128 v[162:165], v192 offset:16384
	ds_read_b128 v[166:169], v192 offset:24576
	v_cvt_pk_bf16_f32 v68, v223, v226
	v_cvt_pk_bf16_f32 v69, v224, v225
	v_cvt_pk_bf16_f32 v70, v220, v222
	v_cvt_pk_bf16_f32 v71, v219, v221
	v_cvt_pk_bf16_f32 v72, v236, v237
	v_cvt_pk_bf16_f32 v73, v238, v239
	s_waitcnt lgkmcnt(1)
	v_mfma_f32_32x32x16_bf16 v[96:111], v[162:165], v[130:133], v[96:111]
	v_cvt_pk_bf16_f32 v74, v247, v248
	v_cvt_pk_bf16_f32 v75, v249, v252
	v_cvt_pk_bf16_f32 v76, v170, v171
	v_cvt_pk_bf16_f32 v77, v172, v173
	v_cvt_pk_bf16_f32 v78, v174, v175
	s_waitcnt lgkmcnt(0)
	v_mfma_f32_32x32x16_bf16 v[80:95], v[166:169], v[130:133], v[80:95]
	ds_read_b128 v[162:165], v193 offset:16384
	ds_read_b128 v[166:169], v193 offset:24576
	ds_read_b64_tr_b16 v[180:181], v206 offset:0
	ds_read_b64_tr_b16 v[182:183], v206 offset:0x800
	ds_read_b64_tr_b16 v[184:185], v206 offset:0x1000
	ds_read_b64_tr_b16 v[186:187], v206 offset:0x1800
	ds_read_b64_tr_b16 v[216:217], v206 offset:0x2000
	ds_read_b64_tr_b16 v[218:219], v206 offset:0x2800
	ds_read_b64_tr_b16 v[220:221], v206 offset:0x3000
	ds_read_b64_tr_b16 v[222:223], v206 offset:0x3800
	v_cvt_pk_bf16_f32 v79, v176, v79
	s_nop 0
	v_permlane32_swap_b32_e32 v64, v66
	v_permlane32_swap_b32_e32 v65, v67
	v_permlane32_swap_b32_e32 v68, v70
	v_permlane32_swap_b32_e32 v69, v71
	s_waitcnt lgkmcnt(9)
	v_mfma_f32_32x32x16_bf16 v[96:111], v[162:165], v[134:137], v[96:111]
	v_permlane32_swap_b32_e32 v72, v74
	v_permlane32_swap_b32_e32 v73, v75
	v_permlane32_swap_b32_e32 v76, v78
	v_permlane32_swap_b32_e32 v77, v79
	s_waitcnt lgkmcnt(8)
	v_mfma_f32_32x32x16_bf16 v[80:95], v[166:169], v[134:137], v[80:95]
	v_add_co_u32_e32 v166, vcc, s19, v178
	s_nop 1
	v_addc_co_u32_e32 v167, vcc, -1, v179, vcc
	v_add_co_u32_e32 v170, vcc, s20, v178
	s_nop 1
	v_addc_co_u32_e32 v171, vcc, -1, v179, vcc
	global_load_dwordx4 v[162:165], v[166:167], off
	s_nop 0
	global_load_dwordx4 v[166:169], v[166:167], off offset:-512
	s_nop 0
	global_load_dwordx4 v[174:177], v[170:171], off
	s_nop 0
	global_load_dwordx4 v[170:173], v[170:171], off offset:-512
	s_waitcnt vmcnt(4)
	ds_write_b128 v211, v[146:149] offset:32768
	s_nop 0
	s_waitcnt lgkmcnt(7)
	v_mfma_f32_32x32x16_bf16 v[0:15], v[64:67], v[180:183], v[0:15]
	ds_read_b64_tr_b16 v[180:181], v206 offset:0x200
	ds_read_b64_tr_b16 v[182:183], v206 offset:0xa00
	s_waitcnt lgkmcnt(7)
; #define SBAR() __builtin_amdgcn_sched_barrier(0)
; __device__ __forceinline__ void partialSM_fixed(f32x16& p0) {
;   for (int r = 0; r < 16; ++r) p0[r] = __builtin_amdgcn_exp2f(p0[r]);
; }
; template <int D0, int BOFF> __device__ __forceinline__ void pv_one_i(f32x16& od, int vb, bf16x8 pa0, bf16x8 pa1, bf16x8 pa2, bf16x8 pa3) {
;   const s16x4 l0 = tr_read<BOFF + v_rd_off(D0, 0, 0)>(vb), h0 = tr_read<BOFF + v_rd_off(D0, 0, 1)>(vb), l1 = tr_read<BOFF + v_rd_off(D0, 1, 0)>(vb), h1 = tr_read<BOFF + v_rd_off(D0, 1, 1)>(vb);
;   const s16x4 l2 = tr_read<BOFF + v_rd_off(D0, 2, 0)>(vb), h2 = tr_read<BOFF + v_rd_off(D0, 2, 1)>(vb), l3 = tr_read<BOFF + v_rd_off(D0, 3, 0)>(vb), h3 = tr_read<BOFF + v_rd_off(D0, 3, 1)>(vb);
;   asm volatile("s_waitcnt lgkmcnt(0)" ::: "memory"); SBAR();
;     ...
;   od = __builtin_amdgcn_mfma_f32_32x32x16_bf16(pa0, PK(l0, h0), od, 0, 0, 0);
;   od = __builtin_amdgcn_mfma_f32_32x32x16_bf16(pa1, PK(l1, h1), od, 0, 0, 0);
;   od = __builtin_amdgcn_mfma_f32_32x32x16_bf16(pa2, PK(l2, h2), od, 0, 0, 0);
;   od = __builtin_amdgcn_mfma_f32_32x32x16_bf16(pa3, PK(l3, h3), od, 0, 0, 0);
;     ...
; }
; template <int BOFF> __device__ __forceinline__ void pv_i(f32x16* o, int vb, bf16x8 pa0, bf16x8 pa1, bf16x8 pa2, bf16x8 pa3) {
;   pv_one_i<0, BOFF>(o[0], vb, pa0, pa1, pa2, pa3); pv_one_i<1, BOFF>(o[1], vb, pa0, pa1, pa2, pa3); pv_one_i<2, BOFF>(o[2], vb, pa0, pa1, pa2, pa3); pv_one_i<3, BOFF>(o[3], vb, pa0, pa1, pa2, pa3);
; }
	v_mfma_f32_32x32x16_bf16 v[0:15], v[68:71], v[184:187], v[0:15]
	ds_read_b64_tr_b16 v[184:185], v206 offset:0x1200
	ds_read_b64_tr_b16 v[186:187], v206 offset:0x1a00
	s_waitcnt lgkmcnt(7)
	v_mfma_f32_32x32x16_bf16 v[0:15], v[72:75], v[216:219], v[0:15]
	ds_read_b64_tr_b16 v[216:217], v206 offset:0x2200
	ds_read_b64_tr_b16 v[218:219], v206 offset:0x2a00
	s_waitcnt lgkmcnt(7)
	v_mfma_f32_32x32x16_bf16 v[0:15], v[76:79], v[220:223], v[0:15]
	ds_read_b64_tr_b16 v[220:221], v206 offset:0x3200
	ds_read_b64_tr_b16 v[222:223], v206 offset:0x3a00
	ds_write_b128 v212, v[150:153] offset:32768
	s_waitcnt lgkmcnt(7)
	v_mfma_f32_32x32x16_bf16 v[16:31], v[64:67], v[180:183], v[16:31]
	ds_read_b64_tr_b16 v[180:181], v206 offset:0x400
	ds_read_b64_tr_b16 v[182:183], v206 offset:0xc00
	s_waitcnt lgkmcnt(7)
	v_mfma_f32_32x32x16_bf16 v[16:31], v[68:71], v[184:187], v[16:31]
	ds_read_b64_tr_b16 v[184:185], v206 offset:0x1400
	ds_read_b64_tr_b16 v[186:187], v206 offset:0x1c00
	s_waitcnt lgkmcnt(7)
	v_mfma_f32_32x32x16_bf16 v[16:31], v[72:75], v[216:219], v[16:31]
	ds_read_b64_tr_b16 v[216:217], v206 offset:0x2400
	ds_read_b64_tr_b16 v[218:219], v206 offset:0x2c00
	s_waitcnt lgkmcnt(7)
	v_mfma_f32_32x32x16_bf16 v[16:31], v[76:79], v[220:223], v[16:31]
	ds_read_b64_tr_b16 v[220:221], v206 offset:0x3400
	ds_read_b64_tr_b16 v[222:223], v206 offset:0x3c00
	ds_write_b128 v213, v[154:157] offset:32768
	s_waitcnt lgkmcnt(7)
	v_mfma_f32_32x32x16_bf16 v[32:47], v[64:67], v[180:183], v[32:47]
	ds_read_b64_tr_b16 v[180:181], v206 offset:0x600
	ds_read_b64_tr_b16 v[182:183], v206 offset:0xe00
	s_waitcnt lgkmcnt(7)
	v_mfma_f32_32x32x16_bf16 v[32:47], v[68:71], v[184:187], v[32:47]
	ds_read_b64_tr_b16 v[184:185], v206 offset:0x1600
	ds_read_b64_tr_b16 v[186:187], v206 offset:0x1e00
	s_waitcnt lgkmcnt(7)
	v_mfma_f32_32x32x16_bf16 v[32:47], v[72:75], v[216:219], v[32:47]
	ds_read_b64_tr_b16 v[216:217], v206 offset:0x2600
	ds_read_b64_tr_b16 v[218:219], v206 offset:0x2e00
	s_waitcnt lgkmcnt(7)
	v_mfma_f32_32x32x16_bf16 v[32:47], v[76:79], v[220:223], v[32:47]
	ds_read_b64_tr_b16 v[220:221], v206 offset:0x3600
	ds_read_b64_tr_b16 v[222:223], v206 offset:0x3e00
	ds_write_b128 v214, v[158:161] offset:32768
	s_waitcnt lgkmcnt(7)
	v_mfma_f32_32x32x16_bf16 v[48:63], v[64:67], v[180:183], v[48:63]
	v_exp_f32_e32 v215, v108
	s_waitcnt vmcnt(4)
	v_exp_f32_e32 v181, v96
	v_exp_f32_e32 v183, v97
	v_exp_f32_e32 v188, v102
	v_exp_f32_e32 v189, v103
	v_exp_f32_e32 v196, v104
	s_waitcnt lgkmcnt(5)
	v_mfma_f32_32x32x16_bf16 v[48:63], v[68:71], v[184:187], v[48:63]
	v_exp_f32_e32 v184, v98
	v_exp_f32_e32 v185, v99
	v_exp_f32_e32 v186, v100
	v_exp_f32_e32 v187, v101
	v_exp_f32_e32 v197, v105
	v_exp_f32_e32 v198, v106
	v_exp_f32_e32 v199, v107
	s_waitcnt lgkmcnt(3)
	v_mfma_f32_32x32x16_bf16 v[48:63], v[72:75], v[216:219], v[48:63]
	v_exp_f32_e32 v216, v109
	v_exp_f32_e32 v217, v110
	v_exp_f32_e32 v218, v111
	s_waitcnt lgkmcnt(0)
	s_barrier
	v_mfma_f32_32x32x16_bf16 v[48:63], v[76:79], v[220:223], v[48:63]
	ds_read_b128 v[64:67], v207 offset:32768
	ds_read_b128 v[96:99], v207 offset:40960
	ds_read_b128 v[146:149], v208 offset:32768
	ds_read_b128 v[150:153], v208 offset:40960
	v_exp_f32_e32 v154, v88
	v_exp_f32_e32 v155, v89
	v_exp_f32_e32 v156, v90
	v_exp_f32_e32 v157, v91
	v_exp_f32_e32 v158, v92
	v_exp_f32_e32 v159, v93
	v_exp_f32_e32 v160, v94
	v_exp_f32_e32 v95, v95
	s_waitcnt lgkmcnt(3)
	v_mfma_f32_32x32x16_bf16 v[64:79], v[64:67], v[142:145], 0
	v_exp_f32_e32 v236, v80
	v_add_f32_e32 v80, 0, v181
	v_add_f32_e32 v80, v183, v80
	v_add_f32_e32 v80, v184, v80
	s_waitcnt lgkmcnt(2)
	v_mfma_f32_32x32x16_bf16 v[96:111], v[96:99], v[142:145], 0
	v_add_f32_e32 v80, v185, v80
	v_add_f32_e32 v80, v186, v80
	v_add_f32_e32 v80, v187, v80
	s_waitcnt lgkmcnt(1)
	v_mfma_f32_32x32x16_bf16 v[64:79], v[146:149], v[138:141], v[64:79]
	v_add_f32_e32 v80, v188, v80
	v_add_f32_e32 v80, v189, v80
	v_add_f32_e32 v80, v196, v80
	s_waitcnt lgkmcnt(0)
	v_mfma_f32_32x32x16_bf16 v[96:111], v[150:153], v[138:141], v[96:111]
	ds_read_b128 v[146:149], v209 offset:32768
	ds_read_b128 v[150:153], v209 offset:40960
	v_add_f32_e32 v80, v197, v80
	v_add_f32_e32 v80, v198, v80
	v_add_f32_e32 v80, v199, v80
	v_add_f32_e32 v80, v215, v80
	v_exp_f32_e32 v237, v81
	s_waitcnt lgkmcnt(1)
	v_mfma_f32_32x32x16_bf16 v[64:79], v[146:149], v[112:115], v[64:79]
	v_add_f32_e32 v80, v216, v80
	v_exp_f32_e32 v238, v82
	v_add_f32_e32 v80, v217, v80
	v_exp_f32_e32 v239, v83
	s_waitcnt lgkmcnt(0)
	v_mfma_f32_32x32x16_bf16 v[96:111], v[150:153], v[112:115], v[96:111]
	ds_read_b128 v[146:149], v210 offset:32768
	ds_read_b128 v[150:153], v210 offset:40960
	v_add_f32_e32 v80, v218, v80
	v_exp_f32_e32 v247, v84
	v_add_f32_e32 v80, v236, v80
	v_exp_f32_e32 v248, v85
	s_waitcnt lgkmcnt(1)
	v_mfma_f32_32x32x16_bf16 v[64:79], v[146:149], v[116:119], v[64:79]
	v_add_f32_e32 v80, v237, v80
	v_exp_f32_e32 v249, v86
	v_add_f32_e32 v80, v238, v80
	v_exp_f32_e32 v252, v87
	s_waitcnt lgkmcnt(0)
	v_mfma_f32_32x32x16_bf16 v[96:111], v[150:153], v[116:119], v[96:111]
	ds_read_b128 v[146:149], v190 offset:32768
	ds_read_b128 v[150:153], v190 offset:40960
	v_add_f32_e32 v80, v239, v80
	v_add_f32_e32 v80, v247, v80
	v_add_f32_e32 v80, v248, v80
	v_add_f32_e32 v80, v249, v80
	v_add_f32_e32 v80, v252, v80
	v_add_f32_e32 v80, v154, v80
	s_waitcnt lgkmcnt(1)
	v_mfma_f32_32x32x16_bf16 v[64:79], v[146:149], v[120:123], v[64:79]
	v_add_f32_e32 v80, v155, v80
	v_add_f32_e32 v80, v156, v80
	v_add_f32_e32 v80, v157, v80
	v_add_f32_e32 v80, v158, v80
	v_add_f32_e32 v80, v159, v80
	s_waitcnt lgkmcnt(0)
; #define SBAR() __builtin_amdgcn_sched_barrier(0)
; __device__ __forceinline__ void finishSM(f32x16& p0, f32x16& p1, float alpha, float& l_reg, bf16x8& pa0, bf16x8& pa1, bf16x8& pa2, bf16x8& pa3) {
;   for (int r = 0; r < 16; ++r) p1[r] = __builtin_amdgcn_exp2f(p1[r]);
;   float ps = 0; for (int r = 0; r < 16; ++r) ps += p0[r]; for (int r = 0; r < 16; ++r) ps += p1[r];
;   { auto rr = __builtin_amdgcn_permlane32_swap(__float_as_uint(ps), __float_as_uint(ps), false, false);
;     ps = __uint_as_float(rr[0]) + __uint_as_float(rr[1]); }
;   l_reg = l_reg * alpha + ps;
;     ...
;   PK4(p0, 0, pa0); PK4(p0, 8, pa1); PK4(p1, 0, pa2); PK4(p1, 8, pa3);
;     ...
; }
; template <int D0, int BOFF> __device__ __forceinline__ void pv_one_i(f32x16& od, int vb, bf16x8 pa0, bf16x8 pa1, bf16x8 pa2, bf16x8 pa3) {
;   const s16x4 l0 = tr_read<BOFF + v_rd_off(D0, 0, 0)>(vb), h0 = tr_read<BOFF + v_rd_off(D0, 0, 1)>(vb), l1 = tr_read<BOFF + v_rd_off(D0, 1, 0)>(vb), h1 = tr_read<BOFF + v_rd_off(D0, 1, 1)>(vb);
;   const s16x4 l2 = tr_read<BOFF + v_rd_off(D0, 2, 0)>(vb), h2 = tr_read<BOFF + v_rd_off(D0, 2, 1)>(vb), l3 = tr_read<BOFF + v_rd_off(D0, 3, 0)>(vb), h3 = tr_read<BOFF + v_rd_off(D0, 3, 1)>(vb);
;   asm volatile("s_waitcnt lgkmcnt(0)" ::: "memory"); SBAR();
;     ...
;   od = __builtin_amdgcn_mfma_f32_32x32x16_bf16(pa0, PK(l0, h0), od, 0, 0, 0);
;   od = __builtin_amdgcn_mfma_f32_32x32x16_bf16(pa1, PK(l1, h1), od, 0, 0, 0);
;   od = __builtin_amdgcn_mfma_f32_32x32x16_bf16(pa2, PK(l2, h2), od, 0, 0, 0);
;   od = __builtin_amdgcn_mfma_f32_32x32x16_bf16(pa3, PK(l3, h3), od, 0, 0, 0);
;     ...
; }
; template <int BOFF> __device__ __forceinline__ void pv_i(f32x16* o, int vb, bf16x8 pa0, bf16x8 pa1, bf16x8 pa2, bf16x8 pa3) {
;   pv_one_i<0, BOFF>(o[0], vb, pa0, pa1, pa2, pa3); pv_one_i<1, BOFF>(o[1], vb, pa0, pa1, pa2, pa3); pv_one_i<2, BOFF>(o[2], vb, pa0, pa1, pa2, pa3); pv_one_i<3, BOFF>(o[3], vb, pa0, pa1, pa2, pa3);
; }
	v_mfma_f32_32x32x16_bf16 v[96:111], v[150:153], v[120:123], v[96:111]
	ds_read_b128 v[146:149], v191 offset:32768
	ds_read_b128 v[150:153], v191 offset:40960
	v_add_f32_e32 v80, v160, v80
	v_add_f32_e32 v180, v95, v80
	v_mov_b32_e32 v182, v180
	v_cvt_pk_bf16_f32 v80, v181, v183
	v_cvt_pk_bf16_f32 v81, v184, v185
	v_cvt_pk_bf16_f32 v82, v186, v187
	s_waitcnt lgkmcnt(1)
	v_mfma_f32_32x32x16_bf16 v[64:79], v[146:149], v[124:127], v[64:79]
	v_cvt_pk_bf16_f32 v83, v188, v189
	v_cvt_pk_bf16_f32 v84, v196, v197
	v_cvt_pk_bf16_f32 v85, v198, v199
	v_cvt_pk_bf16_f32 v86, v215, v216
	v_cvt_pk_bf16_f32 v87, v217, v218
	s_waitcnt lgkmcnt(0)
	v_mfma_f32_32x32x16_bf16 v[96:111], v[150:153], v[124:127], v[96:111]
	ds_read_b128 v[146:149], v192 offset:32768
	ds_read_b128 v[150:153], v192 offset:40960
	v_cvt_pk_bf16_f32 v88, v236, v237
	v_cvt_pk_bf16_f32 v89, v238, v239
	v_cvt_pk_bf16_f32 v90, v247, v248
	v_cvt_pk_bf16_f32 v91, v249, v252
	v_cvt_pk_bf16_f32 v92, v154, v155
	v_cvt_pk_bf16_f32 v93, v156, v157
	s_waitcnt lgkmcnt(1)
	v_mfma_f32_32x32x16_bf16 v[64:79], v[146:149], v[130:133], v[64:79]
	v_cvt_pk_bf16_f32 v94, v158, v159
	v_cvt_pk_bf16_f32 v95, v160, v95
	s_nop 1
	v_permlane32_swap_b32_e32 v180, v182
	v_permlane32_swap_b32_e32 v80, v82
	s_waitcnt lgkmcnt(0)
	v_mfma_f32_32x32x16_bf16 v[96:111], v[150:153], v[130:133], v[96:111]
	ds_read_b128 v[146:149], v193 offset:32768
	ds_read_b128 v[150:153], v193 offset:40960
	ds_read_b64_tr_b16 v[184:185], v206 offset:0x4000
	ds_read_b64_tr_b16 v[186:187], v206 offset:0x4800
	ds_read_b64_tr_b16 v[216:217], v206 offset:0x5000
	ds_read_b64_tr_b16 v[218:219], v206 offset:0x5800
	ds_read_b64_tr_b16 v[220:221], v206 offset:0x6000
	ds_read_b64_tr_b16 v[222:223], v206 offset:0x6800
	ds_read_b64_tr_b16 v[224:225], v206 offset:0x7000
	ds_read_b64_tr_b16 v[226:227], v206 offset:0x7800
	v_permlane32_swap_b32_e32 v81, v83
	v_permlane32_swap_b32_e32 v84, v86
	v_permlane32_swap_b32_e32 v85, v87
	v_permlane32_swap_b32_e32 v88, v90
	v_permlane32_swap_b32_e32 v89, v91
	v_permlane32_swap_b32_e32 v92, v94
	s_waitcnt lgkmcnt(9)
	v_mfma_f32_32x32x16_bf16 v[64:79], v[146:149], v[134:137], v[64:79]
	v_permlane32_swap_b32_e32 v93, v95
	s_waitcnt lgkmcnt(8)
	v_mfma_f32_32x32x16_bf16 v[96:111], v[150:153], v[134:137], v[96:111]
	v_add_co_u32_e32 v150, vcc, s21, v178
	s_nop 1
	v_addc_co_u32_e32 v151, vcc, -1, v179, vcc
	v_add_co_u32_e32 v154, vcc, s22, v178
	s_nop 1
	v_addc_co_u32_e32 v155, vcc, -1, v179, vcc
	global_load_dwordx4 v[146:149], v[150:151], off
	s_nop 0
	global_load_dwordx4 v[150:153], v[150:151], off offset:-512
	s_nop 0
	global_load_dwordx4 v[158:161], v[154:155], off
	s_nop 0
	global_load_dwordx4 v[154:157], v[154:155], off offset:-512
	s_waitcnt vmcnt(4)
	ds_write_b128 v211, v[162:165]
	s_nop 0
	s_waitcnt lgkmcnt(7)
	v_mfma_f32_32x32x16_bf16 v[0:15], v[80:83], v[184:187], v[0:15]
	ds_read_b64_tr_b16 v[184:185], v206 offset:0x4200
	ds_read_b64_tr_b16 v[186:187], v206 offset:0x4a00
	s_waitcnt lgkmcnt(7)
	v_mfma_f32_32x32x16_bf16 v[0:15], v[84:87], v[216:219], v[0:15]
	ds_read_b64_tr_b16 v[216:217], v206 offset:0x5200
	ds_read_b64_tr_b16 v[218:219], v206 offset:0x5a00
	s_waitcnt lgkmcnt(7)
	v_mfma_f32_32x32x16_bf16 v[0:15], v[88:91], v[220:223], v[0:15]
	ds_read_b64_tr_b16 v[220:221], v206 offset:0x6200
	ds_read_b64_tr_b16 v[222:223], v206 offset:0x6a00
	s_waitcnt lgkmcnt(7)
	v_mfma_f32_32x32x16_bf16 v[0:15], v[92:95], v[224:227], v[0:15]
	ds_read_b64_tr_b16 v[224:225], v206 offset:0x7200
	ds_read_b64_tr_b16 v[226:227], v206 offset:0x7a00
	ds_write_b128 v212, v[174:177]
	s_waitcnt lgkmcnt(7)
	v_mfma_f32_32x32x16_bf16 v[16:31], v[80:83], v[184:187], v[16:31]
	ds_read_b64_tr_b16 v[184:185], v206 offset:0x4400
	ds_read_b64_tr_b16 v[186:187], v206 offset:0x4c00
	s_waitcnt lgkmcnt(7)
	v_mfma_f32_32x32x16_bf16 v[16:31], v[84:87], v[216:219], v[16:31]
	ds_read_b64_tr_b16 v[216:217], v206 offset:0x5400
	ds_read_b64_tr_b16 v[218:219], v206 offset:0x5c00
	s_waitcnt lgkmcnt(7)
	v_mfma_f32_32x32x16_bf16 v[16:31], v[88:91], v[220:223], v[16:31]
	ds_read_b64_tr_b16 v[220:221], v206 offset:0x6400
	ds_read_b64_tr_b16 v[222:223], v206 offset:0x6c00
	s_waitcnt lgkmcnt(7)
	v_mfma_f32_32x32x16_bf16 v[16:31], v[92:95], v[224:227], v[16:31]
	ds_read_b64_tr_b16 v[224:225], v206 offset:0x7400
	ds_read_b64_tr_b16 v[226:227], v206 offset:0x7c00
	ds_write_b128 v213, v[166:169]
	s_waitcnt lgkmcnt(7)
	v_mfma_f32_32x32x16_bf16 v[32:47], v[80:83], v[184:187], v[32:47]
	ds_read_b64_tr_b16 v[184:185], v206 offset:0x4600
	ds_read_b64_tr_b16 v[186:187], v206 offset:0x4e00
	s_waitcnt lgkmcnt(7)
	v_mfma_f32_32x32x16_bf16 v[32:47], v[84:87], v[216:219], v[32:47]
	ds_read_b64_tr_b16 v[216:217], v206 offset:0x5600
	ds_read_b64_tr_b16 v[218:219], v206 offset:0x5e00
	s_waitcnt lgkmcnt(7)
	v_mfma_f32_32x32x16_bf16 v[32:47], v[88:91], v[220:223], v[32:47]
	ds_read_b64_tr_b16 v[220:221], v206 offset:0x6600
	ds_read_b64_tr_b16 v[222:223], v206 offset:0x6e00
	s_waitcnt lgkmcnt(7)
	v_mfma_f32_32x32x16_bf16 v[32:47], v[92:95], v[224:227], v[32:47]
	ds_read_b64_tr_b16 v[224:225], v206 offset:0x7600
	ds_read_b64_tr_b16 v[226:227], v206 offset:0x7e00
	ds_write_b128 v214, v[170:173]
	s_waitcnt lgkmcnt(7)
	v_mfma_f32_32x32x16_bf16 v[48:63], v[80:83], v[184:187], v[48:63]
	v_exp_f32_e32 v215, v74
	s_waitcnt vmcnt(4)
	v_exp_f32_e32 v184, v64
	v_exp_f32_e32 v185, v65
	v_exp_f32_e32 v186, v66
	v_exp_f32_e32 v187, v67
	v_exp_f32_e32 v188, v68
	s_waitcnt lgkmcnt(5)
	v_mfma_f32_32x32x16_bf16 v[48:63], v[84:87], v[216:219], v[48:63]
	v_exp_f32_e32 v219, v78
	v_exp_f32_e32 v189, v69
	v_exp_f32_e32 v196, v70
	v_exp_f32_e32 v197, v71
	v_exp_f32_e32 v198, v72
	v_exp_f32_e32 v199, v73
	v_exp_f32_e32 v216, v75
	s_waitcnt lgkmcnt(3)
	v_mfma_f32_32x32x16_bf16 v[48:63], v[88:91], v[220:223], v[48:63]
	v_exp_f32_e32 v220, v79
	v_exp_f32_e32 v217, v76
	v_exp_f32_e32 v218, v77
	s_waitcnt lgkmcnt(0)
	s_barrier
; #define SBAR() __builtin_amdgcn_sched_barrier(0)
; __device__ __forceinline__ void finishSM(f32x16& p0, f32x16& p1, float alpha, float& l_reg, bf16x8& pa0, bf16x8& pa1, bf16x8& pa2, bf16x8& pa3) {
;   for (int r = 0; r < 16; ++r) p1[r] = __builtin_amdgcn_exp2f(p1[r]);
;   float ps = 0; for (int r = 0; r < 16; ++r) ps += p0[r]; for (int r = 0; r < 16; ++r) ps += p1[r];
;   { auto rr = __builtin_amdgcn_permlane32_swap(__float_as_uint(ps), __float_as_uint(ps), false, false);
;     ps = __uint_as_float(rr[0]) + __uint_as_float(rr[1]); }
;   l_reg = l_reg * alpha + ps;
;     ...
;   PK4(p0, 0, pa0); PK4(p0, 8, pa1); PK4(p1, 0, pa2); PK4(p1, 8, pa3);
;     ...
; }
; template <int BOFF> __device__ __forceinline__ void qkt_i(f32x16& p0, f32x16& p1, const int (&kb)[4], const bf16x8* qr) {
;   p0 = f32x16{}; p1 = f32x16{};
; #pragma unroll
;   for (int d0 = 0; d0 < 8; ++d0) { const int off = BOFF + (d0 >> 2) * 128;
;     const bf16x8 b0 = LDSV(kb[d0 & 3] + off), b1 = LDSV(kb[d0 & 3] + off + 8192);
;     p0 = __builtin_amdgcn_mfma_f32_32x32x16_bf16(b0, qr[d0], p0, 0, 0, 0);
;     p1 = __builtin_amdgcn_mfma_f32_32x32x16_bf16(b1, qr[d0], p1, 0, 0, 0); }
; }
; template <int D0, int BOFF> __device__ __forceinline__ void pv_one_i(f32x16& od, int vb, bf16x8 pa0, bf16x8 pa1, bf16x8 pa2, bf16x8 pa3) {
;   const s16x4 l0 = tr_read<BOFF + v_rd_off(D0, 0, 0)>(vb), h0 = tr_read<BOFF + v_rd_off(D0, 0, 1)>(vb), l1 = tr_read<BOFF + v_rd_off(D0, 1, 0)>(vb), h1 = tr_read<BOFF + v_rd_off(D0, 1, 1)>(vb);
;   const s16x4 l2 = tr_read<BOFF + v_rd_off(D0, 2, 0)>(vb), h2 = tr_read<BOFF + v_rd_off(D0, 2, 1)>(vb), l3 = tr_read<BOFF + v_rd_off(D0, 3, 0)>(vb), h3 = tr_read<BOFF + v_rd_off(D0, 3, 1)>(vb);
;   asm volatile("s_waitcnt lgkmcnt(0)" ::: "memory"); SBAR();
;     ...
;   od = __builtin_amdgcn_mfma_f32_32x32x16_bf16(pa0, PK(l0, h0), od, 0, 0, 0);
;   od = __builtin_amdgcn_mfma_f32_32x32x16_bf16(pa1, PK(l1, h1), od, 0, 0, 0);
;   od = __builtin_amdgcn_mfma_f32_32x32x16_bf16(pa2, PK(l2, h2), od, 0, 0, 0);
;   od = __builtin_amdgcn_mfma_f32_32x32x16_bf16(pa3, PK(l3, h3), od, 0, 0, 0);
;     ...
; }
; template <int BOFF> __device__ __forceinline__ void pv_i(f32x16* o, int vb, bf16x8 pa0, bf16x8 pa1, bf16x8 pa2, bf16x8 pa3) {
;   pv_one_i<0, BOFF>(o[0], vb, pa0, pa1, pa2, pa3); pv_one_i<1, BOFF>(o[1], vb, pa0, pa1, pa2, pa3); pv_one_i<2, BOFF>(o[2], vb, pa0, pa1, pa2, pa3); pv_one_i<3, BOFF>(o[3], vb, pa0, pa1, pa2, pa3);
; }
	v_mfma_f32_32x32x16_bf16 v[48:63], v[92:95], v[224:227], v[48:63]
	ds_read_b128 v[64:67], v207
	ds_read_b128 v[68:71], v207 offset:8192
	ds_read_b128 v[162:165], v208
	ds_read_b128 v[166:169], v208 offset:8192
	v_exp_f32_e32 v170, v104
	v_exp_f32_e32 v171, v105
	v_exp_f32_e32 v172, v106
	v_exp_f32_e32 v173, v107
	v_exp_f32_e32 v174, v108
	v_exp_f32_e32 v175, v109
	v_exp_f32_e32 v176, v110
	v_exp_f32_e32 v111, v111
	s_waitcnt lgkmcnt(3)
	v_mfma_f32_32x32x16_bf16 v[80:95], v[64:67], v[142:145], 0
	v_exp_f32_e32 v236, v96
	v_add_f32_e32 v96, 0, v184
	v_add_f32_e32 v96, v185, v96
	v_add_f32_e32 v96, v186, v96
	s_waitcnt lgkmcnt(2)
	v_mfma_f32_32x32x16_bf16 v[64:79], v[68:71], v[142:145], 0
	v_add_f32_e32 v96, v187, v96
	v_add_f32_e32 v96, v188, v96
	v_add_f32_e32 v96, v189, v96
	s_waitcnt lgkmcnt(1)
	v_mfma_f32_32x32x16_bf16 v[80:95], v[162:165], v[138:141], v[80:95]
	v_add_f32_e32 v96, v196, v96
	v_add_f32_e32 v96, v197, v96
	v_add_f32_e32 v96, v198, v96
	s_waitcnt lgkmcnt(0)
	v_mfma_f32_32x32x16_bf16 v[64:79], v[166:169], v[138:141], v[64:79]
	ds_read_b128 v[162:165], v209
	ds_read_b128 v[166:169], v209 offset:8192
	v_add_f32_e32 v96, v199, v96
	v_add_f32_e32 v96, v215, v96
	v_add_f32_e32 v96, v216, v96
	v_add_f32_e32 v96, v217, v96
	v_exp_f32_e32 v237, v97
	s_waitcnt lgkmcnt(1)
	v_mfma_f32_32x32x16_bf16 v[80:95], v[162:165], v[112:115], v[80:95]
	v_add_f32_e32 v96, v218, v96
	v_exp_f32_e32 v238, v98
	v_add_f32_e32 v96, v219, v96
	v_exp_f32_e32 v239, v99
	s_waitcnt lgkmcnt(0)
	v_mfma_f32_32x32x16_bf16 v[64:79], v[166:169], v[112:115], v[64:79]
	ds_read_b128 v[162:165], v210
	ds_read_b128 v[166:169], v210 offset:8192
	v_add_f32_e32 v96, v220, v96
	v_exp_f32_e32 v247, v100
	v_add_f32_e32 v96, v236, v96
	v_exp_f32_e32 v248, v101
	s_waitcnt lgkmcnt(1)
	v_mfma_f32_32x32x16_bf16 v[80:95], v[162:165], v[116:119], v[80:95]
	v_add_f32_e32 v96, v237, v96
	v_exp_f32_e32 v249, v102
	v_add_f32_e32 v96, v238, v96
	v_exp_f32_e32 v252, v103
	s_waitcnt lgkmcnt(0)
	v_mfma_f32_32x32x16_bf16 v[64:79], v[166:169], v[116:119], v[64:79]
	ds_read_b128 v[162:165], v190 offset:0
	ds_read_b128 v[166:169], v190 offset:8192
	v_add_f32_e32 v96, v239, v96
	v_add_f32_e32 v96, v247, v96
	v_add_f32_e32 v96, v248, v96
	v_add_f32_e32 v96, v249, v96
	v_add_f32_e32 v96, v252, v96
	v_add_f32_e32 v96, v170, v96
	s_waitcnt lgkmcnt(1)
	v_mfma_f32_32x32x16_bf16 v[80:95], v[162:165], v[120:123], v[80:95]
	v_add_f32_e32 v96, v171, v96
	v_add_f32_e32 v96, v172, v96
	v_add_f32_e32 v96, v173, v96
	v_add_f32_e32 v96, v174, v96
	v_add_f32_e32 v96, v175, v96
	s_waitcnt lgkmcnt(0)
	v_mfma_f32_32x32x16_bf16 v[64:79], v[166:169], v[120:123], v[64:79]
	ds_read_b128 v[162:165], v191 offset:0
	ds_read_b128 v[166:169], v191 offset:8192
	v_add_f32_e32 v96, v176, v96
	v_add_f32_e32 v181, v111, v96
	v_mov_b32_e32 v183, v181
	s_nop 1
	v_permlane32_swap_b32_e32 v181, v183
	v_pk_add_f32 v[96:97], v[180:181], v[182:183]
	s_waitcnt lgkmcnt(1)
	v_mfma_f32_32x32x16_bf16 v[80:95], v[162:165], v[124:127], v[80:95]
	s_nop 0
	v_add_f32_e32 v96, v128, v96
	v_add_f32_e32 v128, v96, v97
	v_cvt_pk_bf16_f32 v96, v184, v185
	v_cvt_pk_bf16_f32 v97, v186, v187
	s_waitcnt lgkmcnt(0)
	v_mfma_f32_32x32x16_bf16 v[64:79], v[166:169], v[124:127], v[64:79]
	ds_read_b128 v[162:165], v192 offset:0
	ds_read_b128 v[166:169], v192 offset:8192
	v_cvt_pk_bf16_f32 v98, v188, v189
	v_cvt_pk_bf16_f32 v99, v196, v197
	v_cvt_pk_bf16_f32 v100, v198, v199
	v_cvt_pk_bf16_f32 v101, v215, v216
	v_cvt_pk_bf16_f32 v102, v217, v218
	v_cvt_pk_bf16_f32 v103, v219, v220
	s_waitcnt lgkmcnt(1)
	v_mfma_f32_32x32x16_bf16 v[80:95], v[162:165], v[130:133], v[80:95]
	v_cvt_pk_bf16_f32 v104, v236, v237
	v_cvt_pk_bf16_f32 v105, v238, v239
	v_cvt_pk_bf16_f32 v106, v247, v248
	v_cvt_pk_bf16_f32 v107, v249, v252
	v_cvt_pk_bf16_f32 v108, v170, v171
	s_waitcnt lgkmcnt(0)
	v_mfma_f32_32x32x16_bf16 v[64:79], v[166:169], v[130:133], v[64:79]
	ds_read_b128 v[162:165], v193 offset:0
	ds_read_b128 v[166:169], v193 offset:8192
	ds_read_b64_tr_b16 v[180:181], v206 offset:0x8000
	ds_read_b64_tr_b16 v[182:183], v206 offset:0x8800
	ds_read_b64_tr_b16 v[184:185], v206 offset:0x9000
	ds_read_b64_tr_b16 v[186:187], v206 offset:0x9800
	ds_read_b64_tr_b16 v[216:217], v206 offset:0xa000
	ds_read_b64_tr_b16 v[218:219], v206 offset:0xa800
	ds_read_b64_tr_b16 v[220:221], v206 offset:0xb000
	ds_read_b64_tr_b16 v[222:223], v206 offset:0xb800
	v_cvt_pk_bf16_f32 v109, v172, v173
	v_cvt_pk_bf16_f32 v110, v174, v175
	v_cvt_pk_bf16_f32 v111, v176, v111
	s_nop 0
	v_permlane32_swap_b32_e32 v96, v98
	v_permlane32_swap_b32_e32 v97, v99
	s_waitcnt lgkmcnt(9)
	v_mfma_f32_32x32x16_bf16 v[80:95], v[162:165], v[134:137], v[80:95]
	v_permlane32_swap_b32_e32 v100, v102
	v_permlane32_swap_b32_e32 v101, v103
	v_permlane32_swap_b32_e32 v104, v106
	v_permlane32_swap_b32_e32 v105, v107
	v_permlane32_swap_b32_e32 v108, v110
	s_waitcnt lgkmcnt(8)
	v_mfma_f32_32x32x16_bf16 v[64:79], v[166:169], v[134:137], v[64:79]
	v_permlane32_swap_b32_e32 v109, v111
	v_add_co_u32_e32 v166, vcc, s23, v178
	s_nop 1
	v_addc_co_u32_e32 v167, vcc, -1, v179, vcc
	v_add_co_u32_e32 v170, vcc, s24, v178
	s_nop 1
	v_addc_co_u32_e32 v171, vcc, -1, v179, vcc
	global_load_dwordx4 v[162:165], v[166:167], off
	s_nop 0
	global_load_dwordx4 v[166:169], v[166:167], off offset:-512
	s_nop 0
	global_load_dwordx4 v[174:177], v[170:171], off
	s_nop 0
	global_load_dwordx4 v[170:173], v[170:171], off offset:-512
	s_waitcnt vmcnt(4)
	ds_write_b128 v211, v[146:149] offset:16384
	s_nop 0
	s_waitcnt lgkmcnt(7)
	v_mfma_f32_32x32x16_bf16 v[0:15], v[96:99], v[180:183], v[0:15]
	ds_read_b64_tr_b16 v[180:181], v206 offset:0x8200
	ds_read_b64_tr_b16 v[182:183], v206 offset:0x8a00
	s_waitcnt lgkmcnt(7)
; #define SBAR() __builtin_amdgcn_sched_barrier(0)
; __device__ __forceinline__ void partialSM_fixed(f32x16& p0) {
;   for (int r = 0; r < 16; ++r) p0[r] = __builtin_amdgcn_exp2f(p0[r]);
; }
; template <int D0, int BOFF> __device__ __forceinline__ void pv_one_i(f32x16& od, int vb, bf16x8 pa0, bf16x8 pa1, bf16x8 pa2, bf16x8 pa3) {
;   const s16x4 l0 = tr_read<BOFF + v_rd_off(D0, 0, 0)>(vb), h0 = tr_read<BOFF + v_rd_off(D0, 0, 1)>(vb), l1 = tr_read<BOFF + v_rd_off(D0, 1, 0)>(vb), h1 = tr_read<BOFF + v_rd_off(D0, 1, 1)>(vb);
;   const s16x4 l2 = tr_read<BOFF + v_rd_off(D0, 2, 0)>(vb), h2 = tr_read<BOFF + v_rd_off(D0, 2, 1)>(vb), l3 = tr_read<BOFF + v_rd_off(D0, 3, 0)>(vb), h3 = tr_read<BOFF + v_rd_off(D0, 3, 1)>(vb);
;   asm volatile("s_waitcnt lgkmcnt(0)" ::: "memory"); SBAR();
;     ...
;   od = __builtin_amdgcn_mfma_f32_32x32x16_bf16(pa0, PK(l0, h0), od, 0, 0, 0);
;   od = __builtin_amdgcn_mfma_f32_32x32x16_bf16(pa1, PK(l1, h1), od, 0, 0, 0);
;   od = __builtin_amdgcn_mfma_f32_32x32x16_bf16(pa2, PK(l2, h2), od, 0, 0, 0);
;   od = __builtin_amdgcn_mfma_f32_32x32x16_bf16(pa3, PK(l3, h3), od, 0, 0, 0);
;     ...
; }
; template <int BOFF> __device__ __forceinline__ void pv_i(f32x16* o, int vb, bf16x8 pa0, bf16x8 pa1, bf16x8 pa2, bf16x8 pa3) {
;   pv_one_i<0, BOFF>(o[0], vb, pa0, pa1, pa2, pa3); pv_one_i<1, BOFF>(o[1], vb, pa0, pa1, pa2, pa3); pv_one_i<2, BOFF>(o[2], vb, pa0, pa1, pa2, pa3); pv_one_i<3, BOFF>(o[3], vb, pa0, pa1, pa2, pa3);
; }
	v_mfma_f32_32x32x16_bf16 v[0:15], v[100:103], v[184:187], v[0:15]
	ds_read_b64_tr_b16 v[184:185], v206 offset:0x9200
	ds_read_b64_tr_b16 v[186:187], v206 offset:0x9a00
	s_waitcnt lgkmcnt(7)
	v_mfma_f32_32x32x16_bf16 v[0:15], v[104:107], v[216:219], v[0:15]
	ds_read_b64_tr_b16 v[216:217], v206 offset:0xa200
	ds_read_b64_tr_b16 v[218:219], v206 offset:0xaa00
	s_waitcnt lgkmcnt(7)
	v_mfma_f32_32x32x16_bf16 v[0:15], v[108:111], v[220:223], v[0:15]
	ds_read_b64_tr_b16 v[220:221], v206 offset:0xb200
	ds_read_b64_tr_b16 v[222:223], v206 offset:0xba00
	ds_write_b128 v212, v[158:161] offset:16384
	s_waitcnt lgkmcnt(7)
	v_mfma_f32_32x32x16_bf16 v[16:31], v[96:99], v[180:183], v[16:31]
	ds_read_b64_tr_b16 v[180:181], v206 offset:0x8400
	ds_read_b64_tr_b16 v[182:183], v206 offset:0x8c00
	s_waitcnt lgkmcnt(7)
	v_mfma_f32_32x32x16_bf16 v[16:31], v[100:103], v[184:187], v[16:31]
	ds_read_b64_tr_b16 v[184:185], v206 offset:0x9400
	ds_read_b64_tr_b16 v[186:187], v206 offset:0x9c00
	s_waitcnt lgkmcnt(7)
	v_mfma_f32_32x32x16_bf16 v[16:31], v[104:107], v[216:219], v[16:31]
	ds_read_b64_tr_b16 v[216:217], v206 offset:0xa400
	ds_read_b64_tr_b16 v[218:219], v206 offset:0xac00
	s_waitcnt lgkmcnt(7)
	v_mfma_f32_32x32x16_bf16 v[16:31], v[108:111], v[220:223], v[16:31]
	ds_read_b64_tr_b16 v[220:221], v206 offset:0xb400
	ds_read_b64_tr_b16 v[222:223], v206 offset:0xbc00
	ds_write_b128 v213, v[150:153] offset:16384
	s_waitcnt lgkmcnt(7)
	v_mfma_f32_32x32x16_bf16 v[32:47], v[96:99], v[180:183], v[32:47]
	ds_read_b64_tr_b16 v[180:181], v206 offset:0x8600
	ds_read_b64_tr_b16 v[182:183], v206 offset:0x8e00
	s_waitcnt lgkmcnt(7)
	v_mfma_f32_32x32x16_bf16 v[32:47], v[100:103], v[184:187], v[32:47]
	ds_read_b64_tr_b16 v[184:185], v206 offset:0x9600
	ds_read_b64_tr_b16 v[186:187], v206 offset:0x9e00
	s_waitcnt lgkmcnt(7)
	v_mfma_f32_32x32x16_bf16 v[32:47], v[104:107], v[216:219], v[32:47]
	ds_read_b64_tr_b16 v[216:217], v206 offset:0xa600
	ds_read_b64_tr_b16 v[218:219], v206 offset:0xae00
	s_waitcnt lgkmcnt(7)
	v_mfma_f32_32x32x16_bf16 v[32:47], v[108:111], v[220:223], v[32:47]
	ds_read_b64_tr_b16 v[220:221], v206 offset:0xb600
	ds_read_b64_tr_b16 v[222:223], v206 offset:0xbe00
	ds_write_b128 v214, v[154:157] offset:16384
	s_waitcnt lgkmcnt(7)
	v_mfma_f32_32x32x16_bf16 v[48:63], v[96:99], v[180:183], v[48:63]
	v_exp_f32_e32 v215, v92
	s_waitcnt vmcnt(4)
	v_exp_f32_e32 v181, v80
	v_exp_f32_e32 v183, v81
	v_exp_f32_e32 v188, v86
	v_exp_f32_e32 v189, v87
	v_exp_f32_e32 v196, v88
	s_waitcnt lgkmcnt(5)
	v_mfma_f32_32x32x16_bf16 v[48:63], v[100:103], v[184:187], v[48:63]
	v_exp_f32_e32 v184, v82
	v_exp_f32_e32 v185, v83
	v_exp_f32_e32 v186, v84
	v_exp_f32_e32 v187, v85
	v_exp_f32_e32 v197, v89
	v_exp_f32_e32 v198, v90
	v_exp_f32_e32 v199, v91
	s_waitcnt lgkmcnt(3)
	v_mfma_f32_32x32x16_bf16 v[48:63], v[104:107], v[216:219], v[48:63]
	v_exp_f32_e32 v216, v93
	v_exp_f32_e32 v217, v94
	v_exp_f32_e32 v218, v95
	s_waitcnt lgkmcnt(0)
	s_barrier
	v_mfma_f32_32x32x16_bf16 v[48:63], v[108:111], v[220:223], v[48:63]
	ds_read_b128 v[80:83], v207 offset:16384
	ds_read_b128 v[96:99], v207 offset:24576
	ds_read_b128 v[146:149], v208 offset:16384
	ds_read_b128 v[150:153], v208 offset:24576
	v_exp_f32_e32 v154, v72
	v_exp_f32_e32 v155, v73
	v_exp_f32_e32 v156, v74
	v_exp_f32_e32 v157, v75
	v_exp_f32_e32 v158, v76
	v_exp_f32_e32 v159, v77
	v_exp_f32_e32 v160, v78
	v_exp_f32_e32 v79, v79
	s_waitcnt lgkmcnt(3)
	v_mfma_f32_32x32x16_bf16 v[80:95], v[80:83], v[142:145], 0
	v_exp_f32_e32 v236, v64
	v_add_f32_e32 v64, 0, v181
	v_add_f32_e32 v64, v183, v64
	v_add_f32_e32 v64, v184, v64
	s_waitcnt lgkmcnt(2)
	v_mfma_f32_32x32x16_bf16 v[96:111], v[96:99], v[142:145], 0
	v_add_f32_e32 v64, v185, v64
	v_add_f32_e32 v64, v186, v64
	v_add_f32_e32 v64, v187, v64
	s_waitcnt lgkmcnt(1)
	v_mfma_f32_32x32x16_bf16 v[80:95], v[146:149], v[138:141], v[80:95]
	v_add_f32_e32 v64, v188, v64
	v_add_f32_e32 v64, v189, v64
	v_add_f32_e32 v64, v196, v64
	s_waitcnt lgkmcnt(0)
	v_mfma_f32_32x32x16_bf16 v[96:111], v[150:153], v[138:141], v[96:111]
	ds_read_b128 v[146:149], v209 offset:16384
	ds_read_b128 v[150:153], v209 offset:24576
	v_add_f32_e32 v64, v197, v64
	v_add_f32_e32 v64, v198, v64
	v_add_f32_e32 v64, v199, v64
	v_add_f32_e32 v64, v215, v64
	v_exp_f32_e32 v237, v65
	s_waitcnt lgkmcnt(1)
	v_mfma_f32_32x32x16_bf16 v[80:95], v[146:149], v[112:115], v[80:95]
	v_add_f32_e32 v64, v216, v64
	v_exp_f32_e32 v238, v66
	v_add_f32_e32 v64, v217, v64
	v_exp_f32_e32 v239, v67
	s_waitcnt lgkmcnt(0)
	v_mfma_f32_32x32x16_bf16 v[96:111], v[150:153], v[112:115], v[96:111]
	ds_read_b128 v[146:149], v210 offset:16384
	ds_read_b128 v[150:153], v210 offset:24576
	v_add_f32_e32 v64, v218, v64
	v_exp_f32_e32 v247, v68
	v_add_f32_e32 v64, v236, v64
	v_exp_f32_e32 v248, v69
	s_waitcnt lgkmcnt(1)
	v_mfma_f32_32x32x16_bf16 v[80:95], v[146:149], v[116:119], v[80:95]
	v_add_f32_e32 v64, v237, v64
	v_exp_f32_e32 v249, v70
	v_add_f32_e32 v64, v238, v64
	v_exp_f32_e32 v252, v71
	s_waitcnt lgkmcnt(0)
	v_mfma_f32_32x32x16_bf16 v[96:111], v[150:153], v[116:119], v[96:111]
	ds_read_b128 v[146:149], v190 offset:16384
	ds_read_b128 v[150:153], v190 offset:24576
	v_add_f32_e32 v64, v239, v64
	v_add_f32_e32 v64, v247, v64
	v_add_f32_e32 v64, v248, v64
	v_add_f32_e32 v64, v249, v64
	v_add_f32_e32 v64, v252, v64
	v_add_f32_e32 v64, v154, v64
	s_waitcnt lgkmcnt(1)
	v_mfma_f32_32x32x16_bf16 v[80:95], v[146:149], v[120:123], v[80:95]
	v_add_f32_e32 v64, v155, v64
	v_add_f32_e32 v64, v156, v64
	v_add_f32_e32 v64, v157, v64
	v_add_f32_e32 v64, v158, v64
	v_add_f32_e32 v64, v159, v64
	s_waitcnt lgkmcnt(0)
; #define SBAR() __builtin_amdgcn_sched_barrier(0)
; __device__ __forceinline__ void finishSM(f32x16& p0, f32x16& p1, float alpha, float& l_reg, bf16x8& pa0, bf16x8& pa1, bf16x8& pa2, bf16x8& pa3) {
;   for (int r = 0; r < 16; ++r) p1[r] = __builtin_amdgcn_exp2f(p1[r]);
;   float ps = 0; for (int r = 0; r < 16; ++r) ps += p0[r]; for (int r = 0; r < 16; ++r) ps += p1[r];
;   { auto rr = __builtin_amdgcn_permlane32_swap(__float_as_uint(ps), __float_as_uint(ps), false, false);
;     ps = __uint_as_float(rr[0]) + __uint_as_float(rr[1]); }
;   l_reg = l_reg * alpha + ps;
;     ...
;   PK4(p0, 0, pa0); PK4(p0, 8, pa1); PK4(p1, 0, pa2); PK4(p1, 8, pa3);
;     ...
; }
; template <int D0, int BOFF> __device__ __forceinline__ void pv_one_i(f32x16& od, int vb, bf16x8 pa0, bf16x8 pa1, bf16x8 pa2, bf16x8 pa3) {
;   const s16x4 l0 = tr_read<BOFF + v_rd_off(D0, 0, 0)>(vb), h0 = tr_read<BOFF + v_rd_off(D0, 0, 1)>(vb), l1 = tr_read<BOFF + v_rd_off(D0, 1, 0)>(vb), h1 = tr_read<BOFF + v_rd_off(D0, 1, 1)>(vb);
;   const s16x4 l2 = tr_read<BOFF + v_rd_off(D0, 2, 0)>(vb), h2 = tr_read<BOFF + v_rd_off(D0, 2, 1)>(vb), l3 = tr_read<BOFF + v_rd_off(D0, 3, 0)>(vb), h3 = tr_read<BOFF + v_rd_off(D0, 3, 1)>(vb);
;   asm volatile("s_waitcnt lgkmcnt(0)" ::: "memory"); SBAR();
;     ...
;   od = __builtin_amdgcn_mfma_f32_32x32x16_bf16(pa0, PK(l0, h0), od, 0, 0, 0);
;   od = __builtin_amdgcn_mfma_f32_32x32x16_bf16(pa1, PK(l1, h1), od, 0, 0, 0);
;   od = __builtin_amdgcn_mfma_f32_32x32x16_bf16(pa2, PK(l2, h2), od, 0, 0, 0);
;   od = __builtin_amdgcn_mfma_f32_32x32x16_bf16(pa3, PK(l3, h3), od, 0, 0, 0);
;     ...
; }
; template <int BOFF> __device__ __forceinline__ void pv_i(f32x16* o, int vb, bf16x8 pa0, bf16x8 pa1, bf16x8 pa2, bf16x8 pa3) {
;   pv_one_i<0, BOFF>(o[0], vb, pa0, pa1, pa2, pa3); pv_one_i<1, BOFF>(o[1], vb, pa0, pa1, pa2, pa3); pv_one_i<2, BOFF>(o[2], vb, pa0, pa1, pa2, pa3); pv_one_i<3, BOFF>(o[3], vb, pa0, pa1, pa2, pa3);
; }
	v_mfma_f32_32x32x16_bf16 v[96:111], v[150:153], v[120:123], v[96:111]
	ds_read_b128 v[146:149], v191 offset:16384
	ds_read_b128 v[150:153], v191 offset:24576
	v_add_f32_e32 v64, v160, v64
	v_add_f32_e32 v180, v79, v64
	v_cvt_pk_bf16_f32 v64, v181, v183
	v_cvt_pk_bf16_f32 v65, v184, v185
	v_cvt_pk_bf16_f32 v66, v186, v187
	v_cvt_pk_bf16_f32 v67, v188, v189
	s_waitcnt lgkmcnt(1)
	v_mfma_f32_32x32x16_bf16 v[80:95], v[146:149], v[124:127], v[80:95]
	v_cvt_pk_bf16_f32 v68, v196, v197
	v_cvt_pk_bf16_f32 v69, v198, v199
	v_cvt_pk_bf16_f32 v70, v215, v216
	v_cvt_pk_bf16_f32 v71, v217, v218
	v_cvt_pk_bf16_f32 v72, v236, v237
	s_waitcnt lgkmcnt(0)
	v_mfma_f32_32x32x16_bf16 v[96:111], v[150:153], v[124:127], v[96:111]
	ds_read_b128 v[146:149], v192 offset:16384
	ds_read_b128 v[150:153], v192 offset:24576
	v_cvt_pk_bf16_f32 v73, v238, v239
	v_cvt_pk_bf16_f32 v74, v247, v248
	v_cvt_pk_bf16_f32 v75, v249, v252
	v_cvt_pk_bf16_f32 v76, v154, v155
	v_cvt_pk_bf16_f32 v77, v156, v157
	v_cvt_pk_bf16_f32 v78, v158, v159
	s_waitcnt lgkmcnt(1)
	v_mfma_f32_32x32x16_bf16 v[80:95], v[146:149], v[130:133], v[80:95]
	v_cvt_pk_bf16_f32 v79, v160, v79
	v_mov_b32_e32 v182, v180
	v_permlane32_swap_b32_e32 v64, v66
	v_permlane32_swap_b32_e32 v65, v67
	v_permlane32_swap_b32_e32 v68, v70
	s_waitcnt lgkmcnt(0)
	v_mfma_f32_32x32x16_bf16 v[96:111], v[150:153], v[130:133], v[96:111]
	ds_read_b128 v[146:149], v193 offset:16384
	ds_read_b128 v[150:153], v193 offset:24576
	ds_read_b64_tr_b16 v[184:185], v206 offset:0
	ds_read_b64_tr_b16 v[186:187], v206 offset:0x800
	ds_read_b64_tr_b16 v[216:217], v206 offset:0x1000
	ds_read_b64_tr_b16 v[218:219], v206 offset:0x1800
	ds_read_b64_tr_b16 v[220:221], v206 offset:0x2000
	ds_read_b64_tr_b16 v[222:223], v206 offset:0x2800
	ds_read_b64_tr_b16 v[224:225], v206 offset:0x3000
	ds_read_b64_tr_b16 v[226:227], v206 offset:0x3800
	v_permlane32_swap_b32_e32 v69, v71
	v_permlane32_swap_b32_e32 v72, v74
	v_permlane32_swap_b32_e32 v73, v75
	v_permlane32_swap_b32_e32 v76, v78
	v_permlane32_swap_b32_e32 v77, v79
	v_permlane32_swap_b32_e32 v180, v182
	s_waitcnt lgkmcnt(9)
	v_mfma_f32_32x32x16_bf16 v[80:95], v[146:149], v[134:137], v[80:95]
	s_waitcnt lgkmcnt(8)
	v_mfma_f32_32x32x16_bf16 v[96:111], v[150:153], v[134:137], v[96:111]
	v_add_co_u32_e32 v150, vcc, s25, v178
	s_nop 1
	v_addc_co_u32_e32 v151, vcc, -1, v179, vcc
	v_add_co_u32_e32 v154, vcc, s45, v178
	s_nop 1
	v_addc_co_u32_e32 v155, vcc, -1, v179, vcc
	global_load_dwordx4 v[146:149], v[150:151], off
	s_nop 0
	global_load_dwordx4 v[150:153], v[150:151], off offset:-512
	s_nop 0
	global_load_dwordx4 v[158:161], v[154:155], off
	s_nop 0
	global_load_dwordx4 v[154:157], v[154:155], off offset:-512
	s_waitcnt vmcnt(4)
	ds_write_b128 v211, v[162:165] offset:32768
	s_nop 0
	s_waitcnt lgkmcnt(7)
	v_mfma_f32_32x32x16_bf16 v[0:15], v[64:67], v[184:187], v[0:15]
	ds_read_b64_tr_b16 v[184:185], v206 offset:0x200
	ds_read_b64_tr_b16 v[186:187], v206 offset:0xa00
	s_waitcnt lgkmcnt(7)
	v_mfma_f32_32x32x16_bf16 v[0:15], v[68:71], v[216:219], v[0:15]
	ds_read_b64_tr_b16 v[216:217], v206 offset:0x1200
	ds_read_b64_tr_b16 v[218:219], v206 offset:0x1a00
	s_waitcnt lgkmcnt(7)
	v_mfma_f32_32x32x16_bf16 v[0:15], v[72:75], v[220:223], v[0:15]
	ds_read_b64_tr_b16 v[220:221], v206 offset:0x2200
	ds_read_b64_tr_b16 v[222:223], v206 offset:0x2a00
	s_waitcnt lgkmcnt(7)
	v_mfma_f32_32x32x16_bf16 v[0:15], v[76:79], v[224:227], v[0:15]
	ds_read_b64_tr_b16 v[224:225], v206 offset:0x3200
	ds_read_b64_tr_b16 v[226:227], v206 offset:0x3a00
	ds_write_b128 v212, v[174:177] offset:32768
	s_waitcnt lgkmcnt(7)
	v_mfma_f32_32x32x16_bf16 v[16:31], v[64:67], v[184:187], v[16:31]
	ds_read_b64_tr_b16 v[184:185], v206 offset:0x400
	ds_read_b64_tr_b16 v[186:187], v206 offset:0xc00
	s_waitcnt lgkmcnt(7)
	v_mfma_f32_32x32x16_bf16 v[16:31], v[68:71], v[216:219], v[16:31]
	ds_read_b64_tr_b16 v[216:217], v206 offset:0x1400
	ds_read_b64_tr_b16 v[218:219], v206 offset:0x1c00
	s_waitcnt lgkmcnt(7)
	v_mfma_f32_32x32x16_bf16 v[16:31], v[72:75], v[220:223], v[16:31]
	ds_read_b64_tr_b16 v[220:221], v206 offset:0x2400
	ds_read_b64_tr_b16 v[222:223], v206 offset:0x2c00
	s_waitcnt lgkmcnt(7)
	v_mfma_f32_32x32x16_bf16 v[16:31], v[76:79], v[224:227], v[16:31]
	ds_read_b64_tr_b16 v[224:225], v206 offset:0x3400
	ds_read_b64_tr_b16 v[226:227], v206 offset:0x3c00
	ds_write_b128 v213, v[166:169] offset:32768
	s_waitcnt lgkmcnt(7)
	v_mfma_f32_32x32x16_bf16 v[32:47], v[64:67], v[184:187], v[32:47]
	ds_read_b64_tr_b16 v[184:185], v206 offset:0x600
	ds_read_b64_tr_b16 v[186:187], v206 offset:0xe00
	s_waitcnt lgkmcnt(7)
	v_mfma_f32_32x32x16_bf16 v[32:47], v[68:71], v[216:219], v[32:47]
	ds_read_b64_tr_b16 v[216:217], v206 offset:0x1600
	ds_read_b64_tr_b16 v[218:219], v206 offset:0x1e00
	s_waitcnt lgkmcnt(7)
	v_mfma_f32_32x32x16_bf16 v[32:47], v[72:75], v[220:223], v[32:47]
	ds_read_b64_tr_b16 v[220:221], v206 offset:0x2600
	ds_read_b64_tr_b16 v[222:223], v206 offset:0x2e00
	s_waitcnt lgkmcnt(7)
	v_mfma_f32_32x32x16_bf16 v[32:47], v[76:79], v[224:227], v[32:47]
	ds_read_b64_tr_b16 v[224:225], v206 offset:0x3600
	ds_read_b64_tr_b16 v[226:227], v206 offset:0x3e00
	ds_write_b128 v214, v[170:173] offset:32768
	s_waitcnt lgkmcnt(7)
	v_mfma_f32_32x32x16_bf16 v[48:63], v[64:67], v[184:187], v[48:63]
	v_exp_f32_e32 v215, v90
	s_waitcnt vmcnt(4)
	v_exp_f32_e32 v184, v80
	v_exp_f32_e32 v185, v81
	v_exp_f32_e32 v186, v82
	v_exp_f32_e32 v187, v83
	v_exp_f32_e32 v188, v84
	s_waitcnt lgkmcnt(5)
	v_mfma_f32_32x32x16_bf16 v[48:63], v[68:71], v[216:219], v[48:63]
	v_exp_f32_e32 v219, v94
	v_exp_f32_e32 v189, v85
	v_exp_f32_e32 v196, v86
	v_exp_f32_e32 v197, v87
	v_exp_f32_e32 v198, v88
	v_exp_f32_e32 v199, v89
	v_exp_f32_e32 v216, v91
	s_waitcnt lgkmcnt(3)
	v_mfma_f32_32x32x16_bf16 v[48:63], v[72:75], v[220:223], v[48:63]
	v_exp_f32_e32 v220, v95
	v_exp_f32_e32 v217, v92
	v_exp_f32_e32 v218, v93
	s_waitcnt lgkmcnt(0)
	s_barrier
; #define SBAR() __builtin_amdgcn_sched_barrier(0)
; __device__ __forceinline__ void finishSM(f32x16& p0, f32x16& p1, float alpha, float& l_reg, bf16x8& pa0, bf16x8& pa1, bf16x8& pa2, bf16x8& pa3) {
;   for (int r = 0; r < 16; ++r) p1[r] = __builtin_amdgcn_exp2f(p1[r]);
;   float ps = 0; for (int r = 0; r < 16; ++r) ps += p0[r]; for (int r = 0; r < 16; ++r) ps += p1[r];
;   { auto rr = __builtin_amdgcn_permlane32_swap(__float_as_uint(ps), __float_as_uint(ps), false, false);
;     ps = __uint_as_float(rr[0]) + __uint_as_float(rr[1]); }
;   l_reg = l_reg * alpha + ps;
;     ...
;   PK4(p0, 0, pa0); PK4(p0, 8, pa1); PK4(p1, 0, pa2); PK4(p1, 8, pa3);
;     ...
; }
; template <int BOFF> __device__ __forceinline__ void qkt_i(f32x16& p0, f32x16& p1, const int (&kb)[4], const bf16x8* qr) {
;   p0 = f32x16{}; p1 = f32x16{};
; #pragma unroll
;   for (int d0 = 0; d0 < 8; ++d0) { const int off = BOFF + (d0 >> 2) * 128;
;     const bf16x8 b0 = LDSV(kb[d0 & 3] + off), b1 = LDSV(kb[d0 & 3] + off + 8192);
;     p0 = __builtin_amdgcn_mfma_f32_32x32x16_bf16(b0, qr[d0], p0, 0, 0, 0);
;     p1 = __builtin_amdgcn_mfma_f32_32x32x16_bf16(b1, qr[d0], p1, 0, 0, 0); }
; }
; template <int D0, int BOFF> __device__ __forceinline__ void pv_one_i(f32x16& od, int vb, bf16x8 pa0, bf16x8 pa1, bf16x8 pa2, bf16x8 pa3) {
;   const s16x4 l0 = tr_read<BOFF + v_rd_off(D0, 0, 0)>(vb), h0 = tr_read<BOFF + v_rd_off(D0, 0, 1)>(vb), l1 = tr_read<BOFF + v_rd_off(D0, 1, 0)>(vb), h1 = tr_read<BOFF + v_rd_off(D0, 1, 1)>(vb);
;   const s16x4 l2 = tr_read<BOFF + v_rd_off(D0, 2, 0)>(vb), h2 = tr_read<BOFF + v_rd_off(D0, 2, 1)>(vb), l3 = tr_read<BOFF + v_rd_off(D0, 3, 0)>(vb), h3 = tr_read<BOFF + v_rd_off(D0, 3, 1)>(vb);
;   asm volatile("s_waitcnt lgkmcnt(0)" ::: "memory"); SBAR();
;     ...
;   od = __builtin_amdgcn_mfma_f32_32x32x16_bf16(pa0, PK(l0, h0), od, 0, 0, 0);
;   od = __builtin_amdgcn_mfma_f32_32x32x16_bf16(pa1, PK(l1, h1), od, 0, 0, 0);
;   od = __builtin_amdgcn_mfma_f32_32x32x16_bf16(pa2, PK(l2, h2), od, 0, 0, 0);
;   od = __builtin_amdgcn_mfma_f32_32x32x16_bf16(pa3, PK(l3, h3), od, 0, 0, 0);
;     ...
; }
; template <int BOFF> __device__ __forceinline__ void pv_i(f32x16* o, int vb, bf16x8 pa0, bf16x8 pa1, bf16x8 pa2, bf16x8 pa3) {
;   pv_one_i<0, BOFF>(o[0], vb, pa0, pa1, pa2, pa3); pv_one_i<1, BOFF>(o[1], vb, pa0, pa1, pa2, pa3); pv_one_i<2, BOFF>(o[2], vb, pa0, pa1, pa2, pa3); pv_one_i<3, BOFF>(o[3], vb, pa0, pa1, pa2, pa3);
; }
	v_mfma_f32_32x32x16_bf16 v[48:63], v[76:79], v[224:227], v[48:63]
	ds_read_b128 v[64:67], v207 offset:32768
	ds_read_b128 v[80:83], v207 offset:40960
	ds_read_b128 v[162:165], v208 offset:32768
	ds_read_b128 v[166:169], v208 offset:40960
	v_exp_f32_e32 v170, v104
	v_exp_f32_e32 v171, v105
	v_exp_f32_e32 v172, v106
	v_exp_f32_e32 v173, v107
	v_exp_f32_e32 v174, v108
	v_exp_f32_e32 v175, v109
	v_exp_f32_e32 v176, v110
	v_exp_f32_e32 v111, v111
	s_waitcnt lgkmcnt(3)
	v_mfma_f32_32x32x16_bf16 v[64:79], v[64:67], v[142:145], 0
	v_exp_f32_e32 v236, v96
	v_add_f32_e32 v96, 0, v184
	v_add_f32_e32 v96, v185, v96
	v_add_f32_e32 v96, v186, v96
	s_waitcnt lgkmcnt(2)
	v_mfma_f32_32x32x16_bf16 v[80:95], v[80:83], v[142:145], 0
	v_add_f32_e32 v96, v187, v96
	v_add_f32_e32 v96, v188, v96
	v_add_f32_e32 v96, v189, v96
	s_waitcnt lgkmcnt(1)
	v_mfma_f32_32x32x16_bf16 v[64:79], v[162:165], v[138:141], v[64:79]
	v_add_f32_e32 v96, v196, v96
	v_add_f32_e32 v96, v197, v96
	v_add_f32_e32 v96, v198, v96
	s_waitcnt lgkmcnt(0)
	v_mfma_f32_32x32x16_bf16 v[80:95], v[166:169], v[138:141], v[80:95]
	ds_read_b128 v[162:165], v209 offset:32768
	ds_read_b128 v[166:169], v209 offset:40960
	v_add_f32_e32 v96, v199, v96
	v_add_f32_e32 v96, v215, v96
	v_add_f32_e32 v96, v216, v96
	v_add_f32_e32 v96, v217, v96
	v_exp_f32_e32 v237, v97
	s_waitcnt lgkmcnt(1)
	v_mfma_f32_32x32x16_bf16 v[64:79], v[162:165], v[112:115], v[64:79]
	v_add_f32_e32 v96, v218, v96
	v_exp_f32_e32 v238, v98
	v_add_f32_e32 v96, v219, v96
	v_exp_f32_e32 v239, v99
	s_waitcnt lgkmcnt(0)
	v_mfma_f32_32x32x16_bf16 v[80:95], v[166:169], v[112:115], v[80:95]
	ds_read_b128 v[162:165], v210 offset:32768
	ds_read_b128 v[166:169], v210 offset:40960
	v_add_f32_e32 v96, v220, v96
	v_exp_f32_e32 v247, v100
	v_add_f32_e32 v96, v236, v96
	v_exp_f32_e32 v248, v101
	s_waitcnt lgkmcnt(1)
	v_mfma_f32_32x32x16_bf16 v[64:79], v[162:165], v[116:119], v[64:79]
	v_add_f32_e32 v96, v237, v96
	v_exp_f32_e32 v249, v102
	v_add_f32_e32 v96, v238, v96
	v_exp_f32_e32 v252, v103
	s_waitcnt lgkmcnt(0)
	v_mfma_f32_32x32x16_bf16 v[80:95], v[166:169], v[116:119], v[80:95]
	ds_read_b128 v[162:165], v190 offset:32768
	ds_read_b128 v[166:169], v190 offset:40960
	v_add_f32_e32 v96, v239, v96
	v_add_f32_e32 v96, v247, v96
	v_add_f32_e32 v96, v248, v96
	v_add_f32_e32 v96, v249, v96
	v_add_f32_e32 v96, v252, v96
	v_add_f32_e32 v96, v170, v96
	s_waitcnt lgkmcnt(1)
	v_mfma_f32_32x32x16_bf16 v[64:79], v[162:165], v[120:123], v[64:79]
	v_add_f32_e32 v96, v171, v96
	v_add_f32_e32 v96, v172, v96
	v_add_f32_e32 v96, v173, v96
	v_add_f32_e32 v96, v174, v96
	v_add_f32_e32 v96, v175, v96
	s_waitcnt lgkmcnt(0)
	v_mfma_f32_32x32x16_bf16 v[80:95], v[166:169], v[120:123], v[80:95]
	ds_read_b128 v[162:165], v191 offset:32768
	ds_read_b128 v[166:169], v191 offset:40960
	v_add_f32_e32 v96, v176, v96
	v_add_f32_e32 v181, v111, v96
	v_mov_b32_e32 v183, v181
	s_nop 1
	v_permlane32_swap_b32_e32 v181, v183
	v_pk_add_f32 v[96:97], v[180:181], v[182:183]
	s_waitcnt lgkmcnt(1)
	v_mfma_f32_32x32x16_bf16 v[64:79], v[162:165], v[124:127], v[64:79]
	s_nop 0
	v_add_f32_e32 v96, v128, v96
	v_add_f32_e32 v128, v96, v97
	v_cvt_pk_bf16_f32 v96, v184, v185
	v_cvt_pk_bf16_f32 v97, v186, v187
	s_waitcnt lgkmcnt(0)
	v_mfma_f32_32x32x16_bf16 v[80:95], v[166:169], v[124:127], v[80:95]
	ds_read_b128 v[162:165], v192 offset:32768
	ds_read_b128 v[166:169], v192 offset:40960
	v_cvt_pk_bf16_f32 v98, v188, v189
	v_cvt_pk_bf16_f32 v99, v196, v197
	v_cvt_pk_bf16_f32 v100, v198, v199
	v_cvt_pk_bf16_f32 v101, v215, v216
	v_cvt_pk_bf16_f32 v102, v217, v218
	v_cvt_pk_bf16_f32 v103, v219, v220
	s_waitcnt lgkmcnt(1)
	v_mfma_f32_32x32x16_bf16 v[64:79], v[162:165], v[130:133], v[64:79]
	v_cvt_pk_bf16_f32 v104, v236, v237
	v_cvt_pk_bf16_f32 v105, v238, v239
	v_cvt_pk_bf16_f32 v106, v247, v248
	v_cvt_pk_bf16_f32 v107, v249, v252
	v_cvt_pk_bf16_f32 v108, v170, v171
	s_waitcnt lgkmcnt(0)
	v_mfma_f32_32x32x16_bf16 v[80:95], v[166:169], v[130:133], v[80:95]
	ds_read_b128 v[162:165], v193 offset:32768
	ds_read_b128 v[166:169], v193 offset:40960
	ds_read_b64_tr_b16 v[180:181], v206 offset:0x4000
	ds_read_b64_tr_b16 v[182:183], v206 offset:0x4800
	ds_read_b64_tr_b16 v[184:185], v206 offset:0x5000
	ds_read_b64_tr_b16 v[186:187], v206 offset:0x5800
	ds_read_b64_tr_b16 v[216:217], v206 offset:0x6000
	ds_read_b64_tr_b16 v[218:219], v206 offset:0x6800
	ds_read_b64_tr_b16 v[220:221], v206 offset:0x7000
	ds_read_b64_tr_b16 v[222:223], v206 offset:0x7800
	v_cvt_pk_bf16_f32 v109, v172, v173
	v_cvt_pk_bf16_f32 v110, v174, v175
	v_cvt_pk_bf16_f32 v111, v176, v111
	s_nop 0
	v_permlane32_swap_b32_e32 v96, v98
	v_permlane32_swap_b32_e32 v97, v99
	s_waitcnt lgkmcnt(9)
	v_mfma_f32_32x32x16_bf16 v[64:79], v[162:165], v[134:137], v[64:79]
	v_permlane32_swap_b32_e32 v100, v102
	v_permlane32_swap_b32_e32 v101, v103
	v_permlane32_swap_b32_e32 v104, v106
	v_permlane32_swap_b32_e32 v105, v107
	v_permlane32_swap_b32_e32 v108, v110
	s_waitcnt lgkmcnt(8)
	v_mfma_f32_32x32x16_bf16 v[80:95], v[166:169], v[134:137], v[80:95]
	v_permlane32_swap_b32_e32 v109, v111
	v_add_co_u32_e32 v166, vcc, s52, v178
	s_nop 1
	v_addc_co_u32_e32 v167, vcc, -1, v179, vcc
	v_add_co_u32_e32 v170, vcc, s53, v178
	s_nop 1
	v_addc_co_u32_e32 v171, vcc, -1, v179, vcc
	global_load_dwordx4 v[162:165], v[166:167], off
	s_nop 0
	global_load_dwordx4 v[166:169], v[166:167], off offset:-512
	s_nop 0
	global_load_dwordx4 v[174:177], v[170:171], off
	s_nop 0
	global_load_dwordx4 v[170:173], v[170:171], off offset:-512
	s_waitcnt vmcnt(4)
	ds_write_b128 v211, v[146:149]
	s_nop 0
	s_waitcnt lgkmcnt(7)
; #define SBAR() __builtin_amdgcn_sched_barrier(0)
; __device__ __forceinline__ void partialSM_fixed(f32x16& p0) {
;   for (int r = 0; r < 16; ++r) p0[r] = __builtin_amdgcn_exp2f(p0[r]);
; }
; template <int D0, int BOFF> __device__ __forceinline__ void pv_one_i(f32x16& od, int vb, bf16x8 pa0, bf16x8 pa1, bf16x8 pa2, bf16x8 pa3) {
;   const s16x4 l0 = tr_read<BOFF + v_rd_off(D0, 0, 0)>(vb), h0 = tr_read<BOFF + v_rd_off(D0, 0, 1)>(vb), l1 = tr_read<BOFF + v_rd_off(D0, 1, 0)>(vb), h1 = tr_read<BOFF + v_rd_off(D0, 1, 1)>(vb);
;   const s16x4 l2 = tr_read<BOFF + v_rd_off(D0, 2, 0)>(vb), h2 = tr_read<BOFF + v_rd_off(D0, 2, 1)>(vb), l3 = tr_read<BOFF + v_rd_off(D0, 3, 0)>(vb), h3 = tr_read<BOFF + v_rd_off(D0, 3, 1)>(vb);
;   asm volatile("s_waitcnt lgkmcnt(0)" ::: "memory"); SBAR();
;     ...
;   od = __builtin_amdgcn_mfma_f32_32x32x16_bf16(pa0, PK(l0, h0), od, 0, 0, 0);
;   od = __builtin_amdgcn_mfma_f32_32x32x16_bf16(pa1, PK(l1, h1), od, 0, 0, 0);
;   od = __builtin_amdgcn_mfma_f32_32x32x16_bf16(pa2, PK(l2, h2), od, 0, 0, 0);
;   od = __builtin_amdgcn_mfma_f32_32x32x16_bf16(pa3, PK(l3, h3), od, 0, 0, 0);
;     ...
; }
; template <int BOFF> __device__ __forceinline__ void pv_i(f32x16* o, int vb, bf16x8 pa0, bf16x8 pa1, bf16x8 pa2, bf16x8 pa3) {
;   pv_one_i<0, BOFF>(o[0], vb, pa0, pa1, pa2, pa3); pv_one_i<1, BOFF>(o[1], vb, pa0, pa1, pa2, pa3); pv_one_i<2, BOFF>(o[2], vb, pa0, pa1, pa2, pa3); pv_one_i<3, BOFF>(o[3], vb, pa0, pa1, pa2, pa3);
; }
	v_mfma_f32_32x32x16_bf16 v[0:15], v[96:99], v[180:183], v[0:15]
	ds_read_b64_tr_b16 v[180:181], v206 offset:0x4200
	ds_read_b64_tr_b16 v[182:183], v206 offset:0x4a00
	s_waitcnt lgkmcnt(7)
	v_mfma_f32_32x32x16_bf16 v[0:15], v[100:103], v[184:187], v[0:15]
	ds_read_b64_tr_b16 v[184:185], v206 offset:0x5200
	ds_read_b64_tr_b16 v[186:187], v206 offset:0x5a00
	s_waitcnt lgkmcnt(7)
	v_mfma_f32_32x32x16_bf16 v[0:15], v[104:107], v[216:219], v[0:15]
	ds_read_b64_tr_b16 v[216:217], v206 offset:0x6200
	ds_read_b64_tr_b16 v[218:219], v206 offset:0x6a00
	s_waitcnt lgkmcnt(7)
	v_mfma_f32_32x32x16_bf16 v[0:15], v[108:111], v[220:223], v[0:15]
	ds_read_b64_tr_b16 v[220:221], v206 offset:0x7200
	ds_read_b64_tr_b16 v[222:223], v206 offset:0x7a00
	ds_write_b128 v212, v[158:161]
	s_waitcnt lgkmcnt(7)
	v_mfma_f32_32x32x16_bf16 v[16:31], v[96:99], v[180:183], v[16:31]
	ds_read_b64_tr_b16 v[180:181], v206 offset:0x4400
	ds_read_b64_tr_b16 v[182:183], v206 offset:0x4c00
	s_waitcnt lgkmcnt(7)
	v_mfma_f32_32x32x16_bf16 v[16:31], v[100:103], v[184:187], v[16:31]
	ds_read_b64_tr_b16 v[184:185], v206 offset:0x5400
	ds_read_b64_tr_b16 v[186:187], v206 offset:0x5c00
	s_waitcnt lgkmcnt(7)
	v_mfma_f32_32x32x16_bf16 v[16:31], v[104:107], v[216:219], v[16:31]
	ds_read_b64_tr_b16 v[216:217], v206 offset:0x6400
	ds_read_b64_tr_b16 v[218:219], v206 offset:0x6c00
	s_waitcnt lgkmcnt(7)
	v_mfma_f32_32x32x16_bf16 v[16:31], v[108:111], v[220:223], v[16:31]
	ds_read_b64_tr_b16 v[220:221], v206 offset:0x7400
	ds_read_b64_tr_b16 v[222:223], v206 offset:0x7c00
	ds_write_b128 v213, v[150:153]
	s_waitcnt lgkmcnt(7)
	v_mfma_f32_32x32x16_bf16 v[32:47], v[96:99], v[180:183], v[32:47]
	ds_read_b64_tr_b16 v[180:181], v206 offset:0x4600
	ds_read_b64_tr_b16 v[182:183], v206 offset:0x4e00
	s_waitcnt lgkmcnt(7)
	v_mfma_f32_32x32x16_bf16 v[32:47], v[100:103], v[184:187], v[32:47]
	ds_read_b64_tr_b16 v[184:185], v206 offset:0x5600
	ds_read_b64_tr_b16 v[186:187], v206 offset:0x5e00
	s_waitcnt lgkmcnt(7)
	v_mfma_f32_32x32x16_bf16 v[32:47], v[104:107], v[216:219], v[32:47]
	ds_read_b64_tr_b16 v[216:217], v206 offset:0x6600
	ds_read_b64_tr_b16 v[218:219], v206 offset:0x6e00
	s_waitcnt lgkmcnt(7)
	v_mfma_f32_32x32x16_bf16 v[32:47], v[108:111], v[220:223], v[32:47]
	ds_read_b64_tr_b16 v[220:221], v206 offset:0x7600
	ds_read_b64_tr_b16 v[222:223], v206 offset:0x7e00
	ds_write_b128 v214, v[154:157]
	s_waitcnt lgkmcnt(7)
	v_mfma_f32_32x32x16_bf16 v[48:63], v[96:99], v[180:183], v[48:63]
	s_waitcnt vmcnt(4)
	v_exp_f32_e32 v180, v64
	v_exp_f32_e32 v181, v65
	v_exp_f32_e32 v182, v66
	v_exp_f32_e32 v183, v67
	v_exp_f32_e32 v188, v72
	v_exp_f32_e32 v189, v73
	s_waitcnt lgkmcnt(5)
	v_mfma_f32_32x32x16_bf16 v[48:63], v[100:103], v[184:187], v[48:63]
	v_exp_f32_e32 v184, v68
	v_exp_f32_e32 v185, v69
	v_exp_f32_e32 v186, v70
	v_exp_f32_e32 v187, v71
	v_exp_f32_e32 v196, v74
	v_exp_f32_e32 v197, v75
	v_exp_f32_e32 v198, v76
	s_waitcnt lgkmcnt(3)
	v_mfma_f32_32x32x16_bf16 v[48:63], v[104:107], v[216:219], v[48:63]
	v_exp_f32_e32 v199, v77
	v_exp_f32_e32 v216, v78
	v_exp_f32_e32 v217, v79
	s_waitcnt lgkmcnt(0)
	s_barrier
	v_mfma_f32_32x32x16_bf16 v[48:63], v[108:111], v[220:223], v[48:63]
	ds_read_b128 v[64:67], v207
	ds_read_b128 v[68:71], v207 offset:8192
	ds_read_b128 v[146:149], v208
	ds_read_b128 v[150:153], v208 offset:8192
	v_exp_f32_e32 v154, v88
	v_exp_f32_e32 v155, v89
	v_exp_f32_e32 v156, v90
	v_exp_f32_e32 v157, v91
	v_exp_f32_e32 v158, v92
	v_exp_f32_e32 v159, v93
	v_exp_f32_e32 v160, v94
	v_exp_f32_e32 v95, v95
	s_waitcnt lgkmcnt(3)
	v_mfma_f32_32x32x16_bf16 v[96:111], v[64:67], v[142:145], 0
	v_exp_f32_e32 v236, v80
	v_add_f32_e32 v80, 0, v180
	v_add_f32_e32 v80, v181, v80
	v_add_f32_e32 v80, v182, v80
	s_waitcnt lgkmcnt(2)
	v_mfma_f32_32x32x16_bf16 v[64:79], v[68:71], v[142:145], 0
	v_add_f32_e32 v80, v183, v80
	v_add_f32_e32 v80, v184, v80
	v_add_f32_e32 v80, v185, v80
	s_waitcnt lgkmcnt(1)
	v_mfma_f32_32x32x16_bf16 v[96:111], v[146:149], v[138:141], v[96:111]
	v_add_f32_e32 v80, v186, v80
	v_add_f32_e32 v80, v187, v80
	v_add_f32_e32 v80, v188, v80
	s_waitcnt lgkmcnt(0)
	v_mfma_f32_32x32x16_bf16 v[64:79], v[150:153], v[138:141], v[64:79]
	ds_read_b128 v[146:149], v209
	ds_read_b128 v[150:153], v209 offset:8192
	v_add_f32_e32 v80, v189, v80
	v_add_f32_e32 v80, v196, v80
	v_add_f32_e32 v80, v197, v80
	v_add_f32_e32 v80, v198, v80
	v_exp_f32_e32 v237, v81
	s_waitcnt lgkmcnt(1)
	v_mfma_f32_32x32x16_bf16 v[96:111], v[146:149], v[112:115], v[96:111]
	v_add_f32_e32 v80, v199, v80
	v_exp_f32_e32 v238, v82
	v_add_f32_e32 v80, v216, v80
	v_exp_f32_e32 v239, v83
	s_waitcnt lgkmcnt(0)
	v_mfma_f32_32x32x16_bf16 v[64:79], v[150:153], v[112:115], v[64:79]
	ds_read_b128 v[146:149], v210
	ds_read_b128 v[150:153], v210 offset:8192
	v_add_f32_e32 v80, v217, v80
	v_exp_f32_e32 v247, v84
	v_add_f32_e32 v80, v236, v80
	v_exp_f32_e32 v248, v85
	s_waitcnt lgkmcnt(1)
	v_mfma_f32_32x32x16_bf16 v[96:111], v[146:149], v[116:119], v[96:111]
	v_add_f32_e32 v80, v237, v80
	v_exp_f32_e32 v249, v86
	v_add_f32_e32 v80, v238, v80
	v_exp_f32_e32 v252, v87
	s_waitcnt lgkmcnt(0)
	v_mfma_f32_32x32x16_bf16 v[64:79], v[150:153], v[116:119], v[64:79]
	ds_read_b128 v[146:149], v190 offset:0
	ds_read_b128 v[150:153], v190 offset:8192
	v_add_f32_e32 v80, v239, v80
	v_add_f32_e32 v80, v247, v80
	v_add_f32_e32 v80, v248, v80
	v_add_f32_e32 v80, v249, v80
	v_add_f32_e32 v80, v252, v80
	v_add_f32_e32 v80, v154, v80
	s_waitcnt lgkmcnt(1)
	v_mfma_f32_32x32x16_bf16 v[96:111], v[146:149], v[120:123], v[96:111]
	v_add_f32_e32 v80, v155, v80
	v_add_f32_e32 v80, v156, v80
	v_add_f32_e32 v80, v157, v80
	v_add_f32_e32 v80, v158, v80
	v_add_f32_e32 v80, v159, v80
	s_waitcnt lgkmcnt(0)
; #define SBAR() __builtin_amdgcn_sched_barrier(0)
; #define SLOAD(i, k0) do { sr_[i].vs0 = ld8(&Vh[(long)((k0) + sr) * LDK + sc]); sr_[i].vs1 = ld8(&Vh[(long)((k0) + 32 + sr) * LDK + sc]); \
;     sr_[i].ks0 = ld8(&Kh[(long)((k0) + sr) * LDK + sc]); sr_[i].ks1 = ld8(&Kh[(long)((k0) + 32 + sr) * LDK + sc]); } while (0)
; #define SWAIT() asm volatile("s_waitcnt vmcnt(4)" ::: "memory")
; #define NOP_() do { } while (0)
; template <int D0, int BOFF> __device__ __forceinline__ void pv_one_i(f32x16& od, int vb, bf16x8 pa0, bf16x8 pa1, bf16x8 pa2, bf16x8 pa3) {
;   const s16x4 l0 = tr_read<BOFF + v_rd_off(D0, 0, 0)>(vb), h0 = tr_read<BOFF + v_rd_off(D0, 0, 1)>(vb), l1 = tr_read<BOFF + v_rd_off(D0, 1, 0)>(vb), h1 = tr_read<BOFF + v_rd_off(D0, 1, 1)>(vb);
;   const s16x4 l2 = tr_read<BOFF + v_rd_off(D0, 2, 0)>(vb), h2 = tr_read<BOFF + v_rd_off(D0, 2, 1)>(vb), l3 = tr_read<BOFF + v_rd_off(D0, 3, 0)>(vb), h3 = tr_read<BOFF + v_rd_off(D0, 3, 1)>(vb);
;   asm volatile("s_waitcnt lgkmcnt(0)" ::: "memory"); SBAR();
;     ...
;   od = __builtin_amdgcn_mfma_f32_32x32x16_bf16(pa0, PK(l0, h0), od, 0, 0, 0);
;   od = __builtin_amdgcn_mfma_f32_32x32x16_bf16(pa1, PK(l1, h1), od, 0, 0, 0);
;   od = __builtin_amdgcn_mfma_f32_32x32x16_bf16(pa2, PK(l2, h2), od, 0, 0, 0);
;   od = __builtin_amdgcn_mfma_f32_32x32x16_bf16(pa3, PK(l3, h3), od, 0, 0, 0);
;     ...
; }
; template <int BOFF> __device__ __forceinline__ void pv_i(f32x16* o, int vb, bf16x8 pa0, bf16x8 pa1, bf16x8 pa2, bf16x8 pa3) {
;   pv_one_i<0, BOFF>(o[0], vb, pa0, pa1, pa2, pa3); pv_one_i<1, BOFF>(o[1], vb, pa0, pa1, pa2, pa3); pv_one_i<2, BOFF>(o[2], vb, pa0, pa1, pa2, pa3); pv_one_i<3, BOFF>(o[3], vb, pa0, pa1, pa2, pa3);
; }
; template <bool PARTIAL, bool FIXED> ...
;     ...
;   for (; j + 6 < NT; j += 6) {
;     HALF_B(1, 0, SLOAD(1, (j + 2) * KVBLK), do { SWAIT(); SWRITE_I(2, 0); } while (0));
;     HALF_A(2, 1, NOP_(), SLOAD(0, (j + 3) * KVBLK), do { SWAIT(); SWRITE_I(0, 1); } while (0));
;     HALF_B(0, 2, SLOAD(1, (j + 4) * KVBLK), do { SWAIT(); SWRITE_I(1, 0); } while (0));
;     HALF_A(1, 0, NOP_(), SLOAD(0, (j + 5) * KVBLK), do { SWAIT(); SWRITE_I(2, 1); } while (0));
;     HALF_B(2, 1, SLOAD(1, (j + 6) * KVBLK), do { SWAIT(); SWRITE_I(0, 0); } while (0));
;     HALF_A(0, 2, NOP_(), SLOAD(0, (j + 7) * KVBLK), do { SWAIT(); SWRITE_I(1, 1); } while (0));
	v_mfma_f32_32x32x16_bf16 v[64:79], v[150:153], v[120:123], v[64:79]
	ds_read_b128 v[146:149], v191 offset:0
	ds_read_b128 v[150:153], v191 offset:8192
	v_add_f32_e32 v80, v160, v80
	v_add_f32_e32 v80, v95, v80
	v_mov_b32_e32 v81, v80
	s_nop 1
	v_permlane32_swap_b32_e32 v80, v81
	v_add_f32_e32 v80, v80, v81
	s_waitcnt lgkmcnt(1)
	v_mfma_f32_32x32x16_bf16 v[96:111], v[146:149], v[124:127], v[96:111]
	v_add_f32_e32 v215, v128, v80
	v_cvt_pk_bf16_f32 v80, v180, v181
	v_cvt_pk_bf16_f32 v81, v182, v183
	v_cvt_pk_bf16_f32 v82, v184, v185
	v_cvt_pk_bf16_f32 v83, v186, v187
	s_waitcnt lgkmcnt(0)
	v_mfma_f32_32x32x16_bf16 v[64:79], v[150:153], v[124:127], v[64:79]
	ds_read_b128 v[146:149], v192 offset:0
	ds_read_b128 v[150:153], v192 offset:8192
	v_cvt_pk_bf16_f32 v84, v188, v189
	v_cvt_pk_bf16_f32 v85, v196, v197
	v_cvt_pk_bf16_f32 v86, v198, v199
	v_cvt_pk_bf16_f32 v87, v216, v217
	v_cvt_pk_bf16_f32 v88, v236, v237
	v_cvt_pk_bf16_f32 v89, v238, v239
	s_waitcnt lgkmcnt(1)
	v_mfma_f32_32x32x16_bf16 v[96:111], v[146:149], v[130:133], v[96:111]
	v_cvt_pk_bf16_f32 v90, v247, v248
	v_cvt_pk_bf16_f32 v91, v249, v252
	v_cvt_pk_bf16_f32 v92, v154, v155
	v_cvt_pk_bf16_f32 v93, v156, v157
	v_cvt_pk_bf16_f32 v94, v158, v159
	s_waitcnt lgkmcnt(0)
	v_mfma_f32_32x32x16_bf16 v[64:79], v[150:153], v[130:133], v[64:79]
	ds_read_b128 v[146:149], v193 offset:0
	ds_read_b128 v[150:153], v193 offset:8192
	ds_read_b64_tr_b16 v[180:181], v206 offset:0x8000
	ds_read_b64_tr_b16 v[182:183], v206 offset:0x8800
	ds_read_b64_tr_b16 v[184:185], v206 offset:0x9000
	ds_read_b64_tr_b16 v[186:187], v206 offset:0x9800
	ds_read_b64_tr_b16 v[216:217], v206 offset:0xa000
	ds_read_b64_tr_b16 v[218:219], v206 offset:0xa800
	ds_read_b64_tr_b16 v[220:221], v206 offset:0xb000
	ds_read_b64_tr_b16 v[222:223], v206 offset:0xb800
	v_cvt_pk_bf16_f32 v95, v160, v95
	s_nop 0
	v_permlane32_swap_b32_e32 v80, v82
	v_permlane32_swap_b32_e32 v81, v83
	v_permlane32_swap_b32_e32 v84, v86
	v_permlane32_swap_b32_e32 v85, v87
	s_waitcnt lgkmcnt(9)
	v_mfma_f32_32x32x16_bf16 v[96:111], v[146:149], v[134:137], v[96:111]
	v_permlane32_swap_b32_e32 v88, v90
	v_permlane32_swap_b32_e32 v89, v91
	v_permlane32_swap_b32_e32 v92, v94
	v_permlane32_swap_b32_e32 v93, v95
	s_waitcnt lgkmcnt(8)
	v_mfma_f32_32x32x16_bf16 v[64:79], v[150:153], v[134:137], v[64:79]
	v_add_co_u32_e32 v150, vcc, s58, v178
	s_nop 1
	v_addc_co_u32_e32 v151, vcc, -1, v179, vcc
	global_load_dwordx4 v[146:149], v[150:151], off
	global_load_dwordx4 v[154:157], v[150:151], off offset:-512
	s_nop 0
	global_load_dwordx4 v[150:153], v[178:179], off
	global_load_dwordx4 v[158:161], v[178:179], off offset:-512
	s_waitcnt vmcnt(4)
	ds_write_b128 v211, v[162:165] offset:16384
	s_nop 0
	s_waitcnt lgkmcnt(7)
	v_mfma_f32_32x32x16_bf16 v[0:15], v[80:83], v[180:183], v[0:15]
	ds_read_b64_tr_b16 v[180:181], v206 offset:0x8200
	ds_read_b64_tr_b16 v[182:183], v206 offset:0x8a00
	s_waitcnt lgkmcnt(7)
	v_mfma_f32_32x32x16_bf16 v[0:15], v[84:87], v[184:187], v[0:15]
	ds_read_b64_tr_b16 v[184:185], v206 offset:0x9200
	ds_read_b64_tr_b16 v[186:187], v206 offset:0x9a00
	s_waitcnt lgkmcnt(7)
	v_mfma_f32_32x32x16_bf16 v[0:15], v[88:91], v[216:219], v[0:15]
	ds_read_b64_tr_b16 v[216:217], v206 offset:0xa200
	ds_read_b64_tr_b16 v[218:219], v206 offset:0xaa00
	s_waitcnt lgkmcnt(7)
	v_mfma_f32_32x32x16_bf16 v[0:15], v[92:95], v[220:223], v[0:15]
	ds_read_b64_tr_b16 v[220:221], v206 offset:0xb200
	ds_read_b64_tr_b16 v[222:223], v206 offset:0xba00
	ds_write_b128 v212, v[174:177] offset:16384
	s_waitcnt lgkmcnt(7)
	v_mfma_f32_32x32x16_bf16 v[16:31], v[80:83], v[180:183], v[16:31]
	ds_read_b64_tr_b16 v[180:181], v206 offset:0x8400
	ds_read_b64_tr_b16 v[182:183], v206 offset:0x8c00
	s_waitcnt lgkmcnt(7)
	v_mfma_f32_32x32x16_bf16 v[16:31], v[84:87], v[184:187], v[16:31]
	ds_read_b64_tr_b16 v[184:185], v206 offset:0x9400
	ds_read_b64_tr_b16 v[186:187], v206 offset:0x9c00
	s_waitcnt lgkmcnt(7)
	v_mfma_f32_32x32x16_bf16 v[16:31], v[88:91], v[216:219], v[16:31]
	ds_read_b64_tr_b16 v[216:217], v206 offset:0xa400
	ds_read_b64_tr_b16 v[218:219], v206 offset:0xac00
	s_waitcnt lgkmcnt(7)
	v_mfma_f32_32x32x16_bf16 v[16:31], v[92:95], v[220:223], v[16:31]
	ds_read_b64_tr_b16 v[220:221], v206 offset:0xb400
	ds_read_b64_tr_b16 v[222:223], v206 offset:0xbc00
	ds_write_b128 v213, v[166:169] offset:16384
	s_waitcnt lgkmcnt(7)
	v_mfma_f32_32x32x16_bf16 v[32:47], v[80:83], v[180:183], v[32:47]
	ds_read_b64_tr_b16 v[180:181], v206 offset:0x8600
	ds_read_b64_tr_b16 v[182:183], v206 offset:0x8e00
	s_waitcnt lgkmcnt(7)
	v_mfma_f32_32x32x16_bf16 v[32:47], v[84:87], v[184:187], v[32:47]
	ds_read_b64_tr_b16 v[184:185], v206 offset:0x9600
	ds_read_b64_tr_b16 v[186:187], v206 offset:0x9e00
	s_waitcnt lgkmcnt(7)
	v_mfma_f32_32x32x16_bf16 v[32:47], v[88:91], v[216:219], v[32:47]
	ds_read_b64_tr_b16 v[216:217], v206 offset:0xa600
	ds_read_b64_tr_b16 v[218:219], v206 offset:0xae00
	s_waitcnt lgkmcnt(7)
	v_mfma_f32_32x32x16_bf16 v[32:47], v[92:95], v[220:223], v[32:47]
	ds_read_b64_tr_b16 v[220:221], v206 offset:0xb600
	ds_read_b64_tr_b16 v[222:223], v206 offset:0xbe00
	ds_write_b128 v214, v[170:173] offset:16384
	s_waitcnt lgkmcnt(7)
	v_mfma_f32_32x32x16_bf16 v[48:63], v[80:83], v[180:183], v[48:63]
	v_exp_f32_e32 v229, v96
	v_exp_f32_e32 v243, v97
	v_exp_f32_e32 v244, v98
	v_exp_f32_e32 v246, v99
	v_exp_f32_e32 v242, v100
	v_exp_f32_e32 v245, v101
	v_exp_f32_e32 v227, v102
	s_waitcnt lgkmcnt(5)
	v_mfma_f32_32x32x16_bf16 v[48:63], v[84:87], v[184:187], v[48:63]
	v_exp_f32_e32 v228, v103
	v_exp_f32_e32 v226, v105
	v_exp_f32_e32 v224, v106
	v_exp_f32_e32 v225, v107
	s_waitcnt vmcnt(4)
	s_add_i32 s28, s28, 6
	v_lshl_add_u64 v[178:179], v[178:179], 0, s[60:61]
	s_waitcnt lgkmcnt(3)
	v_mfma_f32_32x32x16_bf16 v[48:63], v[88:91], v[216:219], v[48:63]
	v_exp_f32_e32 v219, v110
	s_cmpk_lt_u32 s28, 0x75
	s_waitcnt lgkmcnt(1)
	v_mfma_f32_32x32x16_bf16 v[48:63], v[92:95], v[220:223], v[48:63]
	v_exp_f32_e32 v223, v104
	v_exp_f32_e32 v220, v108
	v_exp_f32_e32 v222, v109
	v_exp_f32_e32 v221, v111
	s_cbranch_scc1 .LBB0_352
; #define SWRITE_I(B, i) do { LDSV(wv0 + (B) * 16384) = sr_[i].vs0; LDSV(wv1 + (B) * 16384) = sr_[i].vs1; LDSV(wk0 + (B) * 16384) = sr_[i].ks0; LDSV(wk1 + (B) * 16384) = sr_[i].ks1; } while (0)
; #define NOP_() do { } while (0)
; template <int BOFF> __device__ __forceinline__ void qkt_i(f32x16& p0, f32x16& p1, const int (&kb)[4], const bf16x8* qr) {
;   p0 = f32x16{}; p1 = f32x16{};
; #pragma unroll
;   for (int d0 = 0; d0 < 8; ++d0) { const int off = BOFF + (d0 >> 2) * 128;
;     const bf16x8 b0 = LDSV(kb[d0 & 3] + off), b1 = LDSV(kb[d0 & 3] + off + 8192);
;     p0 = __builtin_amdgcn_mfma_f32_32x32x16_bf16(b0, qr[d0], p0, 0, 0, 0);
;     p1 = __builtin_amdgcn_mfma_f32_32x32x16_bf16(b1, qr[d0], p1, 0, 0, 0); }
; }
; template <bool PARTIAL, bool FIXED> ...
;     ...
;   if constexpr (!PARTIAL) { const int i1 = tid & 255;
;     warm0 = *(const unsigned*)(Qb_n + (long)(tid >> 1) * LDQ + (tid & 1) * 64);
;     warm1 = *(const unsigned*)((tid < 256 ? Kh_n : Vh_n) + (long)(i1 >> 1) * LDK + (i1 & 1) * 64); }
;   HALF_B(1, 0, NOP_(), SWRITE_I(2, 0));
	v_mov_b32_e32 v252, 0x7fc00000
	v_readlane_b32 s8, v255, 42
	v_readlane_b32 s9, v255, 43
	s_add_u32 s2, s8, s6
	s_addc_u32 s3, s9, s7
	s_lshl_b32 s4, s65, 1
	s_add_u32 s2, s2, s4
	s_addc_u32 s3, s3, 0
	v_ashrrev_i32_e32 v82, 1, v195
	v_mov_b64_e32 v[80:81], s[2:3]
	v_mad_i64_i32 v[80:81], s[2:3], v82, s17, v[80:81]
	v_lshlrev_b32_e32 v82, 7, v195
	v_and_b32_e32 v128, 0x80, v82
	v_lshl_add_u64 v[80:81], v[80:81], 0, v[128:129]
	s_add_u32 s4, s8, s64
	global_load_dword v216, v[80:81], off
	v_cmp_gt_i32_e32 vcc, s14, v195
	v_mov_b32_e32 v80, 0xa00
	v_mov_b32_e32 v81, 0x800
	s_addc_u32 s5, s9, s57
	v_cndmask_b32_e32 v80, v80, v81, vcc
	v_mov_b32_e32 v81, v129
	v_bfe_u32 v82, v195, 1, 7
	v_lshl_add_u64 v[80:81], s[4:5], 0, v[80:81]
	s_lshl_b32 s46, s56, 1
	v_mul_u32_u24_e32 v82, 0x600, v82
	v_lshl_add_u64 v[80:81], v[80:81], 0, s[46:47]
	v_lshlrev_b32_e32 v82, 1, v82
	v_mov_b32_e32 v83, v129
	v_lshl_add_u64 v[80:81], v[80:81], 0, v[82:83]
	v_lshl_add_u64 v[80:81], v[80:81], 0, v[128:129]
	global_load_dword v217, v[80:81], off
	v_and_b32_e32 v247, 0x3fffffc0, v195
	s_waitcnt lgkmcnt(0)
	s_barrier
	ds_read_b128 v[80:83], v207 offset:16384
	ds_read_b128 v[96:99], v207 offset:24576
	ds_read_b128 v[100:103], v208 offset:16384
	ds_read_b128 v[170:173], v208 offset:24576
	v_exp_f32_e32 v104, v68
	v_exp_f32_e32 v105, v69
	s_waitcnt lgkmcnt(3)
	v_mfma_f32_32x32x16_bf16 v[80:95], v[80:83], v[142:145], 0
	v_exp_f32_e32 v106, v70
	v_exp_f32_e32 v107, v71
	v_exp_f32_e32 v108, v72
	v_exp_f32_e32 v109, v73
	v_exp_f32_e32 v110, v74
	v_exp_f32_e32 v111, v75
	v_exp_f32_e32 v196, v76
	s_waitcnt lgkmcnt(1)
	v_mfma_f32_32x32x16_bf16 v[80:95], v[100:103], v[138:141], v[80:95]
	ds_read_b128 v[100:103], v209 offset:16384
	ds_read_b128 v[162:165], v209 offset:24576
	v_exp_f32_e32 v197, v77
	v_exp_f32_e32 v198, v78
	v_exp_f32_e32 v79, v79
	s_waitcnt lgkmcnt(1)
	v_mfma_f32_32x32x16_bf16 v[80:95], v[100:103], v[112:115], v[80:95]
	ds_read_b128 v[100:103], v210 offset:16384
	ds_read_b128 v[166:169], v210 offset:24576
	s_waitcnt lgkmcnt(1)
	v_mfma_f32_32x32x16_bf16 v[80:95], v[100:103], v[116:119], v[80:95]
	ds_read_b128 v[100:103], v190 offset:16384
	ds_read_b128 v[174:177], v190 offset:24576
	s_waitcnt lgkmcnt(1)
	v_mfma_f32_32x32x16_bf16 v[80:95], v[100:103], v[120:123], v[80:95]
	ds_read_b128 v[100:103], v191 offset:16384
	ds_read_b128 v[178:181], v191 offset:24576
	s_waitcnt lgkmcnt(1)
	v_mfma_f32_32x32x16_bf16 v[80:95], v[100:103], v[124:127], v[80:95]
	ds_read_b128 v[100:103], v192 offset:16384
	ds_read_b128 v[182:185], v192 offset:24576
	s_waitcnt lgkmcnt(1)
	v_mfma_f32_32x32x16_bf16 v[80:95], v[100:103], v[130:133], v[80:95]
	ds_read_b128 v[100:103], v193 offset:16384
	ds_read_b128 v[186:189], v193 offset:24576
	s_waitcnt lgkmcnt(1)
	v_mfma_f32_32x32x16_bf16 v[80:95], v[100:103], v[134:137], v[80:95]
	v_exp_f32_e32 v100, v64
	v_add_f32_e32 v64, 0, v229
	v_add_f32_e32 v64, v243, v64
	v_add_f32_e32 v64, v244, v64
	v_add_f32_e32 v64, v246, v64
	v_add_f32_e32 v64, v242, v64
	v_add_f32_e32 v64, v245, v64
	v_add_f32_e32 v64, v227, v64
	v_add_f32_e32 v64, v228, v64
	v_add_f32_e32 v64, v223, v64
	v_add_f32_e32 v64, v226, v64
	v_add_f32_e32 v64, v224, v64
	v_add_f32_e32 v64, v225, v64
	v_add_f32_e32 v64, v220, v64
	v_exp_f32_e32 v101, v65
	v_add_f32_e32 v64, v222, v64
	v_exp_f32_e32 v102, v66
	v_add_f32_e32 v64, v219, v64
	v_exp_f32_e32 v103, v67
	v_add_f32_e32 v64, v221, v64
	v_add_f32_e32 v64, v100, v64
	v_add_f32_e32 v64, v101, v64
	v_add_f32_e32 v64, v102, v64
	v_add_f32_e32 v64, v103, v64
	v_add_f32_e32 v64, v104, v64
	v_add_f32_e32 v64, v105, v64
	v_add_f32_e32 v64, v106, v64
	v_add_f32_e32 v64, v107, v64
	v_add_f32_e32 v64, v108, v64
	v_add_f32_e32 v64, v109, v64
	v_add_f32_e32 v64, v110, v64
	v_add_f32_e32 v64, v111, v64
	v_add_f32_e32 v64, v196, v64
	v_add_f32_e32 v64, v197, v64
	v_add_f32_e32 v64, v198, v64
	v_add_f32_e32 v128, v79, v64
	v_mov_b32_e32 v218, v128
	s_nop 1
	v_permlane32_swap_b32_e32 v128, v218
	v_cvt_pk_bf16_f32 v64, v229, v243
	v_cvt_pk_bf16_f32 v65, v244, v246
	v_cvt_pk_bf16_f32 v66, v242, v245
	v_cvt_pk_bf16_f32 v67, v227, v228
	v_cvt_pk_bf16_f32 v68, v223, v226
	v_cvt_pk_bf16_f32 v69, v224, v225
	v_cvt_pk_bf16_f32 v70, v220, v222
	v_cvt_pk_bf16_f32 v71, v219, v221
	v_cvt_pk_bf16_f32 v72, v100, v101
	v_cvt_pk_bf16_f32 v73, v102, v103
	v_cvt_pk_bf16_f32 v74, v104, v105
	v_cvt_pk_bf16_f32 v75, v106, v107
	v_cvt_pk_bf16_f32 v76, v108, v109
	v_cvt_pk_bf16_f32 v77, v110, v111
	v_cvt_pk_bf16_f32 v78, v196, v197
	v_cvt_pk_bf16_f32 v79, v198, v79
	s_nop 0
	v_permlane32_swap_b32_e32 v64, v66
	v_permlane32_swap_b32_e32 v65, v67
	v_permlane32_swap_b32_e32 v68, v70
	v_permlane32_swap_b32_e32 v69, v71
	v_permlane32_swap_b32_e32 v72, v74
	v_permlane32_swap_b32_e32 v73, v75
	v_permlane32_swap_b32_e32 v76, v78
	v_permlane32_swap_b32_e32 v77, v79
	ds_read_b64_tr_b16 v[100:101], v206 offset:0
	ds_read_b64_tr_b16 v[102:103], v206 offset:0x800
	ds_read_b64_tr_b16 v[104:105], v206 offset:0x1000
	ds_read_b64_tr_b16 v[106:107], v206 offset:0x1800
	ds_read_b64_tr_b16 v[108:109], v206 offset:0x2000
	ds_read_b64_tr_b16 v[110:111], v206 offset:0x2800
	ds_read_b64_tr_b16 v[220:221], v206 offset:0x3000
	ds_read_b64_tr_b16 v[222:223], v206 offset:0x3800
	s_waitcnt lgkmcnt(0)
	s_nop 0
	v_mfma_f32_32x32x16_bf16 v[0:15], v[64:67], v[100:103], v[0:15]
	ds_read_b64_tr_b16 v[100:101], v206 offset:0x200
	ds_read_b64_tr_b16 v[102:103], v206 offset:0xa00
	v_mfma_f32_32x32x16_bf16 v[0:15], v[68:71], v[104:107], v[0:15]
	ds_read_b64_tr_b16 v[104:105], v206 offset:0x1200
	ds_read_b64_tr_b16 v[106:107], v206 offset:0x1a00
	v_mfma_f32_32x32x16_bf16 v[0:15], v[72:75], v[108:111], v[0:15]
	ds_read_b64_tr_b16 v[108:109], v206 offset:0x2200
	ds_read_b64_tr_b16 v[110:111], v206 offset:0x2a00
	v_mfma_f32_32x32x16_bf16 v[0:15], v[76:79], v[220:223], v[0:15]
	ds_read_b64_tr_b16 v[220:221], v206 offset:0x3200
	ds_read_b64_tr_b16 v[222:223], v206 offset:0x3a00
	s_waitcnt lgkmcnt(0)
; #define SBAR() __builtin_amdgcn_sched_barrier(0)
; #define SWRITE_I(B, i) do { LDSV(wv0 + (B) * 16384) = sr_[i].vs0; LDSV(wv1 + (B) * 16384) = sr_[i].vs1; LDSV(wk0 + (B) * 16384) = sr_[i].ks0; LDSV(wk1 + (B) * 16384) = sr_[i].ks1; } while (0)
; #define NOP_() do { } while (0)
; template <int D0, int BOFF> __device__ __forceinline__ void pv_one_i(f32x16& od, int vb, bf16x8 pa0, bf16x8 pa1, bf16x8 pa2, bf16x8 pa3) {
;   const s16x4 l0 = tr_read<BOFF + v_rd_off(D0, 0, 0)>(vb), h0 = tr_read<BOFF + v_rd_off(D0, 0, 1)>(vb), l1 = tr_read<BOFF + v_rd_off(D0, 1, 0)>(vb), h1 = tr_read<BOFF + v_rd_off(D0, 1, 1)>(vb);
;   const s16x4 l2 = tr_read<BOFF + v_rd_off(D0, 2, 0)>(vb), h2 = tr_read<BOFF + v_rd_off(D0, 2, 1)>(vb), l3 = tr_read<BOFF + v_rd_off(D0, 3, 0)>(vb), h3 = tr_read<BOFF + v_rd_off(D0, 3, 1)>(vb);
;   asm volatile("s_waitcnt lgkmcnt(0)" ::: "memory"); SBAR();
;     ...
;   od = __builtin_amdgcn_mfma_f32_32x32x16_bf16(pa0, PK(l0, h0), od, 0, 0, 0);
;   od = __builtin_amdgcn_mfma_f32_32x32x16_bf16(pa1, PK(l1, h1), od, 0, 0, 0);
;   od = __builtin_amdgcn_mfma_f32_32x32x16_bf16(pa2, PK(l2, h2), od, 0, 0, 0);
;   od = __builtin_amdgcn_mfma_f32_32x32x16_bf16(pa3, PK(l3, h3), od, 0, 0, 0);
;     ...
; }
; template <int BOFF> __device__ __forceinline__ void pv_i(f32x16* o, int vb, bf16x8 pa0, bf16x8 pa1, bf16x8 pa2, bf16x8 pa3) {
;   pv_one_i<0, BOFF>(o[0], vb, pa0, pa1, pa2, pa3); pv_one_i<1, BOFF>(o[1], vb, pa0, pa1, pa2, pa3); pv_one_i<2, BOFF>(o[2], vb, pa0, pa1, pa2, pa3); pv_one_i<3, BOFF>(o[3], vb, pa0, pa1, pa2, pa3);
; }
; template <bool PARTIAL, bool FIXED> ...
;     ...
;   HALF_B(1, 0, NOP_(), SWRITE_I(2, 0));
;   HALF_A(2, 1, do { if (mask_last) { asm volatile("; masked tail tile" ::: "memory"); const float NEG = -INFINITY; \
;       _Pragma("unroll") for (int r = 8; r < 16; ++r) pA0[r] = NEG; _Pragma("unroll") for (int r = 0; r < 16; ++r) pA1[r] = NEG; } } while (0), NOP_(), NOP_());
	v_mfma_f32_32x32x16_bf16 v[16:31], v[64:67], v[100:103], v[16:31]
	ds_read_b64_tr_b16 v[100:101], v206 offset:0x400
	ds_read_b64_tr_b16 v[102:103], v206 offset:0xc00
	v_mfma_f32_32x32x16_bf16 v[16:31], v[68:71], v[104:107], v[16:31]
	ds_read_b64_tr_b16 v[104:105], v206 offset:0x1400
	ds_read_b64_tr_b16 v[106:107], v206 offset:0x1c00
	v_mfma_f32_32x32x16_bf16 v[16:31], v[72:75], v[108:111], v[16:31]
	ds_read_b64_tr_b16 v[108:109], v206 offset:0x2400
	ds_read_b64_tr_b16 v[110:111], v206 offset:0x2c00
	v_mfma_f32_32x32x16_bf16 v[16:31], v[76:79], v[220:223], v[16:31]
	ds_read_b64_tr_b16 v[220:221], v206 offset:0x3400
	ds_read_b64_tr_b16 v[222:223], v206 offset:0x3c00
	s_waitcnt lgkmcnt(0)
	v_mfma_f32_32x32x16_bf16 v[32:47], v[64:67], v[100:103], v[32:47]
	ds_read_b64_tr_b16 v[100:101], v206 offset:0x600
	ds_read_b64_tr_b16 v[102:103], v206 offset:0xe00
	v_mfma_f32_32x32x16_bf16 v[32:47], v[68:71], v[104:107], v[32:47]
	ds_read_b64_tr_b16 v[104:105], v206 offset:0x1600
	ds_read_b64_tr_b16 v[106:107], v206 offset:0x1e00
	v_mfma_f32_32x32x16_bf16 v[32:47], v[72:75], v[108:111], v[32:47]
	ds_read_b64_tr_b16 v[108:109], v206 offset:0x2600
	ds_read_b64_tr_b16 v[110:111], v206 offset:0x2e00
	v_mfma_f32_32x32x16_bf16 v[32:47], v[76:79], v[220:223], v[32:47]
	ds_read_b64_tr_b16 v[220:221], v206 offset:0x3600
	ds_read_b64_tr_b16 v[222:223], v206 offset:0x3e00
	s_waitcnt lgkmcnt(0)
	v_mfma_f32_32x32x16_bf16 v[48:63], v[64:67], v[100:103], v[48:63]
	s_waitcnt vmcnt(5)
	ds_write_b128 v211, v[146:149] offset:32768
	s_waitcnt vmcnt(3)
	ds_write_b128 v212, v[150:153] offset:32768
	ds_write_b128 v213, v[154:157] offset:32768
	s_waitcnt vmcnt(2)
	ds_write_b128 v214, v[158:161] offset:32768
	s_waitcnt lgkmcnt(0)
	s_barrier
	v_mfma_f32_32x32x16_bf16 v[48:63], v[68:71], v[104:107], v[48:63]
	v_mfma_f32_32x32x16_bf16 v[48:63], v[72:75], v[108:111], v[48:63]
	v_mfma_f32_32x32x16_bf16 v[48:63], v[76:79], v[220:223], v[48:63]
	ds_read_b128 v[64:67], v207 offset:32768
	ds_read_b128 v[100:103], v208 offset:32768
	s_add_i32 s2, 0, 0x18000
	s_waitcnt lgkmcnt(1)
	v_mfma_f32_32x32x16_bf16 v[64:79], v[64:67], v[142:145], 0
	s_waitcnt lgkmcnt(0)
	v_mfma_f32_32x32x16_bf16 v[64:79], v[100:103], v[138:141], v[64:79]
	ds_read_b128 v[100:103], v209 offset:32768
	s_waitcnt lgkmcnt(0)
	v_mfma_f32_32x32x16_bf16 v[64:79], v[100:103], v[112:115], v[64:79]
	ds_read_b128 v[100:103], v210 offset:32768
	s_waitcnt lgkmcnt(0)
	v_mfma_f32_32x32x16_bf16 v[64:79], v[100:103], v[116:119], v[64:79]
	ds_read_b128 v[100:103], v190 offset:32768
	s_waitcnt lgkmcnt(0)
	v_mfma_f32_32x32x16_bf16 v[64:79], v[100:103], v[120:123], v[64:79]
	ds_read_b128 v[100:103], v191 offset:32768
	s_waitcnt lgkmcnt(0)
	v_mfma_f32_32x32x16_bf16 v[64:79], v[100:103], v[124:127], v[64:79]
	ds_read_b128 v[100:103], v192 offset:32768
	s_waitcnt lgkmcnt(0)
	v_mfma_f32_32x32x16_bf16 v[64:79], v[100:103], v[130:133], v[64:79]
	ds_read_b128 v[100:103], v193 offset:32768
	s_waitcnt lgkmcnt(0)
	v_and_b32_e32 v190, 63, v195
	v_lshlrev_b32_e32 v191, 4, v195
	v_and_b32_e32 v192, 31, v195
	v_bfe_u32 v193, v195, 5, 1
	v_mfma_f32_32x32x16_bf16 v[64:79], v[100:103], v[134:137], v[64:79]
	v_mfma_f32_32x32x16_bf16 v[96:111], v[96:99], v[142:145], 0
	s_nop 10
	v_exp_f32_e32 v72, v80
	v_exp_f32_e32 v80, v81
	v_exp_f32_e32 v73, v82
	v_exp_f32_e32 v81, v83
	v_exp_f32_e32 v74, v84
	v_add_f32_e32 v84, 0, v72
	v_exp_f32_e32 v82, v85
	v_mfma_f32_32x32x16_bf16 v[96:111], v[170:173], v[138:141], v[96:111]
	v_add_f32_e32 v84, v80, v84
	v_exp_f32_e32 v75, v86
	v_add_f32_e32 v84, v73, v84
	v_exp_f32_e32 v83, v87
	v_add_f32_e32 v84, v81, v84
	v_exp_f32_e32 v76, v88
	v_add_f32_e32 v84, v74, v84
	v_mfma_f32_32x32x16_bf16 v[96:111], v[162:165], v[112:115], v[96:111]
	v_exp_f32_e32 v85, v89
	v_add_f32_e32 v84, v82, v84
	v_exp_f32_e32 v77, v90
	v_add_f32_e32 v84, v75, v84
	v_exp_f32_e32 v87, v91
	v_add_f32_e32 v84, v83, v84
	v_exp_f32_e32 v78, v92
	v_mfma_f32_32x32x16_bf16 v[96:111], v[166:169], v[116:119], v[96:111]
	v_add_f32_e32 v84, v76, v84
	v_exp_f32_e32 v89, v93
	v_add_f32_e32 v84, v85, v84
	v_exp_f32_e32 v79, v94
	v_add_f32_e32 v84, v77, v84
	v_exp_f32_e32 v90, v95
	v_add_f32_e32 v84, v87, v84
	v_mfma_f32_32x32x16_bf16 v[96:111], v[174:177], v[120:123], v[96:111]
	v_add_f32_e32 v84, v78, v84
	v_add_f32_e32 v84, v89, v84
	v_add_f32_e32 v84, v79, v84
	v_add_f32_e32 v84, v90, v84
	v_lshl_add_u32 v88, v247, 2, s2
	v_cvt_pk_bf16_f32 v72, v72, v80
	v_cvt_pk_bf16_f32 v73, v73, v81
	v_mfma_f32_32x32x16_bf16 v[96:111], v[178:181], v[124:127], v[96:111]
	v_cvt_pk_bf16_f32 v74, v74, v82
	v_cvt_pk_bf16_f32 v75, v75, v83
	v_cvt_pk_bf16_f32 v76, v76, v85
	v_cvt_pk_bf16_f32 v77, v77, v87
	v_cvt_pk_bf16_f32 v78, v78, v89
	v_cvt_pk_bf16_f32 v79, v79, v90
	s_nop 0
	v_permlane32_swap_b32_e32 v72, v74
	v_mfma_f32_32x32x16_bf16 v[96:111], v[182:185], v[130:133], v[96:111]
	v_permlane32_swap_b32_e32 v73, v75
	v_permlane32_swap_b32_e32 v76, v78
	v_permlane32_swap_b32_e32 v77, v79
	v_mfma_f32_32x32x16_bf16 v[96:111], v[186:189], v[134:137], v[96:111]
	s_nop 11
	v_exp_f32_e32 v91, v96
	v_exp_f32_e32 v92, v97
	v_exp_f32_e32 v93, v98
	v_exp_f32_e32 v94, v99
	v_exp_f32_e32 v95, v100
	v_add_f32_e32 v84, v84, v91
	v_exp_f32_e32 v96, v101
	v_add_f32_e32 v84, v92, v84
	v_exp_f32_e32 v97, v102
	v_add_f32_e32 v84, v93, v84
	v_exp_f32_e32 v98, v103
	v_add_f32_e32 v84, v94, v84
	v_exp_f32_e32 v99, v104
	v_add_f32_e32 v84, v95, v84
	v_exp_f32_e32 v100, v105
	v_add_f32_e32 v84, v96, v84
	v_exp_f32_e32 v101, v106
	v_add_f32_e32 v84, v97, v84
	v_exp_f32_e32 v102, v107
	v_add_f32_e32 v84, v98, v84
	v_exp_f32_e32 v103, v108
	v_add_f32_e32 v84, v99, v84
	v_exp_f32_e32 v104, v109
	v_add_f32_e32 v84, v100, v84
	v_exp_f32_e32 v105, v110
	v_add_f32_e32 v84, v101, v84
	v_exp_f32_e32 v106, v111
	v_add_f32_e32 v84, v102, v84
	v_add_f32_e32 v84, v103, v84
	v_add_f32_e32 v84, v104, v84
	v_add_f32_e32 v84, v105, v84
	v_add_f32_e32 v84, v106, v84
	v_mov_b32_e32 v86, v84
	s_nop 1
	v_permlane32_swap_b32_e32 v84, v86
	v_cvt_pk_bf16_f32 v80, v91, v92
	v_cvt_pk_bf16_f32 v81, v93, v94
	v_cvt_pk_bf16_f32 v82, v95, v96
	v_cvt_pk_bf16_f32 v83, v97, v98
	v_cvt_pk_bf16_f32 v90, v99, v100
	v_cvt_pk_bf16_f32 v91, v101, v102
	v_cvt_pk_bf16_f32 v92, v103, v104
	v_cvt_pk_bf16_f32 v93, v105, v106
	s_nop 0
	v_permlane32_swap_b32_e32 v80, v82
	v_permlane32_swap_b32_e32 v81, v83
	v_permlane32_swap_b32_e32 v90, v92
	v_permlane32_swap_b32_e32 v91, v93
	ds_read_b64_tr_b16 v[94:95], v206 offset:0x4000
	ds_read_b64_tr_b16 v[96:97], v206 offset:0x4800
	ds_read_b64_tr_b16 v[98:99], v206 offset:0x5000
	ds_read_b64_tr_b16 v[100:101], v206 offset:0x5800
	ds_read_b64_tr_b16 v[102:103], v206 offset:0x6000
	ds_read_b64_tr_b16 v[104:105], v206 offset:0x6800
	ds_read_b64_tr_b16 v[106:107], v206 offset:0x7000
	ds_read_b64_tr_b16 v[108:109], v206 offset:0x7800
	s_waitcnt lgkmcnt(0)
; #define SBAR() __builtin_amdgcn_sched_barrier(0)
; #define NOP_() do { } while (0)
; template <bool PARTIAL, bool FIXED> ...
;     ...
;   HALF_A(2, 1, do { if (mask_last) { asm volatile("; masked tail tile" ::: "memory"); const float NEG = -INFINITY; \
;       _Pragma("unroll") for (int r = 8; r < 16; ++r) pA0[r] = NEG; _Pragma("unroll") for (int r = 0; r < 16; ++r) pA1[r] = NEG; } } while (0), NOP_(), NOP_());
;     ...
;   SBAR(); finishSM(pA0, pA1, alA, l_reg, pa0, pa1, pa2, pa3); SBAR();
;   pv_i<2 * 16384>(o, vbi, pa0, pa1, pa2, pa3);
;     ...
;   if (hi == 0) li_l[r32] = l_reg; asm volatile("s_waitcnt lgkmcnt(0)" ::: "memory");
	s_nop 0
	v_mfma_f32_32x32x16_bf16 v[0:15], v[72:75], v[94:97], v[0:15]
	ds_read_b64_tr_b16 v[94:95], v206 offset:0x4200
	ds_read_b64_tr_b16 v[96:97], v206 offset:0x4a00
	v_mfma_f32_32x32x16_bf16 v[0:15], v[76:79], v[98:101], v[0:15]
	ds_read_b64_tr_b16 v[98:99], v206 offset:0x5200
	ds_read_b64_tr_b16 v[100:101], v206 offset:0x5a00
	v_mfma_f32_32x32x16_bf16 v[0:15], v[80:83], v[102:105], v[0:15]
	ds_read_b64_tr_b16 v[102:103], v206 offset:0x6200
	ds_read_b64_tr_b16 v[104:105], v206 offset:0x6a00
	v_mfma_f32_32x32x16_bf16 v[0:15], v[90:93], v[106:109], v[0:15]
	ds_read_b64_tr_b16 v[106:107], v206 offset:0x7200
	ds_read_b64_tr_b16 v[108:109], v206 offset:0x7a00
	s_waitcnt lgkmcnt(0)
	v_mfma_f32_32x32x16_bf16 v[16:31], v[72:75], v[94:97], v[16:31]
	ds_read_b64_tr_b16 v[94:95], v206 offset:0x4400
	ds_read_b64_tr_b16 v[96:97], v206 offset:0x4c00
	v_mfma_f32_32x32x16_bf16 v[16:31], v[76:79], v[98:101], v[16:31]
	ds_read_b64_tr_b16 v[98:99], v206 offset:0x5400
	ds_read_b64_tr_b16 v[100:101], v206 offset:0x5c00
	v_mfma_f32_32x32x16_bf16 v[16:31], v[80:83], v[102:105], v[16:31]
	ds_read_b64_tr_b16 v[102:103], v206 offset:0x6400
	ds_read_b64_tr_b16 v[104:105], v206 offset:0x6c00
	v_mfma_f32_32x32x16_bf16 v[16:31], v[90:93], v[106:109], v[16:31]
	ds_read_b64_tr_b16 v[106:107], v206 offset:0x7400
	ds_read_b64_tr_b16 v[108:109], v206 offset:0x7c00
	s_waitcnt lgkmcnt(0)
	v_mfma_f32_32x32x16_bf16 v[32:47], v[72:75], v[94:97], v[32:47]
	ds_read_b64_tr_b16 v[94:95], v206 offset:0x4600
	ds_read_b64_tr_b16 v[96:97], v206 offset:0x4e00
	v_mfma_f32_32x32x16_bf16 v[32:47], v[76:79], v[98:101], v[32:47]
	ds_read_b64_tr_b16 v[98:99], v206 offset:0x5600
	ds_read_b64_tr_b16 v[100:101], v206 offset:0x5e00
	v_mfma_f32_32x32x16_bf16 v[32:47], v[80:83], v[102:105], v[32:47]
	ds_read_b64_tr_b16 v[102:103], v206 offset:0x6600
	ds_read_b64_tr_b16 v[104:105], v206 offset:0x6e00
	v_mfma_f32_32x32x16_bf16 v[32:47], v[90:93], v[106:109], v[32:47]
	ds_read_b64_tr_b16 v[106:107], v206 offset:0x7600
	ds_read_b64_tr_b16 v[108:109], v206 offset:0x7e00
	s_waitcnt lgkmcnt(0)
	v_mfma_f32_32x32x16_bf16 v[48:63], v[72:75], v[94:97], v[48:63]
	v_exp_f32_e32 v64, v64
	v_exp_f32_e32 v65, v65
	v_exp_f32_e32 v66, v66
	v_exp_f32_e32 v67, v67
	v_exp_f32_e32 v68, v68
	v_exp_f32_e32 v69, v69
	v_exp_f32_e32 v70, v70
	v_mfma_f32_32x32x16_bf16 v[48:63], v[76:79], v[98:101], v[48:63]
	v_exp_f32_e32 v71, v71
	v_mfma_f32_32x32x16_bf16 v[48:63], v[80:83], v[102:105], v[48:63]
	v_mfma_f32_32x32x16_bf16 v[48:63], v[90:93], v[106:109], v[48:63]
	v_add_f32_e32 v72, 0, v64
	v_add_f32_e32 v72, v65, v72
	v_add_f32_e32 v72, v66, v72
	v_add_f32_e32 v72, v67, v72
	v_add_f32_e32 v72, v68, v72
	v_add_f32_e32 v72, v69, v72
	v_add_f32_e32 v72, v70, v72
	v_add_f32_e32 v72, v71, v72
	v_add_f32_e32 v85, 0, v72
	v_mov_b32_e32 v87, v85
	s_nop 1
	v_permlane32_swap_b32_e32 v85, v87
	v_cvt_pk_bf16_f32 v64, v64, v65
	v_cvt_pk_bf16_f32 v65, v66, v67
	v_cvt_pk_bf16_f32 v66, v68, v69
	v_cvt_pk_bf16_f32 v67, v70, v71
	v_cvt_pk_bf16_f32 v68, v129, v129
	v_cvt_pk_bf16_f32 v69, v129, v129
	v_cvt_pk_bf16_f32 v70, v129, v129
	v_cvt_pk_bf16_f32 v71, v129, v129
	v_cvt_pk_bf16_f32 v72, v129, v129
	v_cvt_pk_bf16_f32 v73, v129, v129
	v_cvt_pk_bf16_f32 v74, v129, v129
	v_cvt_pk_bf16_f32 v75, v129, v129
	v_cvt_pk_bf16_f32 v76, v129, v129
	v_cvt_pk_bf16_f32 v77, v129, v129
	v_cvt_pk_bf16_f32 v78, v129, v129
	v_cvt_pk_bf16_f32 v79, v129, v129
	s_nop 0
	v_permlane32_swap_b32_e32 v64, v66
	v_permlane32_swap_b32_e32 v65, v67
	v_permlane32_swap_b32_e32 v68, v70
	v_permlane32_swap_b32_e32 v69, v71
	v_permlane32_swap_b32_e32 v72, v74
	v_permlane32_swap_b32_e32 v73, v75
	v_permlane32_swap_b32_e32 v76, v78
	v_permlane32_swap_b32_e32 v77, v79
	ds_read_b64_tr_b16 v[80:81], v206 offset:0x8000
	ds_read_b64_tr_b16 v[82:83], v206 offset:0x8800
	ds_read_b64_tr_b16 v[90:91], v206 offset:0x9000
	ds_read_b64_tr_b16 v[92:93], v206 offset:0x9800
	ds_read_b64_tr_b16 v[94:95], v206 offset:0xa000
	ds_read_b64_tr_b16 v[96:97], v206 offset:0xa800
	ds_read_b64_tr_b16 v[98:99], v206 offset:0xb000
	ds_read_b64_tr_b16 v[100:101], v206 offset:0xb800
	s_waitcnt lgkmcnt(0)
	s_nop 0
	v_mfma_f32_32x32x16_bf16 v[0:15], v[64:67], v[80:83], v[0:15]
	ds_read_b64_tr_b16 v[80:81], v206 offset:0x8200
	ds_read_b64_tr_b16 v[82:83], v206 offset:0x8a00
	v_mfma_f32_32x32x16_bf16 v[0:15], v[68:71], v[90:93], v[0:15]
	ds_read_b64_tr_b16 v[90:91], v206 offset:0x9200
	ds_read_b64_tr_b16 v[92:93], v206 offset:0x9a00
	v_mfma_f32_32x32x16_bf16 v[0:15], v[72:75], v[94:97], v[0:15]
	ds_read_b64_tr_b16 v[94:95], v206 offset:0xa200
	ds_read_b64_tr_b16 v[96:97], v206 offset:0xaa00
	v_mfma_f32_32x32x16_bf16 v[0:15], v[76:79], v[98:101], v[0:15]
	ds_read_b64_tr_b16 v[98:99], v206 offset:0xb200
	ds_read_b64_tr_b16 v[100:101], v206 offset:0xba00
	s_waitcnt lgkmcnt(0)
	v_mfma_f32_32x32x16_bf16 v[16:31], v[64:67], v[80:83], v[16:31]
	ds_read_b64_tr_b16 v[80:81], v206 offset:0x8400
	ds_read_b64_tr_b16 v[82:83], v206 offset:0x8c00
	v_mfma_f32_32x32x16_bf16 v[16:31], v[68:71], v[90:93], v[16:31]
	ds_read_b64_tr_b16 v[90:91], v206 offset:0x9400
	ds_read_b64_tr_b16 v[92:93], v206 offset:0x9c00
	v_mfma_f32_32x32x16_bf16 v[16:31], v[72:75], v[94:97], v[16:31]
	ds_read_b64_tr_b16 v[94:95], v206 offset:0xa400
	ds_read_b64_tr_b16 v[96:97], v206 offset:0xac00
	v_mfma_f32_32x32x16_bf16 v[16:31], v[76:79], v[98:101], v[16:31]
	ds_read_b64_tr_b16 v[98:99], v206 offset:0xb400
	ds_read_b64_tr_b16 v[100:101], v206 offset:0xbc00
	s_waitcnt lgkmcnt(0)
	v_mfma_f32_32x32x16_bf16 v[32:47], v[64:67], v[80:83], v[32:47]
	ds_read_b64_tr_b16 v[80:81], v206 offset:0x8600
	ds_read_b64_tr_b16 v[82:83], v206 offset:0x8e00
	v_mfma_f32_32x32x16_bf16 v[32:47], v[68:71], v[90:93], v[32:47]
	ds_read_b64_tr_b16 v[90:91], v206 offset:0x9600
	ds_read_b64_tr_b16 v[92:93], v206 offset:0x9e00
	v_mfma_f32_32x32x16_bf16 v[32:47], v[72:75], v[94:97], v[32:47]
	ds_read_b64_tr_b16 v[94:95], v206 offset:0xa600
	ds_read_b64_tr_b16 v[96:97], v206 offset:0xae00
	v_mfma_f32_32x32x16_bf16 v[32:47], v[76:79], v[98:101], v[32:47]
	ds_read_b64_tr_b16 v[98:99], v206 offset:0xb600
	ds_read_b64_tr_b16 v[100:101], v206 offset:0xbe00
	s_waitcnt lgkmcnt(0)
	v_mfma_f32_32x32x16_bf16 v[48:63], v[64:67], v[80:83], v[48:63]
	v_cmp_gt_u32_e32 vcc, 32, v190
	v_mfma_f32_32x32x16_bf16 v[48:63], v[68:71], v[90:93], v[48:63]
	v_mfma_f32_32x32x16_bf16 v[48:63], v[72:75], v[94:97], v[48:63]
	v_mfma_f32_32x32x16_bf16 v[48:63], v[76:79], v[98:101], v[48:63]
	s_and_saveexec_b64 s[28:29], vcc
	s_cbranch_execz .LBB0_309
	v_add_f32_e32 v64, v128, v218
	v_add_f32_e32 v66, v215, v64
	v_pk_add_f32 v[64:65], v[84:85], v[86:87]
	v_lshl_add_u32 v67, v192, 2, v88
	v_add_f32_e32 v64, v66, v64
	v_add_f32_e32 v64, v64, v65
	ds_write_b32 v67, v64
	s_branch .LBB0_309

; #define PG8_STAGE(bufoff, gbase, voff) do { _Pragma("unroll") for (int _i = 0; _i < 2; ++_i) \
;         __builtin_amdgcn_global_load_lds((const unsigned*)((const char*)(gbase) + (voff)[_i]), (PG8_LAS unsigned*)(lds + (bufoff) + ldsw + _i * 8192), 16, 0, 0); } while (0)
; #define PG8_LDA(dst, b, h) do { _Pragma("unroll") for (int m = 0; m < 4; ++m) _Pragma("unroll") for (int k = 0; k < 2; ++k) dst[m][k] = *(const PG8_LAS bf16x8*)(lds + PG8_SA(b, h) + aoff + m * 2048 + k * 1024); } while (0)
; #define PG8_LDB(dst, b, h) do { _Pragma("unroll") for (int n = 0; n < 2; ++n) _Pragma("unroll") for (int k = 0; k < 2; ++k) dst[n][k] = *(const PG8_LAS bf16x8*)(lds + PG8_SB(b, h) + boff + n * 2048 + k * 1024); } while (0)
; #define PG8_MMA(ai, bj, At, Bt) do { __builtin_amdgcn_s_setprio(1); _Pragma("unroll") for (int m = 0; m < 4; ++m) _Pragma("unroll") for (int n = 0; n < 2; ++n) _Pragma("unroll") for (int k = 0; k < 2; ++k) \
;         acc[ai][bj][m][n] = __builtin_amdgcn_mfma_f32_16x16x32_bf16(Bt[n][k], At[m][k], acc[ai][bj][m][n], 0, 0, 0); __builtin_amdgcn_s_setprio(0); } while (0)
; #define PG8_WAIT_V(n) asm volatile("s_waitcnt vmcnt(" #n ")" ::: "memory")
; #define PG8_WAIT_L(n) asm volatile("s_waitcnt lgkmcnt(" #n ")" ::: "memory")
; #define PG8_BAR __builtin_amdgcn_s_barrier()
; #define PG8_SCHED __builtin_amdgcn_sched_barrier(0)
; template <class Epi, class Sched, bool ALIGN_EPI = false, bool SP2 = false>
; __device__ __forceinline__ void gemm_phase(PG8_LAS unsigned char* lds, const Gemm g, const Sched& S, const Epi& E) {
;     ...
;             PG8_LDB(B0, 0, 0); PG8_LDB(B1, 0, 1); PG8_SCHED; PG8_LDA(At, 0, 0); PG8_STAGE(PG8_SA(1, 1), a1 + hstep, voffA);
;             PG8_WAIT_V(8); PG8_WAIT_L(0); PG8_BAR; PG8_MMA(0, 0, At, B0); PG8_MMA(0, 1, At, B1); PG8_BAR; PG8_SCHED;
;             PG8_LDA(At, 0, 1); PG8_STAGE(PG8_SB(0, 0), b2, voffB); PG8_STAGE(PG8_SB(0, 1), b2 + hstep, voffB); PG8_STAGE(PG8_SA(0, 0), a2, voffA);
;             PG8_WAIT_V(8); PG8_WAIT_L(0); PG8_BAR; if (full) { PG8_MMA(1, 0, At, B0); PG8_MMA(1, 1, At, B1); } PG8_BAR; PG8_SCHED;
.LBB0_500:
	s_add_u32 s2, s80, 0xfffc0080
	s_addc_u32 s3, s81, -1
	s_add_i32 s4, 0, 0x10000
	s_cmp_eq_u32 s90, 12
	s_cselect_b32 s31, s1, s3
	s_cselect_b32 s30, s35, s2
	v_add_u32_e32 v128, s4, v226
	s_cselect_b32 s29, s51, s89
	s_cselect_b32 s28, s87, s88
	s_add_i32 s5, 0, 0x14000
	ds_read_b128 v[146:149], v128
	ds_read_b128 v[150:153], v128 offset:1024
	ds_read_b128 v[154:157], v128 offset:2048
	ds_read_b128 v[158:161], v128 offset:3072
	v_add_u32_e32 v128, s5, v226
	ds_read_b128 v[130:133], v128
	ds_read_b128 v[134:137], v128 offset:1024
	ds_read_b128 v[138:141], v128 offset:2048
	ds_read_b128 v[142:145], v128 offset:3072
	v_lshl_add_u64 v[196:197], s[80:81], 0, v[214:215]
	s_add_i32 m0, s65, 0xc000
	s_waitcnt lgkmcnt(7)
	ds_read_b128 v[162:165], v228
	ds_read_b128 v[166:169], v228 offset:1024
	ds_read_b128 v[170:173], v228 offset:2048
	ds_read_b128 v[174:177], v228 offset:3072
	ds_read_b128 v[178:181], v228 offset:4096
	ds_read_b128 v[182:185], v228 offset:5120
	ds_read_b128 v[186:189], v228 offset:6144
	ds_read_b128 v[190:193], v228 offset:7168
	global_load_lds_dwordx4 v[196:197], off
	v_lshl_add_u64 v[196:197], s[80:81], 0, v[216:217]
	s_add_i32 m0, s65, 0xe000
	s_nop 0
	global_load_lds_dwordx4 v[196:197], off
	s_waitcnt vmcnt(8)
	s_waitcnt lgkmcnt(0)
	s_barrier
	s_setprio 1
	s_waitcnt lgkmcnt(0)
	v_mfma_f32_16x16x32_bf16 v[124:127], v[146:149], v[162:165], v[124:127]
	v_mfma_f32_16x16x32_bf16 v[120:123], v[154:157], v[162:165], v[120:123]
	v_mfma_f32_16x16x32_bf16 v[108:111], v[146:149], v[170:173], v[108:111]
	v_mfma_f32_16x16x32_bf16 v[104:107], v[154:157], v[170:173], v[104:107]
	v_mfma_f32_16x16x32_bf16 v[92:95], v[146:149], v[178:181], v[92:95]
	v_mfma_f32_16x16x32_bf16 v[88:91], v[154:157], v[178:181], v[88:91]
	v_mfma_f32_16x16x32_bf16 v[76:79], v[146:149], v[186:189], v[76:79]
	v_mfma_f32_16x16x32_bf16 v[72:75], v[154:157], v[186:189], v[72:75]
	v_mfma_f32_16x16x32_bf16 v[124:127], v[150:153], v[166:169], v[124:127]
	v_mfma_f32_16x16x32_bf16 v[120:123], v[158:161], v[166:169], v[120:123]
	v_mfma_f32_16x16x32_bf16 v[108:111], v[150:153], v[174:177], v[108:111]
	v_mfma_f32_16x16x32_bf16 v[104:107], v[158:161], v[174:177], v[104:107]
	v_mfma_f32_16x16x32_bf16 v[92:95], v[150:153], v[182:185], v[92:95]
	v_mfma_f32_16x16x32_bf16 v[88:91], v[158:161], v[182:185], v[88:91]
	v_mfma_f32_16x16x32_bf16 v[76:79], v[150:153], v[190:193], v[76:79]
	v_mfma_f32_16x16x32_bf16 v[72:75], v[158:161], v[190:193], v[72:75]
	v_mfma_f32_16x16x32_bf16 v[116:119], v[130:133], v[162:165], v[116:119]
	v_mfma_f32_16x16x32_bf16 v[112:115], v[138:141], v[162:165], v[112:115]
	v_mfma_f32_16x16x32_bf16 v[100:103], v[130:133], v[170:173], v[100:103]
	v_mfma_f32_16x16x32_bf16 v[96:99], v[138:141], v[170:173], v[96:99]
	v_mfma_f32_16x16x32_bf16 v[84:87], v[130:133], v[178:181], v[84:87]
	v_mfma_f32_16x16x32_bf16 v[80:83], v[138:141], v[178:181], v[80:83]
	v_mfma_f32_16x16x32_bf16 v[68:71], v[130:133], v[186:189], v[68:71]
	v_mfma_f32_16x16x32_bf16 v[64:67], v[138:141], v[186:189], v[64:67]
	v_mfma_f32_16x16x32_bf16 v[116:119], v[134:137], v[166:169], v[116:119]
	v_mfma_f32_16x16x32_bf16 v[112:115], v[142:145], v[166:169], v[112:115]
	v_mfma_f32_16x16x32_bf16 v[100:103], v[134:137], v[174:177], v[100:103]
	v_mfma_f32_16x16x32_bf16 v[96:99], v[142:145], v[174:177], v[96:99]
	v_mfma_f32_16x16x32_bf16 v[84:87], v[134:137], v[182:185], v[84:87]
	v_mfma_f32_16x16x32_bf16 v[80:83], v[142:145], v[182:185], v[80:83]
	v_mfma_f32_16x16x32_bf16 v[68:71], v[134:137], v[190:193], v[68:71]
	v_mfma_f32_16x16x32_bf16 v[64:67], v[142:145], v[190:193], v[64:67]
	s_setprio 0
	s_barrier
	s_add_i32 s2, s4, s64
	v_lshl_add_u64 v[218:219], s[28:29], 0, v[208:209]
	s_mov_b32 m0, s2
	ds_read_b128 v[186:189], v228 offset:16384
	ds_read_b128 v[190:193], v228 offset:17408
	ds_read_b128 v[178:181], v228 offset:18432
	ds_read_b128 v[182:185], v228 offset:19456
	ds_read_b128 v[170:173], v228 offset:20480
	ds_read_b128 v[174:177], v228 offset:21504
	ds_read_b128 v[162:165], v228 offset:22528
	ds_read_b128 v[166:169], v228 offset:23552
	global_load_lds_dwordx4 v[218:219], off
	s_add_i32 m0, s2, 0x2000
	s_add_u32 s2, s28, 0x40000
	v_lshl_add_u64 v[220:221], s[28:29], 0, v[212:213]
	s_addc_u32 s3, s29, 0
	s_add_i32 s4, s5, s64
	global_load_lds_dwordx4 v[220:221], off
	v_lshl_add_u64 v[196:197], s[2:3], 0, v[208:209]
	s_mov_b32 m0, s4
	v_lshl_add_u64 v[222:223], s[30:31], 0, v[206:207]
	global_load_lds_dwordx4 v[196:197], off
	v_lshl_add_u64 v[196:197], s[2:3], 0, v[212:213]
	s_add_i32 m0, s4, 0x2000
	v_lshl_add_u64 v[224:225], s[30:31], 0, v[210:211]
	global_load_lds_dwordx4 v[196:197], off
	s_mov_b32 m0, s65
	v_cndmask_b32_e64 v128, 0, 1, s[78:79]
	global_load_lds_dwordx4 v[222:223], off
	s_mov_b32 m0, s70
	v_cmp_ne_u32_e64 s[38:39], 1, v128
	global_load_lds_dwordx4 v[224:225], off
	s_waitcnt vmcnt(8)
	s_waitcnt lgkmcnt(0)
	s_andn2_b64 vcc, exec, s[78:79]
	s_barrier
	s_cbranch_vccnz .LBB0_502
; #define PG8_MMA(ai, bj, At, Bt) do { __builtin_amdgcn_s_setprio(1); _Pragma("unroll") for (int m = 0; m < 4; ++m) _Pragma("unroll") for (int n = 0; n < 2; ++n) _Pragma("unroll") for (int k = 0; k < 2; ++k) \
;         acc[ai][bj][m][n] = __builtin_amdgcn_mfma_f32_16x16x32_bf16(Bt[n][k], At[m][k], acc[ai][bj][m][n], 0, 0, 0); __builtin_amdgcn_s_setprio(0); } while (0)
; #define PG8_WAIT_V(n) asm volatile("s_waitcnt vmcnt(" #n ")" ::: "memory")
; #define PG8_WAIT_L(n) asm volatile("s_waitcnt lgkmcnt(" #n ")" ::: "memory")
; #define PG8_BAR __builtin_amdgcn_s_barrier()
; #define PG8_SCHED __builtin_amdgcn_sched_barrier(0)
; template <class Epi, class Sched, bool ALIGN_EPI = false, bool SP2 = false>
; __device__ __forceinline__ void gemm_phase(PG8_LAS unsigned char* lds, const Gemm g, const Sched& S, const Epi& E) {
;     ...
;             PG8_WAIT_V(8); PG8_WAIT_L(0); PG8_BAR; if (full) { PG8_MMA(1, 0, At, B0); PG8_MMA(1, 1, At, B1); } PG8_BAR; PG8_SCHED;
	s_setprio 1
	s_waitcnt lgkmcnt(0)
	v_mfma_f32_16x16x32_bf16 v[60:63], v[146:149], v[186:189], v[60:63]
	v_mfma_f32_16x16x32_bf16 v[56:59], v[154:157], v[186:189], v[56:59]
	v_mfma_f32_16x16x32_bf16 v[44:47], v[146:149], v[178:181], v[44:47]
	v_mfma_f32_16x16x32_bf16 v[40:43], v[154:157], v[178:181], v[40:43]
	v_mfma_f32_16x16x32_bf16 v[28:31], v[146:149], v[170:173], v[28:31]
	v_mfma_f32_16x16x32_bf16 v[24:27], v[154:157], v[170:173], v[24:27]
	v_mfma_f32_16x16x32_bf16 v[12:15], v[146:149], v[162:165], v[12:15]
	v_mfma_f32_16x16x32_bf16 v[8:11], v[154:157], v[162:165], v[8:11]
	v_mfma_f32_16x16x32_bf16 v[60:63], v[150:153], v[190:193], v[60:63]
	v_mfma_f32_16x16x32_bf16 v[56:59], v[158:161], v[190:193], v[56:59]
	v_mfma_f32_16x16x32_bf16 v[44:47], v[150:153], v[182:185], v[44:47]
	v_mfma_f32_16x16x32_bf16 v[40:43], v[158:161], v[182:185], v[40:43]
	v_mfma_f32_16x16x32_bf16 v[28:31], v[150:153], v[174:177], v[28:31]
	v_mfma_f32_16x16x32_bf16 v[24:27], v[158:161], v[174:177], v[24:27]
	v_mfma_f32_16x16x32_bf16 v[12:15], v[150:153], v[166:169], v[12:15]
	v_mfma_f32_16x16x32_bf16 v[8:11], v[158:161], v[166:169], v[8:11]
	v_mfma_f32_16x16x32_bf16 v[52:55], v[130:133], v[186:189], v[52:55]
	v_mfma_f32_16x16x32_bf16 v[48:51], v[138:141], v[186:189], v[48:51]
	v_mfma_f32_16x16x32_bf16 v[36:39], v[130:133], v[178:181], v[36:39]
	v_mfma_f32_16x16x32_bf16 v[32:35], v[138:141], v[178:181], v[32:35]
	v_mfma_f32_16x16x32_bf16 v[20:23], v[130:133], v[170:173], v[20:23]
	v_mfma_f32_16x16x32_bf16 v[16:19], v[138:141], v[170:173], v[16:19]
	v_mfma_f32_16x16x32_bf16 v[4:7], v[130:133], v[162:165], v[4:7]
	v_mfma_f32_16x16x32_bf16 v[0:3], v[138:141], v[162:165], v[0:3]
	v_mfma_f32_16x16x32_bf16 v[52:55], v[134:137], v[190:193], v[52:55]
	v_mfma_f32_16x16x32_bf16 v[48:51], v[142:145], v[190:193], v[48:51]
	v_mfma_f32_16x16x32_bf16 v[36:39], v[134:137], v[182:185], v[36:39]
	v_mfma_f32_16x16x32_bf16 v[32:35], v[142:145], v[182:185], v[32:35]
	v_mfma_f32_16x16x32_bf16 v[20:23], v[134:137], v[174:177], v[20:23]
	v_mfma_f32_16x16x32_bf16 v[16:19], v[142:145], v[174:177], v[16:19]
	v_mfma_f32_16x16x32_bf16 v[4:7], v[134:137], v[166:169], v[4:7]
	v_mfma_f32_16x16x32_bf16 v[0:3], v[142:145], v[166:169], v[0:3]
	s_setprio 0
; #define PG8_STAGE(bufoff, gbase, voff) do { _Pragma("unroll") for (int _i = 0; _i < 2; ++_i) \
;         __builtin_amdgcn_global_load_lds((const unsigned*)((const char*)(gbase) + (voff)[_i]), (PG8_LAS unsigned*)(lds + (bufoff) + ldsw + _i * 8192), 16, 0, 0); } while (0)
; #define PG8_LDA(dst, b, h) do { _Pragma("unroll") for (int m = 0; m < 4; ++m) _Pragma("unroll") for (int k = 0; k < 2; ++k) dst[m][k] = *(const PG8_LAS bf16x8*)(lds + PG8_SA(b, h) + aoff + m * 2048 + k * 1024); } while (0)
; #define PG8_LDB(dst, b, h) do { _Pragma("unroll") for (int n = 0; n < 2; ++n) _Pragma("unroll") for (int k = 0; k < 2; ++k) dst[n][k] = *(const PG8_LAS bf16x8*)(lds + PG8_SB(b, h) + boff + n * 2048 + k * 1024); } while (0)
; #define PG8_MMA(ai, bj, At, Bt) do { __builtin_amdgcn_s_setprio(1); _Pragma("unroll") for (int m = 0; m < 4; ++m) _Pragma("unroll") for (int n = 0; n < 2; ++n) _Pragma("unroll") for (int k = 0; k < 2; ++k) \
;         acc[ai][bj][m][n] = __builtin_amdgcn_mfma_f32_16x16x32_bf16(Bt[n][k], At[m][k], acc[ai][bj][m][n], 0, 0, 0); __builtin_amdgcn_s_setprio(0); } while (0)
; #define PG8_WAIT_V(n) asm volatile("s_waitcnt vmcnt(" #n ")" ::: "memory")
; #define PG8_WAIT_L(n) asm volatile("s_waitcnt lgkmcnt(" #n ")" ::: "memory")
; #define PG8_BAR __builtin_amdgcn_s_barrier()
; #define PG8_SCHED __builtin_amdgcn_sched_barrier(0)
; template <class Epi, class Sched, bool ALIGN_EPI = false, bool SP2 = false>
; __device__ __forceinline__ void gemm_phase(PG8_LAS unsigned char* lds, const Gemm g, const Sched& S, const Epi& E) {
;     ...
;             PG8_LDB(B0, 1, 0); PG8_LDB(B1, 1, 1); PG8_SCHED; PG8_LDA(At, 1, 0); PG8_STAGE(PG8_SA(0, 1), a2 + hstep, voffA);
;             PG8_WAIT_V(8); PG8_WAIT_L(0); PG8_BAR; PG8_MMA(0, 0, At, B0); PG8_MMA(0, 1, At, B1); PG8_BAR; PG8_SCHED;
;             PG8_LDA(At, 1, 1); PG8_STAGE(PG8_SB(1, 0), b3, voffB); PG8_STAGE(PG8_SB(1, 1), b3 + hstep, voffB); PG8_STAGE(PG8_SA(1, 0), a3, voffA);
;             PG8_WAIT_V(8); PG8_WAIT_L(0); PG8_BAR; if (full) { PG8_MMA(1, 0, At, B0); PG8_MMA(1, 1, At, B1); } PG8_BAR; PG8_SCHED;
.LBB0_502:
	s_barrier
	s_add_i32 s4, 0, 0x18000
	v_add_u32_e32 v128, s4, v226
	s_add_i32 s5, 0, 0x1c000
	ds_read_b128 v[146:149], v128
	ds_read_b128 v[150:153], v128 offset:1024
	ds_read_b128 v[154:157], v128 offset:2048
	ds_read_b128 v[158:161], v128 offset:3072
	v_add_u32_e32 v128, s5, v226
	ds_read_b128 v[130:133], v128
	ds_read_b128 v[134:137], v128 offset:1024
	ds_read_b128 v[138:141], v128 offset:2048
	ds_read_b128 v[142:145], v128 offset:3072
	s_add_u32 s2, s30, 0x40000
	s_addc_u32 s3, s31, 0
	s_mov_b32 m0, s71
	v_lshl_add_u64 v[196:197], s[2:3], 0, v[206:207]
	s_waitcnt lgkmcnt(7)
	ds_read_b128 v[162:165], v228 offset:32768
	ds_read_b128 v[166:169], v228 offset:33792
	ds_read_b128 v[170:173], v228 offset:34816
	ds_read_b128 v[174:177], v228 offset:35840
	ds_read_b128 v[178:181], v228 offset:36864
	ds_read_b128 v[182:185], v228 offset:37888
	ds_read_b128 v[186:189], v228 offset:38912
	ds_read_b128 v[190:193], v228 offset:39936
	global_load_lds_dwordx4 v[196:197], off
	v_lshl_add_u64 v[196:197], s[2:3], 0, v[210:211]
	s_mov_b32 m0, s77
	s_nop 0
	global_load_lds_dwordx4 v[196:197], off
	s_waitcnt vmcnt(8)
	s_waitcnt lgkmcnt(0)
	s_barrier
	s_setprio 1
	s_waitcnt lgkmcnt(0)
	v_mfma_f32_16x16x32_bf16 v[124:127], v[146:149], v[162:165], v[124:127]
	v_mfma_f32_16x16x32_bf16 v[120:123], v[154:157], v[162:165], v[120:123]
	v_mfma_f32_16x16x32_bf16 v[108:111], v[146:149], v[170:173], v[108:111]
	v_mfma_f32_16x16x32_bf16 v[104:107], v[154:157], v[170:173], v[104:107]
	v_mfma_f32_16x16x32_bf16 v[92:95], v[146:149], v[178:181], v[92:95]
	v_mfma_f32_16x16x32_bf16 v[88:91], v[154:157], v[178:181], v[88:91]
	v_mfma_f32_16x16x32_bf16 v[76:79], v[146:149], v[186:189], v[76:79]
	v_mfma_f32_16x16x32_bf16 v[72:75], v[154:157], v[186:189], v[72:75]
	v_mfma_f32_16x16x32_bf16 v[124:127], v[150:153], v[166:169], v[124:127]
	v_mfma_f32_16x16x32_bf16 v[120:123], v[158:161], v[166:169], v[120:123]
	v_mfma_f32_16x16x32_bf16 v[108:111], v[150:153], v[174:177], v[108:111]
	v_mfma_f32_16x16x32_bf16 v[104:107], v[158:161], v[174:177], v[104:107]
	v_mfma_f32_16x16x32_bf16 v[92:95], v[150:153], v[182:185], v[92:95]
	v_mfma_f32_16x16x32_bf16 v[88:91], v[158:161], v[182:185], v[88:91]
	v_mfma_f32_16x16x32_bf16 v[76:79], v[150:153], v[190:193], v[76:79]
	v_mfma_f32_16x16x32_bf16 v[72:75], v[158:161], v[190:193], v[72:75]
	v_mfma_f32_16x16x32_bf16 v[116:119], v[130:133], v[162:165], v[116:119]
	v_mfma_f32_16x16x32_bf16 v[112:115], v[138:141], v[162:165], v[112:115]
	v_mfma_f32_16x16x32_bf16 v[100:103], v[130:133], v[170:173], v[100:103]
	v_mfma_f32_16x16x32_bf16 v[96:99], v[138:141], v[170:173], v[96:99]
	v_mfma_f32_16x16x32_bf16 v[84:87], v[130:133], v[178:181], v[84:87]
	v_mfma_f32_16x16x32_bf16 v[80:83], v[138:141], v[178:181], v[80:83]
	v_mfma_f32_16x16x32_bf16 v[68:71], v[130:133], v[186:189], v[68:71]
	v_mfma_f32_16x16x32_bf16 v[64:67], v[138:141], v[186:189], v[64:67]
	v_mfma_f32_16x16x32_bf16 v[116:119], v[134:137], v[166:169], v[116:119]
	v_mfma_f32_16x16x32_bf16 v[112:115], v[142:145], v[166:169], v[112:115]
	v_mfma_f32_16x16x32_bf16 v[100:103], v[134:137], v[174:177], v[100:103]
	v_mfma_f32_16x16x32_bf16 v[96:99], v[142:145], v[174:177], v[96:99]
	v_mfma_f32_16x16x32_bf16 v[84:87], v[134:137], v[182:185], v[84:87]
	v_mfma_f32_16x16x32_bf16 v[80:83], v[142:145], v[182:185], v[80:83]
	v_mfma_f32_16x16x32_bf16 v[68:71], v[134:137], v[190:193], v[68:71]
	v_mfma_f32_16x16x32_bf16 v[64:67], v[142:145], v[190:193], v[64:67]
	s_setprio 0
	s_barrier
	s_add_i32 s2, s4, s64
	v_lshl_add_u64 v[196:197], v[218:219], 0, s[26:27]
	s_mov_b32 m0, s2
	ds_read_b128 v[186:189], v228 offset:49152
	ds_read_b128 v[190:193], v228 offset:50176
	ds_read_b128 v[178:181], v228 offset:51200
	ds_read_b128 v[182:185], v228 offset:52224
	ds_read_b128 v[170:173], v228 offset:53248
	ds_read_b128 v[174:177], v228 offset:54272
	ds_read_b128 v[162:165], v228 offset:55296
	ds_read_b128 v[166:169], v228 offset:56320
	global_load_lds_dwordx4 v[196:197], off
	s_add_i32 m0, s2, 0x2000
	s_add_u32 s2, s28, 0x40080
	v_lshl_add_u64 v[196:197], v[220:221], 0, s[26:27]
	s_addc_u32 s3, s29, 0
	s_add_i32 s4, s5, s64
	global_load_lds_dwordx4 v[196:197], off
	v_lshl_add_u64 v[196:197], s[2:3], 0, v[208:209]
	s_mov_b32 m0, s4
	s_and_b64 vcc, exec, s[38:39]
	global_load_lds_dwordx4 v[196:197], off
	v_lshl_add_u64 v[196:197], s[2:3], 0, v[212:213]
	s_add_i32 m0, s4, 0x2000
	s_nop 0
	global_load_lds_dwordx4 v[196:197], off
	v_lshl_add_u64 v[196:197], v[222:223], 0, s[26:27]
	s_mov_b32 m0, s82
	s_nop 0
	global_load_lds_dwordx4 v[196:197], off
	v_lshl_add_u64 v[196:197], v[224:225], 0, s[26:27]
	s_mov_b32 m0, s83
	s_nop 0
	global_load_lds_dwordx4 v[196:197], off
	s_waitcnt vmcnt(8)
	s_waitcnt lgkmcnt(0)
	s_barrier
	s_cbranch_vccnz .LBB0_499
	s_setprio 1
	s_waitcnt lgkmcnt(0)
	v_mfma_f32_16x16x32_bf16 v[60:63], v[146:149], v[186:189], v[60:63]
	v_mfma_f32_16x16x32_bf16 v[56:59], v[154:157], v[186:189], v[56:59]
	v_mfma_f32_16x16x32_bf16 v[44:47], v[146:149], v[178:181], v[44:47]
	v_mfma_f32_16x16x32_bf16 v[40:43], v[154:157], v[178:181], v[40:43]
	v_mfma_f32_16x16x32_bf16 v[28:31], v[146:149], v[170:173], v[28:31]
	v_mfma_f32_16x16x32_bf16 v[24:27], v[154:157], v[170:173], v[24:27]
	v_mfma_f32_16x16x32_bf16 v[12:15], v[146:149], v[162:165], v[12:15]
	v_mfma_f32_16x16x32_bf16 v[8:11], v[154:157], v[162:165], v[8:11]
	v_mfma_f32_16x16x32_bf16 v[60:63], v[150:153], v[190:193], v[60:63]
	v_mfma_f32_16x16x32_bf16 v[56:59], v[158:161], v[190:193], v[56:59]
	v_mfma_f32_16x16x32_bf16 v[44:47], v[150:153], v[182:185], v[44:47]
	v_mfma_f32_16x16x32_bf16 v[40:43], v[158:161], v[182:185], v[40:43]
	v_mfma_f32_16x16x32_bf16 v[28:31], v[150:153], v[174:177], v[28:31]
	v_mfma_f32_16x16x32_bf16 v[24:27], v[158:161], v[174:177], v[24:27]
	v_mfma_f32_16x16x32_bf16 v[12:15], v[150:153], v[166:169], v[12:15]
	v_mfma_f32_16x16x32_bf16 v[8:11], v[158:161], v[166:169], v[8:11]
	v_mfma_f32_16x16x32_bf16 v[52:55], v[130:133], v[186:189], v[52:55]
	v_mfma_f32_16x16x32_bf16 v[48:51], v[138:141], v[186:189], v[48:51]
	v_mfma_f32_16x16x32_bf16 v[36:39], v[130:133], v[178:181], v[36:39]
	v_mfma_f32_16x16x32_bf16 v[32:35], v[138:141], v[178:181], v[32:35]
	v_mfma_f32_16x16x32_bf16 v[20:23], v[130:133], v[170:173], v[20:23]
	v_mfma_f32_16x16x32_bf16 v[16:19], v[138:141], v[170:173], v[16:19]
	v_mfma_f32_16x16x32_bf16 v[4:7], v[130:133], v[162:165], v[4:7]
	v_mfma_f32_16x16x32_bf16 v[0:3], v[138:141], v[162:165], v[0:3]
	v_mfma_f32_16x16x32_bf16 v[52:55], v[134:137], v[190:193], v[52:55]
	v_mfma_f32_16x16x32_bf16 v[48:51], v[142:145], v[190:193], v[48:51]
	v_mfma_f32_16x16x32_bf16 v[36:39], v[134:137], v[182:185], v[36:39]
	v_mfma_f32_16x16x32_bf16 v[32:35], v[142:145], v[182:185], v[32:35]
	v_mfma_f32_16x16x32_bf16 v[20:23], v[134:137], v[174:177], v[20:23]
	v_mfma_f32_16x16x32_bf16 v[16:19], v[142:145], v[174:177], v[16:19]
	v_mfma_f32_16x16x32_bf16 v[4:7], v[134:137], v[166:169], v[4:7]
	v_mfma_f32_16x16x32_bf16 v[0:3], v[142:145], v[166:169], v[0:3]
	s_setprio 0
	s_branch .LBB0_499

; #define PG8_STAGE(bufoff, gbase, voff) do { _Pragma("unroll") for (int _i = 0; _i < 2; ++_i) \
;         __builtin_amdgcn_global_load_lds((const unsigned*)((const char*)(gbase) + (voff)[_i]), (PG8_LAS unsigned*)(lds + (bufoff) + ldsw + _i * 8192), 16, 0, 0); } while (0)
; #define PG8_LDA(dst, b, h) do { _Pragma("unroll") for (int m = 0; m < 4; ++m) _Pragma("unroll") for (int k = 0; k < 2; ++k) dst[m][k] = *(const PG8_LAS bf16x8*)(lds + PG8_SA(b, h) + aoff + m * 2048 + k * 1024); } while (0)
; #define PG8_LDB(dst, b, h) do { _Pragma("unroll") for (int n = 0; n < 2; ++n) _Pragma("unroll") for (int k = 0; k < 2; ++k) dst[n][k] = *(const PG8_LAS bf16x8*)(lds + PG8_SB(b, h) + boff + n * 2048 + k * 1024); } while (0)
; #define PG8_MMA(ai, bj, At, Bt) do { __builtin_amdgcn_s_setprio(1); _Pragma("unroll") for (int m = 0; m < 4; ++m) _Pragma("unroll") for (int n = 0; n < 2; ++n) _Pragma("unroll") for (int k = 0; k < 2; ++k) \
;         acc[ai][bj][m][n] = __builtin_amdgcn_mfma_f32_16x16x32_bf16(Bt[n][k], At[m][k], acc[ai][bj][m][n], 0, 0, 0); __builtin_amdgcn_s_setprio(0); } while (0)
; #define PG8_WAIT_V(n) asm volatile("s_waitcnt vmcnt(" #n ")" ::: "memory")
; #define PG8_WAIT_L(n) asm volatile("s_waitcnt lgkmcnt(" #n ")" ::: "memory")
; #define PG8_BAR __builtin_amdgcn_s_barrier()
; #define PG8_SCHED __builtin_amdgcn_sched_barrier(0)
; template <class Epi, class Sched, bool ALIGN_EPI = false, bool SP2 = false>
; __device__ __forceinline__ void gemm_phase(PG8_LAS unsigned char* lds, const Gemm g, const Sched& S, const Epi& E) {
;     ...
;             PG8_LDB(B0, 0, 0); PG8_LDB(B1, 0, 1); PG8_SCHED; PG8_LDA(At, 0, 0); PG8_STAGE(PG8_SA(1, 1), a1 + hstep, voffA);
;             PG8_WAIT_V(8); PG8_WAIT_L(0); PG8_BAR; PG8_MMA(0, 0, At, B0); PG8_MMA(0, 1, At, B1); PG8_BAR; PG8_SCHED;
;             PG8_LDA(At, 0, 1); PG8_STAGE(PG8_SB(0, 0), b2, voffB); PG8_STAGE(PG8_SB(0, 1), b2 + hstep, voffB); PG8_STAGE(PG8_SA(0, 0), a2, voffA);
;             PG8_WAIT_V(8); PG8_WAIT_L(0); PG8_BAR; if (full) { PG8_MMA(1, 0, At, B0); PG8_MMA(1, 1, At, B1); } PG8_BAR; PG8_SCHED;
.LBB0_916:
	s_add_u32 s2, s48, 0xfffc0080
	s_addc_u32 s3, s49, -1
	s_add_i32 s4, 0, 0x10000
	s_cmp_eq_u32 s79, s51
	s_cselect_b32 s35, s85, s3
	s_cselect_b32 s34, s84, s2
	v_add_u32_e32 v128, s4, v195
	s_cselect_b32 s29, s87, s50
	s_cselect_b32 s28, s86, s83
	s_add_i32 s5, 0, 0x14000
	ds_read_b128 v[146:149], v128
	ds_read_b128 v[150:153], v128 offset:1024
	ds_read_b128 v[154:157], v128 offset:2048
	ds_read_b128 v[158:161], v128 offset:3072
	v_add_u32_e32 v128, s5, v195
	ds_read_b128 v[130:133], v128
	ds_read_b128 v[134:137], v128 offset:1024
	ds_read_b128 v[138:141], v128 offset:2048
	ds_read_b128 v[142:145], v128 offset:3072
	v_lshl_add_u64 v[196:197], s[48:49], 0, v[218:219]
	s_add_i32 m0, s70, 0xc000
	s_waitcnt lgkmcnt(7)
	ds_read_b128 v[162:165], v242
	ds_read_b128 v[166:169], v242 offset:1024
	ds_read_b128 v[170:173], v242 offset:2048
	ds_read_b128 v[174:177], v242 offset:3072
	ds_read_b128 v[178:181], v242 offset:4096
	ds_read_b128 v[182:185], v242 offset:5120
	ds_read_b128 v[186:189], v242 offset:6144
	ds_read_b128 v[190:193], v242 offset:7168
	global_load_lds_dwordx4 v[196:197], off
	v_lshl_add_u64 v[196:197], s[48:49], 0, v[220:221]
	s_add_i32 m0, s70, 0xe000
	s_nop 0
	global_load_lds_dwordx4 v[196:197], off
	s_waitcnt vmcnt(8)
	s_waitcnt lgkmcnt(0)
	s_barrier
	s_setprio 1
	s_waitcnt lgkmcnt(0)
	v_mfma_f32_16x16x32_bf16 v[124:127], v[146:149], v[162:165], v[124:127]
	v_mfma_f32_16x16x32_bf16 v[120:123], v[154:157], v[162:165], v[120:123]
	v_mfma_f32_16x16x32_bf16 v[116:119], v[146:149], v[170:173], v[116:119]
	v_mfma_f32_16x16x32_bf16 v[112:115], v[154:157], v[170:173], v[112:115]
	v_mfma_f32_16x16x32_bf16 v[104:107], v[146:149], v[178:181], v[104:107]
	v_mfma_f32_16x16x32_bf16 v[96:99], v[154:157], v[178:181], v[96:99]
	v_mfma_f32_16x16x32_bf16 v[88:91], v[146:149], v[186:189], v[88:91]
	v_mfma_f32_16x16x32_bf16 v[80:83], v[154:157], v[186:189], v[80:83]
	v_mfma_f32_16x16x32_bf16 v[124:127], v[150:153], v[166:169], v[124:127]
	v_mfma_f32_16x16x32_bf16 v[120:123], v[158:161], v[166:169], v[120:123]
	v_mfma_f32_16x16x32_bf16 v[116:119], v[150:153], v[174:177], v[116:119]
	v_mfma_f32_16x16x32_bf16 v[112:115], v[158:161], v[174:177], v[112:115]
	v_mfma_f32_16x16x32_bf16 v[104:107], v[150:153], v[182:185], v[104:107]
	v_mfma_f32_16x16x32_bf16 v[96:99], v[158:161], v[182:185], v[96:99]
	v_mfma_f32_16x16x32_bf16 v[88:91], v[150:153], v[190:193], v[88:91]
	v_mfma_f32_16x16x32_bf16 v[80:83], v[158:161], v[190:193], v[80:83]
	v_mfma_f32_16x16x32_bf16 v[108:111], v[130:133], v[162:165], v[108:111]
	v_mfma_f32_16x16x32_bf16 v[100:103], v[138:141], v[162:165], v[100:103]
	v_mfma_f32_16x16x32_bf16 v[92:95], v[130:133], v[170:173], v[92:95]
	v_mfma_f32_16x16x32_bf16 v[84:87], v[138:141], v[170:173], v[84:87]
	v_mfma_f32_16x16x32_bf16 v[76:79], v[130:133], v[178:181], v[76:79]
	v_mfma_f32_16x16x32_bf16 v[72:75], v[138:141], v[178:181], v[72:75]
	v_mfma_f32_16x16x32_bf16 v[68:71], v[130:133], v[186:189], v[68:71]
	v_mfma_f32_16x16x32_bf16 v[56:59], v[138:141], v[186:189], v[56:59]
	v_mfma_f32_16x16x32_bf16 v[108:111], v[134:137], v[166:169], v[108:111]
	v_mfma_f32_16x16x32_bf16 v[100:103], v[142:145], v[166:169], v[100:103]
	v_mfma_f32_16x16x32_bf16 v[92:95], v[134:137], v[174:177], v[92:95]
	v_mfma_f32_16x16x32_bf16 v[84:87], v[142:145], v[174:177], v[84:87]
	v_mfma_f32_16x16x32_bf16 v[76:79], v[134:137], v[182:185], v[76:79]
	v_mfma_f32_16x16x32_bf16 v[72:75], v[142:145], v[182:185], v[72:75]
	v_mfma_f32_16x16x32_bf16 v[68:71], v[134:137], v[190:193], v[68:71]
	v_mfma_f32_16x16x32_bf16 v[56:59], v[142:145], v[190:193], v[56:59]
	s_setprio 0
	s_barrier
	s_add_i32 s2, s4, s65
	v_lshl_add_u64 v[222:223], s[28:29], 0, v[208:209]
	s_mov_b32 m0, s2
	ds_read_b128 v[186:189], v242 offset:16384
	ds_read_b128 v[190:193], v242 offset:17408
	ds_read_b128 v[178:181], v242 offset:18432
	ds_read_b128 v[182:185], v242 offset:19456
	ds_read_b128 v[170:173], v242 offset:20480
	ds_read_b128 v[174:177], v242 offset:21504
	ds_read_b128 v[162:165], v242 offset:22528
	ds_read_b128 v[166:169], v242 offset:23552
	global_load_lds_dwordx4 v[222:223], off
	s_add_i32 m0, s2, 0x2000
	s_add_u32 s2, s28, 0x40000
	v_lshl_add_u64 v[224:225], s[28:29], 0, v[212:213]
	s_addc_u32 s3, s29, 0
	s_add_i32 s4, s5, s65
	global_load_lds_dwordx4 v[224:225], off
	v_lshl_add_u64 v[196:197], s[2:3], 0, v[208:209]
	s_mov_b32 m0, s4
	v_lshl_add_u64 v[226:227], s[34:35], 0, v[206:207]
	global_load_lds_dwordx4 v[196:197], off
	v_lshl_add_u64 v[196:197], s[2:3], 0, v[212:213]
	s_add_i32 m0, s4, 0x2000
	v_lshl_add_u64 v[228:229], s[34:35], 0, v[210:211]
	global_load_lds_dwordx4 v[196:197], off
	s_mov_b32 m0, s70
	v_cndmask_b32_e64 v128, 0, 1, s[92:93]
	global_load_lds_dwordx4 v[226:227], off
	s_mov_b32 m0, s71
	v_cmp_ne_u32_e64 s[38:39], 1, v128
	global_load_lds_dwordx4 v[228:229], off
	s_waitcnt vmcnt(8)
	s_waitcnt lgkmcnt(0)
	s_andn2_b64 vcc, exec, s[92:93]
	s_barrier
	s_cbranch_vccnz .LBB0_918
; #define PG8_MMA(ai, bj, At, Bt) do { __builtin_amdgcn_s_setprio(1); _Pragma("unroll") for (int m = 0; m < 4; ++m) _Pragma("unroll") for (int n = 0; n < 2; ++n) _Pragma("unroll") for (int k = 0; k < 2; ++k) \
;         acc[ai][bj][m][n] = __builtin_amdgcn_mfma_f32_16x16x32_bf16(Bt[n][k], At[m][k], acc[ai][bj][m][n], 0, 0, 0); __builtin_amdgcn_s_setprio(0); } while (0)
; #define PG8_WAIT_V(n) asm volatile("s_waitcnt vmcnt(" #n ")" ::: "memory")
; #define PG8_WAIT_L(n) asm volatile("s_waitcnt lgkmcnt(" #n ")" ::: "memory")
; #define PG8_BAR __builtin_amdgcn_s_barrier()
; #define PG8_SCHED __builtin_amdgcn_sched_barrier(0)
; template <class Epi, class Sched, bool ALIGN_EPI = false, bool SP2 = false>
; __device__ __forceinline__ void gemm_phase(PG8_LAS unsigned char* lds, const Gemm g, const Sched& S, const Epi& E) {
;     ...
;             PG8_WAIT_V(8); PG8_WAIT_L(0); PG8_BAR; if (full) { PG8_MMA(1, 0, At, B0); PG8_MMA(1, 1, At, B1); } PG8_BAR; PG8_SCHED;
	s_setprio 1
	s_waitcnt lgkmcnt(0)
	v_mfma_f32_16x16x32_bf16 v[64:67], v[146:149], v[186:189], v[64:67]
	v_mfma_f32_16x16x32_bf16 v[60:63], v[154:157], v[186:189], v[60:63]
	v_mfma_f32_16x16x32_bf16 v[44:47], v[146:149], v[178:181], v[44:47]
	v_mfma_f32_16x16x32_bf16 v[40:43], v[154:157], v[178:181], v[40:43]
	v_mfma_f32_16x16x32_bf16 v[28:31], v[146:149], v[170:173], v[28:31]
	v_mfma_f32_16x16x32_bf16 v[24:27], v[154:157], v[170:173], v[24:27]
	v_mfma_f32_16x16x32_bf16 v[12:15], v[146:149], v[162:165], v[12:15]
	v_mfma_f32_16x16x32_bf16 v[8:11], v[154:157], v[162:165], v[8:11]
	v_mfma_f32_16x16x32_bf16 v[64:67], v[150:153], v[190:193], v[64:67]
	v_mfma_f32_16x16x32_bf16 v[60:63], v[158:161], v[190:193], v[60:63]
	v_mfma_f32_16x16x32_bf16 v[44:47], v[150:153], v[182:185], v[44:47]
	v_mfma_f32_16x16x32_bf16 v[40:43], v[158:161], v[182:185], v[40:43]
	v_mfma_f32_16x16x32_bf16 v[28:31], v[150:153], v[174:177], v[28:31]
	v_mfma_f32_16x16x32_bf16 v[24:27], v[158:161], v[174:177], v[24:27]
	v_mfma_f32_16x16x32_bf16 v[12:15], v[150:153], v[166:169], v[12:15]
	v_mfma_f32_16x16x32_bf16 v[8:11], v[158:161], v[166:169], v[8:11]
	v_mfma_f32_16x16x32_bf16 v[52:55], v[130:133], v[186:189], v[52:55]
	v_mfma_f32_16x16x32_bf16 v[48:51], v[138:141], v[186:189], v[48:51]
	v_mfma_f32_16x16x32_bf16 v[36:39], v[130:133], v[178:181], v[36:39]
	v_mfma_f32_16x16x32_bf16 v[32:35], v[138:141], v[178:181], v[32:35]
	v_mfma_f32_16x16x32_bf16 v[20:23], v[130:133], v[170:173], v[20:23]
	v_mfma_f32_16x16x32_bf16 v[16:19], v[138:141], v[170:173], v[16:19]
	v_mfma_f32_16x16x32_bf16 v[4:7], v[130:133], v[162:165], v[4:7]
	v_mfma_f32_16x16x32_bf16 v[0:3], v[138:141], v[162:165], v[0:3]
	v_mfma_f32_16x16x32_bf16 v[52:55], v[134:137], v[190:193], v[52:55]
	v_mfma_f32_16x16x32_bf16 v[48:51], v[142:145], v[190:193], v[48:51]
	v_mfma_f32_16x16x32_bf16 v[36:39], v[134:137], v[182:185], v[36:39]
	v_mfma_f32_16x16x32_bf16 v[32:35], v[142:145], v[182:185], v[32:35]
	v_mfma_f32_16x16x32_bf16 v[20:23], v[134:137], v[174:177], v[20:23]
	v_mfma_f32_16x16x32_bf16 v[16:19], v[142:145], v[174:177], v[16:19]
	v_mfma_f32_16x16x32_bf16 v[4:7], v[134:137], v[166:169], v[4:7]
	v_mfma_f32_16x16x32_bf16 v[0:3], v[142:145], v[166:169], v[0:3]
	s_setprio 0
; #define PG8_STAGE(bufoff, gbase, voff) do { _Pragma("unroll") for (int _i = 0; _i < 2; ++_i) \
;         __builtin_amdgcn_global_load_lds((const unsigned*)((const char*)(gbase) + (voff)[_i]), (PG8_LAS unsigned*)(lds + (bufoff) + ldsw + _i * 8192), 16, 0, 0); } while (0)
; #define PG8_LDA(dst, b, h) do { _Pragma("unroll") for (int m = 0; m < 4; ++m) _Pragma("unroll") for (int k = 0; k < 2; ++k) dst[m][k] = *(const PG8_LAS bf16x8*)(lds + PG8_SA(b, h) + aoff + m * 2048 + k * 1024); } while (0)
; #define PG8_LDB(dst, b, h) do { _Pragma("unroll") for (int n = 0; n < 2; ++n) _Pragma("unroll") for (int k = 0; k < 2; ++k) dst[n][k] = *(const PG8_LAS bf16x8*)(lds + PG8_SB(b, h) + boff + n * 2048 + k * 1024); } while (0)
; #define PG8_MMA(ai, bj, At, Bt) do { __builtin_amdgcn_s_setprio(1); _Pragma("unroll") for (int m = 0; m < 4; ++m) _Pragma("unroll") for (int n = 0; n < 2; ++n) _Pragma("unroll") for (int k = 0; k < 2; ++k) \
;         acc[ai][bj][m][n] = __builtin_amdgcn_mfma_f32_16x16x32_bf16(Bt[n][k], At[m][k], acc[ai][bj][m][n], 0, 0, 0); __builtin_amdgcn_s_setprio(0); } while (0)
; #define PG8_WAIT_V(n) asm volatile("s_waitcnt vmcnt(" #n ")" ::: "memory")
; #define PG8_WAIT_L(n) asm volatile("s_waitcnt lgkmcnt(" #n ")" ::: "memory")
; #define PG8_BAR __builtin_amdgcn_s_barrier()
; #define PG8_SCHED __builtin_amdgcn_sched_barrier(0)
; template <class Epi, class Sched, bool ALIGN_EPI = false, bool SP2 = false>
; __device__ __forceinline__ void gemm_phase(PG8_LAS unsigned char* lds, const Gemm g, const Sched& S, const Epi& E) {
;     ...
;             PG8_LDB(B0, 1, 0); PG8_LDB(B1, 1, 1); PG8_SCHED; PG8_LDA(At, 1, 0); PG8_STAGE(PG8_SA(0, 1), a2 + hstep, voffA);
;             PG8_WAIT_V(8); PG8_WAIT_L(0); PG8_BAR; PG8_MMA(0, 0, At, B0); PG8_MMA(0, 1, At, B1); PG8_BAR; PG8_SCHED;
;             PG8_LDA(At, 1, 1); PG8_STAGE(PG8_SB(1, 0), b3, voffB); PG8_STAGE(PG8_SB(1, 1), b3 + hstep, voffB); PG8_STAGE(PG8_SA(1, 0), a3, voffA);
;             PG8_WAIT_V(8); PG8_WAIT_L(0); PG8_BAR; if (full) { PG8_MMA(1, 0, At, B0); PG8_MMA(1, 1, At, B1); } PG8_BAR; PG8_SCHED;
.LBB0_918:
	s_barrier
	s_add_i32 s4, 0, 0x18000
	v_add_u32_e32 v128, s4, v195
	s_add_i32 s5, 0, 0x1c000
	ds_read_b128 v[146:149], v128
	ds_read_b128 v[150:153], v128 offset:1024
	ds_read_b128 v[154:157], v128 offset:2048
	ds_read_b128 v[158:161], v128 offset:3072
	v_add_u32_e32 v128, s5, v195
	ds_read_b128 v[130:133], v128
	ds_read_b128 v[134:137], v128 offset:1024
	ds_read_b128 v[138:141], v128 offset:2048
	ds_read_b128 v[142:145], v128 offset:3072
	s_add_u32 s2, s34, 0x40000
	s_addc_u32 s3, s35, 0
	s_mov_b32 m0, s73
	v_lshl_add_u64 v[196:197], s[2:3], 0, v[206:207]
	s_waitcnt lgkmcnt(7)
	ds_read_b128 v[162:165], v242 offset:32768
	ds_read_b128 v[166:169], v242 offset:33792
	ds_read_b128 v[170:173], v242 offset:34816
	ds_read_b128 v[174:177], v242 offset:35840
	ds_read_b128 v[178:181], v242 offset:36864
	ds_read_b128 v[182:185], v242 offset:37888
	ds_read_b128 v[186:189], v242 offset:38912
	ds_read_b128 v[190:193], v242 offset:39936
	global_load_lds_dwordx4 v[196:197], off
	v_lshl_add_u64 v[196:197], s[2:3], 0, v[210:211]
	s_mov_b32 m0, s77
	s_nop 0
	global_load_lds_dwordx4 v[196:197], off
	s_waitcnt vmcnt(8)
	s_waitcnt lgkmcnt(0)
	s_barrier
	s_setprio 1
	s_waitcnt lgkmcnt(0)
	v_mfma_f32_16x16x32_bf16 v[124:127], v[146:149], v[162:165], v[124:127]
	v_mfma_f32_16x16x32_bf16 v[120:123], v[154:157], v[162:165], v[120:123]
	v_mfma_f32_16x16x32_bf16 v[116:119], v[146:149], v[170:173], v[116:119]
	v_mfma_f32_16x16x32_bf16 v[112:115], v[154:157], v[170:173], v[112:115]
	v_mfma_f32_16x16x32_bf16 v[104:107], v[146:149], v[178:181], v[104:107]
	v_mfma_f32_16x16x32_bf16 v[96:99], v[154:157], v[178:181], v[96:99]
	v_mfma_f32_16x16x32_bf16 v[88:91], v[146:149], v[186:189], v[88:91]
	v_mfma_f32_16x16x32_bf16 v[80:83], v[154:157], v[186:189], v[80:83]
	v_mfma_f32_16x16x32_bf16 v[124:127], v[150:153], v[166:169], v[124:127]
	v_mfma_f32_16x16x32_bf16 v[120:123], v[158:161], v[166:169], v[120:123]
	v_mfma_f32_16x16x32_bf16 v[116:119], v[150:153], v[174:177], v[116:119]
	v_mfma_f32_16x16x32_bf16 v[112:115], v[158:161], v[174:177], v[112:115]
	v_mfma_f32_16x16x32_bf16 v[104:107], v[150:153], v[182:185], v[104:107]
	v_mfma_f32_16x16x32_bf16 v[96:99], v[158:161], v[182:185], v[96:99]
	v_mfma_f32_16x16x32_bf16 v[88:91], v[150:153], v[190:193], v[88:91]
	v_mfma_f32_16x16x32_bf16 v[80:83], v[158:161], v[190:193], v[80:83]
	v_mfma_f32_16x16x32_bf16 v[108:111], v[130:133], v[162:165], v[108:111]
	v_mfma_f32_16x16x32_bf16 v[100:103], v[138:141], v[162:165], v[100:103]
	v_mfma_f32_16x16x32_bf16 v[92:95], v[130:133], v[170:173], v[92:95]
	v_mfma_f32_16x16x32_bf16 v[84:87], v[138:141], v[170:173], v[84:87]
	v_mfma_f32_16x16x32_bf16 v[76:79], v[130:133], v[178:181], v[76:79]
	v_mfma_f32_16x16x32_bf16 v[72:75], v[138:141], v[178:181], v[72:75]
	v_mfma_f32_16x16x32_bf16 v[68:71], v[130:133], v[186:189], v[68:71]
	v_mfma_f32_16x16x32_bf16 v[56:59], v[138:141], v[186:189], v[56:59]
	v_mfma_f32_16x16x32_bf16 v[108:111], v[134:137], v[166:169], v[108:111]
	v_mfma_f32_16x16x32_bf16 v[100:103], v[142:145], v[166:169], v[100:103]
	v_mfma_f32_16x16x32_bf16 v[92:95], v[134:137], v[174:177], v[92:95]
	v_mfma_f32_16x16x32_bf16 v[84:87], v[142:145], v[174:177], v[84:87]
	v_mfma_f32_16x16x32_bf16 v[76:79], v[134:137], v[182:185], v[76:79]
	v_mfma_f32_16x16x32_bf16 v[72:75], v[142:145], v[182:185], v[72:75]
	v_mfma_f32_16x16x32_bf16 v[68:71], v[134:137], v[190:193], v[68:71]
	v_mfma_f32_16x16x32_bf16 v[56:59], v[142:145], v[190:193], v[56:59]
	s_setprio 0
	s_barrier
	s_add_i32 s2, s4, s65
	v_lshl_add_u64 v[196:197], v[222:223], 0, s[26:27]
	s_mov_b32 m0, s2
	ds_read_b128 v[186:189], v242 offset:49152
	ds_read_b128 v[190:193], v242 offset:50176
	ds_read_b128 v[178:181], v242 offset:51200
	ds_read_b128 v[182:185], v242 offset:52224
	ds_read_b128 v[170:173], v242 offset:53248
	ds_read_b128 v[174:177], v242 offset:54272
	ds_read_b128 v[162:165], v242 offset:55296
	ds_read_b128 v[166:169], v242 offset:56320
	global_load_lds_dwordx4 v[196:197], off
	s_add_i32 m0, s2, 0x2000
	s_add_u32 s2, s28, 0x40080
	v_lshl_add_u64 v[196:197], v[224:225], 0, s[26:27]
	s_addc_u32 s3, s29, 0
	s_add_i32 s4, s5, s65
	global_load_lds_dwordx4 v[196:197], off
	v_lshl_add_u64 v[196:197], s[2:3], 0, v[208:209]
	s_mov_b32 m0, s4
	s_and_b64 vcc, exec, s[38:39]
	global_load_lds_dwordx4 v[196:197], off
	v_lshl_add_u64 v[196:197], s[2:3], 0, v[212:213]
	s_add_i32 m0, s4, 0x2000
	s_nop 0
	global_load_lds_dwordx4 v[196:197], off
	v_lshl_add_u64 v[196:197], v[226:227], 0, s[26:27]
	s_mov_b32 m0, s81
	s_nop 0
	global_load_lds_dwordx4 v[196:197], off
	v_lshl_add_u64 v[196:197], v[228:229], 0, s[26:27]
	s_mov_b32 m0, s88
	s_nop 0
	global_load_lds_dwordx4 v[196:197], off
	s_waitcnt vmcnt(8)
	s_waitcnt lgkmcnt(0)
	s_barrier
	s_cbranch_vccnz .LBB0_915
	s_setprio 1
	s_waitcnt lgkmcnt(0)
	v_mfma_f32_16x16x32_bf16 v[64:67], v[146:149], v[186:189], v[64:67]
	v_mfma_f32_16x16x32_bf16 v[60:63], v[154:157], v[186:189], v[60:63]
	v_mfma_f32_16x16x32_bf16 v[44:47], v[146:149], v[178:181], v[44:47]
	v_mfma_f32_16x16x32_bf16 v[40:43], v[154:157], v[178:181], v[40:43]
	v_mfma_f32_16x16x32_bf16 v[28:31], v[146:149], v[170:173], v[28:31]
	v_mfma_f32_16x16x32_bf16 v[24:27], v[154:157], v[170:173], v[24:27]
	v_mfma_f32_16x16x32_bf16 v[12:15], v[146:149], v[162:165], v[12:15]
	v_mfma_f32_16x16x32_bf16 v[8:11], v[154:157], v[162:165], v[8:11]
	v_mfma_f32_16x16x32_bf16 v[64:67], v[150:153], v[190:193], v[64:67]
	v_mfma_f32_16x16x32_bf16 v[60:63], v[158:161], v[190:193], v[60:63]
	v_mfma_f32_16x16x32_bf16 v[44:47], v[150:153], v[182:185], v[44:47]
	v_mfma_f32_16x16x32_bf16 v[40:43], v[158:161], v[182:185], v[40:43]
	v_mfma_f32_16x16x32_bf16 v[28:31], v[150:153], v[174:177], v[28:31]
	v_mfma_f32_16x16x32_bf16 v[24:27], v[158:161], v[174:177], v[24:27]
	v_mfma_f32_16x16x32_bf16 v[12:15], v[150:153], v[166:169], v[12:15]
	v_mfma_f32_16x16x32_bf16 v[8:11], v[158:161], v[166:169], v[8:11]
	v_mfma_f32_16x16x32_bf16 v[52:55], v[130:133], v[186:189], v[52:55]
	v_mfma_f32_16x16x32_bf16 v[48:51], v[138:141], v[186:189], v[48:51]
	v_mfma_f32_16x16x32_bf16 v[36:39], v[130:133], v[178:181], v[36:39]
	v_mfma_f32_16x16x32_bf16 v[32:35], v[138:141], v[178:181], v[32:35]
	v_mfma_f32_16x16x32_bf16 v[20:23], v[130:133], v[170:173], v[20:23]
	v_mfma_f32_16x16x32_bf16 v[16:19], v[138:141], v[170:173], v[16:19]
	v_mfma_f32_16x16x32_bf16 v[4:7], v[130:133], v[162:165], v[4:7]
	v_mfma_f32_16x16x32_bf16 v[0:3], v[138:141], v[162:165], v[0:3]
	v_mfma_f32_16x16x32_bf16 v[52:55], v[134:137], v[190:193], v[52:55]
	v_mfma_f32_16x16x32_bf16 v[48:51], v[142:145], v[190:193], v[48:51]
	v_mfma_f32_16x16x32_bf16 v[36:39], v[134:137], v[182:185], v[36:39]
	v_mfma_f32_16x16x32_bf16 v[32:35], v[142:145], v[182:185], v[32:35]
	v_mfma_f32_16x16x32_bf16 v[20:23], v[134:137], v[174:177], v[20:23]
	v_mfma_f32_16x16x32_bf16 v[16:19], v[142:145], v[174:177], v[16:19]
	v_mfma_f32_16x16x32_bf16 v[4:7], v[134:137], v[166:169], v[4:7]
	v_mfma_f32_16x16x32_bf16 v[0:3], v[142:145], v[166:169], v[0:3]
	s_setprio 0
	s_branch .LBB0_915

; #define PG8_STAGE(bufoff, gbase, voff) do { _Pragma("unroll") for (int _i = 0; _i < 2; ++_i) \
;         __builtin_amdgcn_global_load_lds((const unsigned*)((const char*)(gbase) + (voff)[_i]), (PG8_LAS unsigned*)(lds + (bufoff) + ldsw + _i * 8192), 16, 0, 0); } while (0)
; #define PG8_LDA(dst, b, h) do { _Pragma("unroll") for (int m = 0; m < 4; ++m) _Pragma("unroll") for (int k = 0; k < 2; ++k) dst[m][k] = *(const PG8_LAS bf16x8*)(lds + PG8_SA(b, h) + aoff + m * 2048 + k * 1024); } while (0)
; #define PG8_LDB(dst, b, h) do { _Pragma("unroll") for (int n = 0; n < 2; ++n) _Pragma("unroll") for (int k = 0; k < 2; ++k) dst[n][k] = *(const PG8_LAS bf16x8*)(lds + PG8_SB(b, h) + boff + n * 2048 + k * 1024); } while (0)
; #define PG8_MMA(ai, bj, At, Bt) do { __builtin_amdgcn_s_setprio(1); _Pragma("unroll") for (int m = 0; m < 4; ++m) _Pragma("unroll") for (int n = 0; n < 2; ++n) _Pragma("unroll") for (int k = 0; k < 2; ++k) \
;         acc[ai][bj][m][n] = __builtin_amdgcn_mfma_f32_16x16x32_bf16(Bt[n][k], At[m][k], acc[ai][bj][m][n], 0, 0, 0); __builtin_amdgcn_s_setprio(0); } while (0)
; #define PG8_WAIT_V(n) asm volatile("s_waitcnt vmcnt(" #n ")" ::: "memory")
; #define PG8_WAIT_L(n) asm volatile("s_waitcnt lgkmcnt(" #n ")" ::: "memory")
; #define PG8_BAR __builtin_amdgcn_s_barrier()
; #define PG8_SCHED __builtin_amdgcn_sched_barrier(0)
; template <class Epi, class Sched, bool ALIGN_EPI = false, bool SP2 = false>
; __device__ __forceinline__ void gemm_phase(PG8_LAS unsigned char* lds, const Gemm g, const Sched& S, const Epi& E) {
;     ...
;             PG8_LDB(B0, 0, 0); PG8_LDB(B1, 0, 1); PG8_SCHED; PG8_LDA(At, 0, 0); PG8_STAGE(PG8_SA(1, 1), a1 + hstep, voffA);
;             PG8_WAIT_V(8); PG8_WAIT_L(0); PG8_BAR; PG8_MMA(0, 0, At, B0); PG8_MMA(0, 1, At, B1); PG8_BAR; PG8_SCHED;
;             PG8_LDA(At, 0, 1); PG8_STAGE(PG8_SB(0, 0), b2, voffB); PG8_STAGE(PG8_SB(0, 1), b2 + hstep, voffB); PG8_STAGE(PG8_SA(0, 0), a2, voffA);
;             PG8_WAIT_V(8); PG8_WAIT_L(0); PG8_BAR; if (full) { PG8_MMA(1, 0, At, B0); PG8_MMA(1, 1, At, B1); } PG8_BAR; PG8_SCHED;
.LBB0_1079:
	s_add_u32 s2, s48, 0xfffc0080
	s_addc_u32 s3, s49, -1
	s_add_i32 s4, 0, 0x10000
	s_cmp_eq_u32 s12, 12
	s_cselect_b32 s35, s1, s3
	s_cselect_b32 s34, s90, s2
	v_add_u32_e32 v128, s4, v226
	s_cselect_b32 s29, s75, s50
	s_cselect_b32 s28, s91, s92
	s_add_i32 s5, 0, 0x14000
	ds_read_b128 v[146:149], v128
	ds_read_b128 v[150:153], v128 offset:1024
	ds_read_b128 v[154:157], v128 offset:2048
	ds_read_b128 v[158:161], v128 offset:3072
	v_add_u32_e32 v128, s5, v226
	ds_read_b128 v[130:133], v128
	ds_read_b128 v[134:137], v128 offset:1024
	ds_read_b128 v[138:141], v128 offset:2048
	ds_read_b128 v[142:145], v128 offset:3072
	v_lshl_add_u64 v[196:197], s[48:49], 0, v[214:215]
	s_add_i32 m0, s70, 0xc000
	s_waitcnt lgkmcnt(7)
	ds_read_b128 v[162:165], v228
	ds_read_b128 v[166:169], v228 offset:1024
	ds_read_b128 v[170:173], v228 offset:2048
	ds_read_b128 v[174:177], v228 offset:3072
	ds_read_b128 v[178:181], v228 offset:4096
	ds_read_b128 v[182:185], v228 offset:5120
	ds_read_b128 v[186:189], v228 offset:6144
	ds_read_b128 v[190:193], v228 offset:7168
	global_load_lds_dwordx4 v[196:197], off
	v_lshl_add_u64 v[196:197], s[48:49], 0, v[216:217]
	s_add_i32 m0, s70, 0xe000
	s_nop 0
	global_load_lds_dwordx4 v[196:197], off
	s_waitcnt vmcnt(8)
	s_waitcnt lgkmcnt(0)
	s_barrier
	s_setprio 1
	s_waitcnt lgkmcnt(0)
	v_mfma_f32_16x16x32_bf16 v[124:127], v[146:149], v[162:165], v[124:127]
	v_mfma_f32_16x16x32_bf16 v[120:123], v[154:157], v[162:165], v[120:123]
	v_mfma_f32_16x16x32_bf16 v[108:111], v[146:149], v[170:173], v[108:111]
	v_mfma_f32_16x16x32_bf16 v[104:107], v[154:157], v[170:173], v[104:107]
	v_mfma_f32_16x16x32_bf16 v[92:95], v[146:149], v[178:181], v[92:95]
	v_mfma_f32_16x16x32_bf16 v[88:91], v[154:157], v[178:181], v[88:91]
	v_mfma_f32_16x16x32_bf16 v[76:79], v[146:149], v[186:189], v[76:79]
	v_mfma_f32_16x16x32_bf16 v[72:75], v[154:157], v[186:189], v[72:75]
	v_mfma_f32_16x16x32_bf16 v[124:127], v[150:153], v[166:169], v[124:127]
	v_mfma_f32_16x16x32_bf16 v[120:123], v[158:161], v[166:169], v[120:123]
	v_mfma_f32_16x16x32_bf16 v[108:111], v[150:153], v[174:177], v[108:111]
	v_mfma_f32_16x16x32_bf16 v[104:107], v[158:161], v[174:177], v[104:107]
	v_mfma_f32_16x16x32_bf16 v[92:95], v[150:153], v[182:185], v[92:95]
	v_mfma_f32_16x16x32_bf16 v[88:91], v[158:161], v[182:185], v[88:91]
	v_mfma_f32_16x16x32_bf16 v[76:79], v[150:153], v[190:193], v[76:79]
	v_mfma_f32_16x16x32_bf16 v[72:75], v[158:161], v[190:193], v[72:75]
	v_mfma_f32_16x16x32_bf16 v[116:119], v[130:133], v[162:165], v[116:119]
	v_mfma_f32_16x16x32_bf16 v[112:115], v[138:141], v[162:165], v[112:115]
	v_mfma_f32_16x16x32_bf16 v[100:103], v[130:133], v[170:173], v[100:103]
	v_mfma_f32_16x16x32_bf16 v[96:99], v[138:141], v[170:173], v[96:99]
	v_mfma_f32_16x16x32_bf16 v[84:87], v[130:133], v[178:181], v[84:87]
	v_mfma_f32_16x16x32_bf16 v[80:83], v[138:141], v[178:181], v[80:83]
	v_mfma_f32_16x16x32_bf16 v[68:71], v[130:133], v[186:189], v[68:71]
	v_mfma_f32_16x16x32_bf16 v[64:67], v[138:141], v[186:189], v[64:67]
	v_mfma_f32_16x16x32_bf16 v[116:119], v[134:137], v[166:169], v[116:119]
	v_mfma_f32_16x16x32_bf16 v[112:115], v[142:145], v[166:169], v[112:115]
	v_mfma_f32_16x16x32_bf16 v[100:103], v[134:137], v[174:177], v[100:103]
	v_mfma_f32_16x16x32_bf16 v[96:99], v[142:145], v[174:177], v[96:99]
	v_mfma_f32_16x16x32_bf16 v[84:87], v[134:137], v[182:185], v[84:87]
	v_mfma_f32_16x16x32_bf16 v[80:83], v[142:145], v[182:185], v[80:83]
	v_mfma_f32_16x16x32_bf16 v[68:71], v[134:137], v[190:193], v[68:71]
	v_mfma_f32_16x16x32_bf16 v[64:67], v[142:145], v[190:193], v[64:67]
	s_setprio 0
	s_barrier
	s_add_i32 s2, s4, s65
	v_lshl_add_u64 v[218:219], s[28:29], 0, v[208:209]
	s_mov_b32 m0, s2
	ds_read_b128 v[186:189], v228 offset:16384
	ds_read_b128 v[190:193], v228 offset:17408
	ds_read_b128 v[178:181], v228 offset:18432
	ds_read_b128 v[182:185], v228 offset:19456
	ds_read_b128 v[170:173], v228 offset:20480
	ds_read_b128 v[174:177], v228 offset:21504
	ds_read_b128 v[162:165], v228 offset:22528
	ds_read_b128 v[166:169], v228 offset:23552
	global_load_lds_dwordx4 v[218:219], off
	s_add_i32 m0, s2, 0x2000
	s_add_u32 s2, s28, 0x40000
	v_lshl_add_u64 v[220:221], s[28:29], 0, v[212:213]
	s_addc_u32 s3, s29, 0
	s_add_i32 s4, s5, s65
	global_load_lds_dwordx4 v[220:221], off
	v_lshl_add_u64 v[196:197], s[2:3], 0, v[208:209]
	s_mov_b32 m0, s4
	v_lshl_add_u64 v[222:223], s[34:35], 0, v[206:207]
	global_load_lds_dwordx4 v[196:197], off
	v_lshl_add_u64 v[196:197], s[2:3], 0, v[212:213]
	s_add_i32 m0, s4, 0x2000
	v_lshl_add_u64 v[224:225], s[34:35], 0, v[210:211]
	global_load_lds_dwordx4 v[196:197], off
	s_mov_b32 m0, s70
	v_cndmask_b32_e64 v128, 0, 1, s[82:83]
	global_load_lds_dwordx4 v[222:223], off
	s_mov_b32 m0, s71
	v_cmp_ne_u32_e64 s[38:39], 1, v128
	global_load_lds_dwordx4 v[224:225], off
	s_waitcnt vmcnt(8)
	s_waitcnt lgkmcnt(0)
	s_andn2_b64 vcc, exec, s[82:83]
	s_barrier
	s_cbranch_vccnz .LBB0_1081
; #define PG8_STAGE(bufoff, gbase, voff) do { _Pragma("unroll") for (int _i = 0; _i < 2; ++_i) \
;         __builtin_amdgcn_global_load_lds((const unsigned*)((const char*)(gbase) + (voff)[_i]), (PG8_LAS unsigned*)(lds + (bufoff) + ldsw + _i * 8192), 16, 0, 0); } while (0)
; #define PG8_LDA(dst, b, h) do { _Pragma("unroll") for (int m = 0; m < 4; ++m) _Pragma("unroll") for (int k = 0; k < 2; ++k) dst[m][k] = *(const PG8_LAS bf16x8*)(lds + PG8_SA(b, h) + aoff + m * 2048 + k * 1024); } while (0)
; #define PG8_LDB(dst, b, h) do { _Pragma("unroll") for (int n = 0; n < 2; ++n) _Pragma("unroll") for (int k = 0; k < 2; ++k) dst[n][k] = *(const PG8_LAS bf16x8*)(lds + PG8_SB(b, h) + boff + n * 2048 + k * 1024); } while (0)
; #define PG8_MMA(ai, bj, At, Bt) do { __builtin_amdgcn_s_setprio(1); _Pragma("unroll") for (int m = 0; m < 4; ++m) _Pragma("unroll") for (int n = 0; n < 2; ++n) _Pragma("unroll") for (int k = 0; k < 2; ++k) \
;         acc[ai][bj][m][n] = __builtin_amdgcn_mfma_f32_16x16x32_bf16(Bt[n][k], At[m][k], acc[ai][bj][m][n], 0, 0, 0); __builtin_amdgcn_s_setprio(0); } while (0)
; #define PG8_WAIT_V(n) asm volatile("s_waitcnt vmcnt(" #n ")" ::: "memory")
; #define PG8_WAIT_L(n) asm volatile("s_waitcnt lgkmcnt(" #n ")" ::: "memory")
; template <class Epi, class Sched, bool ALIGN_EPI = false, bool SP2 = false>
; __device__ __forceinline__ void gemm_phase(PG8_LAS unsigned char* lds, const Gemm g, const Sched& S, const Epi& E) {
;     ...
;             PG8_WAIT_V(8); PG8_WAIT_L(0); PG8_BAR; PG8_MMA(0, 0, At, B0); PG8_MMA(0, 1, At, B1); PG8_BAR; PG8_SCHED;
;             PG8_LDA(At, 0, 1); PG8_STAGE(PG8_SB(0, 0), b2, voffB); PG8_STAGE(PG8_SB(0, 1), b2 + hstep, voffB); PG8_STAGE(PG8_SA(0, 0), a2, voffA);
;             PG8_WAIT_V(8); PG8_WAIT_L(0); PG8_BAR; if (full) { PG8_MMA(1, 0, At, B0); PG8_MMA(1, 1, At, B1); } PG8_BAR; PG8_SCHED;
;             PG8_LDB(B0, 1, 0); PG8_LDB(B1, 1, 1); PG8_SCHED; PG8_LDA(At, 1, 0); PG8_STAGE(PG8_SA(0, 1), a2 + hstep, voffA);
;             PG8_WAIT_V(8); PG8_WAIT_L(0); PG8_BAR; PG8_MMA(0, 0, At, B0); PG8_MMA(0, 1, At, B1); PG8_BAR; PG8_SCHED;
;             PG8_LDA(At, 1, 1); PG8_STAGE(PG8_SB(1, 0), b3, voffB); PG8_STAGE(PG8_SB(1, 1), b3 + hstep, voffB); PG8_STAGE(PG8_SA(1, 0), a3, voffA);
;             PG8_WAIT_V(8); PG8_WAIT_L(0); PG8_BAR; if (full) { PG8_MMA(1, 0, At, B0); PG8_MMA(1, 1, At, B1); } PG8_BAR; PG8_SCHED;
	s_setprio 1
	s_waitcnt lgkmcnt(0)
	v_mfma_f32_16x16x32_bf16 v[60:63], v[146:149], v[186:189], v[60:63]
	v_mfma_f32_16x16x32_bf16 v[52:55], v[154:157], v[186:189], v[52:55]
	v_mfma_f32_16x16x32_bf16 v[44:47], v[146:149], v[178:181], v[44:47]
	v_mfma_f32_16x16x32_bf16 v[36:39], v[154:157], v[178:181], v[36:39]
	v_mfma_f32_16x16x32_bf16 v[28:31], v[146:149], v[170:173], v[28:31]
	v_mfma_f32_16x16x32_bf16 v[20:23], v[154:157], v[170:173], v[20:23]
	v_mfma_f32_16x16x32_bf16 v[12:15], v[146:149], v[162:165], v[12:15]
	v_mfma_f32_16x16x32_bf16 v[4:7], v[154:157], v[162:165], v[4:7]
	v_mfma_f32_16x16x32_bf16 v[60:63], v[150:153], v[190:193], v[60:63]
	v_mfma_f32_16x16x32_bf16 v[52:55], v[158:161], v[190:193], v[52:55]
	v_mfma_f32_16x16x32_bf16 v[44:47], v[150:153], v[182:185], v[44:47]
	v_mfma_f32_16x16x32_bf16 v[36:39], v[158:161], v[182:185], v[36:39]
	v_mfma_f32_16x16x32_bf16 v[28:31], v[150:153], v[174:177], v[28:31]
	v_mfma_f32_16x16x32_bf16 v[20:23], v[158:161], v[174:177], v[20:23]
	v_mfma_f32_16x16x32_bf16 v[12:15], v[150:153], v[166:169], v[12:15]
	v_mfma_f32_16x16x32_bf16 v[4:7], v[158:161], v[166:169], v[4:7]
	v_mfma_f32_16x16x32_bf16 v[56:59], v[130:133], v[186:189], v[56:59]
	v_mfma_f32_16x16x32_bf16 v[48:51], v[138:141], v[186:189], v[48:51]
	v_mfma_f32_16x16x32_bf16 v[40:43], v[130:133], v[178:181], v[40:43]
	v_mfma_f32_16x16x32_bf16 v[32:35], v[138:141], v[178:181], v[32:35]
	v_mfma_f32_16x16x32_bf16 v[24:27], v[130:133], v[170:173], v[24:27]
	v_mfma_f32_16x16x32_bf16 v[16:19], v[138:141], v[170:173], v[16:19]
	v_mfma_f32_16x16x32_bf16 v[8:11], v[130:133], v[162:165], v[8:11]
	v_mfma_f32_16x16x32_bf16 v[0:3], v[138:141], v[162:165], v[0:3]
	v_mfma_f32_16x16x32_bf16 v[56:59], v[134:137], v[190:193], v[56:59]
	v_mfma_f32_16x16x32_bf16 v[48:51], v[142:145], v[190:193], v[48:51]
	v_mfma_f32_16x16x32_bf16 v[40:43], v[134:137], v[182:185], v[40:43]
	v_mfma_f32_16x16x32_bf16 v[32:35], v[142:145], v[182:185], v[32:35]
	v_mfma_f32_16x16x32_bf16 v[24:27], v[134:137], v[174:177], v[24:27]
	v_mfma_f32_16x16x32_bf16 v[16:19], v[142:145], v[174:177], v[16:19]
	v_mfma_f32_16x16x32_bf16 v[8:11], v[134:137], v[166:169], v[8:11]
	v_mfma_f32_16x16x32_bf16 v[0:3], v[142:145], v[166:169], v[0:3]
	s_setprio 0
; #define PG8_STAGE(bufoff, gbase, voff) do { _Pragma("unroll") for (int _i = 0; _i < 2; ++_i) \
;         __builtin_amdgcn_global_load_lds((const unsigned*)((const char*)(gbase) + (voff)[_i]), (PG8_LAS unsigned*)(lds + (bufoff) + ldsw + _i * 8192), 16, 0, 0); } while (0)
; #define PG8_LDA(dst, b, h) do { _Pragma("unroll") for (int m = 0; m < 4; ++m) _Pragma("unroll") for (int k = 0; k < 2; ++k) dst[m][k] = *(const PG8_LAS bf16x8*)(lds + PG8_SA(b, h) + aoff + m * 2048 + k * 1024); } while (0)
; #define PG8_LDB(dst, b, h) do { _Pragma("unroll") for (int n = 0; n < 2; ++n) _Pragma("unroll") for (int k = 0; k < 2; ++k) dst[n][k] = *(const PG8_LAS bf16x8*)(lds + PG8_SB(b, h) + boff + n * 2048 + k * 1024); } while (0)
; #define PG8_MMA(ai, bj, At, Bt) do { __builtin_amdgcn_s_setprio(1); _Pragma("unroll") for (int m = 0; m < 4; ++m) _Pragma("unroll") for (int n = 0; n < 2; ++n) _Pragma("unroll") for (int k = 0; k < 2; ++k) \
;         acc[ai][bj][m][n] = __builtin_amdgcn_mfma_f32_16x16x32_bf16(Bt[n][k], At[m][k], acc[ai][bj][m][n], 0, 0, 0); __builtin_amdgcn_s_setprio(0); } while (0)
; #define PG8_WAIT_V(n) asm volatile("s_waitcnt vmcnt(" #n ")" ::: "memory")
; #define PG8_WAIT_L(n) asm volatile("s_waitcnt lgkmcnt(" #n ")" ::: "memory")
; #define PG8_BAR __builtin_amdgcn_s_barrier()
; #define PG8_SCHED __builtin_amdgcn_sched_barrier(0)
; template <class Epi, class Sched, bool ALIGN_EPI = false, bool SP2 = false>
; __device__ __forceinline__ void gemm_phase(PG8_LAS unsigned char* lds, const Gemm g, const Sched& S, const Epi& E) {
;     ...
;             PG8_LDB(B0, 1, 0); PG8_LDB(B1, 1, 1); PG8_SCHED; PG8_LDA(At, 1, 0); PG8_STAGE(PG8_SA(0, 1), a2 + hstep, voffA);
;             PG8_WAIT_V(8); PG8_WAIT_L(0); PG8_BAR; PG8_MMA(0, 0, At, B0); PG8_MMA(0, 1, At, B1); PG8_BAR; PG8_SCHED;
;             PG8_LDA(At, 1, 1); PG8_STAGE(PG8_SB(1, 0), b3, voffB); PG8_STAGE(PG8_SB(1, 1), b3 + hstep, voffB); PG8_STAGE(PG8_SA(1, 0), a3, voffA);
;             PG8_WAIT_V(8); PG8_WAIT_L(0); PG8_BAR; if (full) { PG8_MMA(1, 0, At, B0); PG8_MMA(1, 1, At, B1); } PG8_BAR; PG8_SCHED;
.LBB0_1081:
	s_barrier
	s_add_i32 s4, 0, 0x18000
	v_add_u32_e32 v128, s4, v226
	s_add_i32 s5, 0, 0x1c000
	ds_read_b128 v[146:149], v128
	ds_read_b128 v[150:153], v128 offset:1024
	ds_read_b128 v[154:157], v128 offset:2048
	ds_read_b128 v[158:161], v128 offset:3072
	v_add_u32_e32 v128, s5, v226
	ds_read_b128 v[130:133], v128
	ds_read_b128 v[134:137], v128 offset:1024
	ds_read_b128 v[138:141], v128 offset:2048
	ds_read_b128 v[142:145], v128 offset:3072
	s_add_u32 s2, s34, 0x40000
	s_addc_u32 s3, s35, 0
	s_mov_b32 m0, s73
	v_lshl_add_u64 v[196:197], s[2:3], 0, v[206:207]
	s_waitcnt lgkmcnt(7)
	ds_read_b128 v[162:165], v228 offset:32768
	ds_read_b128 v[166:169], v228 offset:33792
	ds_read_b128 v[170:173], v228 offset:34816
	ds_read_b128 v[174:177], v228 offset:35840
	ds_read_b128 v[178:181], v228 offset:36864
	ds_read_b128 v[182:185], v228 offset:37888
	ds_read_b128 v[186:189], v228 offset:38912
	ds_read_b128 v[190:193], v228 offset:39936
	global_load_lds_dwordx4 v[196:197], off
	v_lshl_add_u64 v[196:197], s[2:3], 0, v[210:211]
	s_mov_b32 m0, s81
	s_nop 0
	global_load_lds_dwordx4 v[196:197], off
	s_waitcnt vmcnt(8)
	s_waitcnt lgkmcnt(0)
	s_barrier
	s_setprio 1
	s_waitcnt lgkmcnt(0)
	v_mfma_f32_16x16x32_bf16 v[124:127], v[146:149], v[162:165], v[124:127]
	v_mfma_f32_16x16x32_bf16 v[120:123], v[154:157], v[162:165], v[120:123]
	v_mfma_f32_16x16x32_bf16 v[108:111], v[146:149], v[170:173], v[108:111]
	v_mfma_f32_16x16x32_bf16 v[104:107], v[154:157], v[170:173], v[104:107]
	v_mfma_f32_16x16x32_bf16 v[92:95], v[146:149], v[178:181], v[92:95]
	v_mfma_f32_16x16x32_bf16 v[88:91], v[154:157], v[178:181], v[88:91]
	v_mfma_f32_16x16x32_bf16 v[76:79], v[146:149], v[186:189], v[76:79]
	v_mfma_f32_16x16x32_bf16 v[72:75], v[154:157], v[186:189], v[72:75]
	v_mfma_f32_16x16x32_bf16 v[124:127], v[150:153], v[166:169], v[124:127]
	v_mfma_f32_16x16x32_bf16 v[120:123], v[158:161], v[166:169], v[120:123]
	v_mfma_f32_16x16x32_bf16 v[108:111], v[150:153], v[174:177], v[108:111]
	v_mfma_f32_16x16x32_bf16 v[104:107], v[158:161], v[174:177], v[104:107]
	v_mfma_f32_16x16x32_bf16 v[92:95], v[150:153], v[182:185], v[92:95]
	v_mfma_f32_16x16x32_bf16 v[88:91], v[158:161], v[182:185], v[88:91]
	v_mfma_f32_16x16x32_bf16 v[76:79], v[150:153], v[190:193], v[76:79]
	v_mfma_f32_16x16x32_bf16 v[72:75], v[158:161], v[190:193], v[72:75]
	v_mfma_f32_16x16x32_bf16 v[116:119], v[130:133], v[162:165], v[116:119]
	v_mfma_f32_16x16x32_bf16 v[112:115], v[138:141], v[162:165], v[112:115]
	v_mfma_f32_16x16x32_bf16 v[100:103], v[130:133], v[170:173], v[100:103]
	v_mfma_f32_16x16x32_bf16 v[96:99], v[138:141], v[170:173], v[96:99]
	v_mfma_f32_16x16x32_bf16 v[84:87], v[130:133], v[178:181], v[84:87]
	v_mfma_f32_16x16x32_bf16 v[80:83], v[138:141], v[178:181], v[80:83]
	v_mfma_f32_16x16x32_bf16 v[68:71], v[130:133], v[186:189], v[68:71]
	v_mfma_f32_16x16x32_bf16 v[64:67], v[138:141], v[186:189], v[64:67]
	v_mfma_f32_16x16x32_bf16 v[116:119], v[134:137], v[166:169], v[116:119]
	v_mfma_f32_16x16x32_bf16 v[112:115], v[142:145], v[166:169], v[112:115]
	v_mfma_f32_16x16x32_bf16 v[100:103], v[134:137], v[174:177], v[100:103]
	v_mfma_f32_16x16x32_bf16 v[96:99], v[142:145], v[174:177], v[96:99]
	v_mfma_f32_16x16x32_bf16 v[84:87], v[134:137], v[182:185], v[84:87]
	v_mfma_f32_16x16x32_bf16 v[80:83], v[142:145], v[182:185], v[80:83]
	v_mfma_f32_16x16x32_bf16 v[68:71], v[134:137], v[190:193], v[68:71]
	v_mfma_f32_16x16x32_bf16 v[64:67], v[142:145], v[190:193], v[64:67]
	s_setprio 0
	s_barrier
	s_add_i32 s2, s4, s65
	v_lshl_add_u64 v[196:197], v[218:219], 0, s[26:27]
	s_mov_b32 m0, s2
	ds_read_b128 v[186:189], v228 offset:49152
	ds_read_b128 v[190:193], v228 offset:50176
	ds_read_b128 v[178:181], v228 offset:51200
	ds_read_b128 v[182:185], v228 offset:52224
	ds_read_b128 v[170:173], v228 offset:53248
	ds_read_b128 v[174:177], v228 offset:54272
	ds_read_b128 v[162:165], v228 offset:55296
	ds_read_b128 v[166:169], v228 offset:56320
	global_load_lds_dwordx4 v[196:197], off
	s_add_i32 m0, s2, 0x2000
	s_add_u32 s2, s28, 0x40080
	v_lshl_add_u64 v[196:197], v[220:221], 0, s[26:27]
	s_addc_u32 s3, s29, 0
	s_add_i32 s4, s5, s65
	global_load_lds_dwordx4 v[196:197], off
	v_lshl_add_u64 v[196:197], s[2:3], 0, v[208:209]
	s_mov_b32 m0, s4
	s_and_b64 vcc, exec, s[38:39]
	global_load_lds_dwordx4 v[196:197], off
	v_lshl_add_u64 v[196:197], s[2:3], 0, v[212:213]
	s_add_i32 m0, s4, 0x2000
	s_nop 0
	global_load_lds_dwordx4 v[196:197], off
	v_lshl_add_u64 v[196:197], v[222:223], 0, s[26:27]
	s_mov_b32 m0, s84
	s_nop 0
	global_load_lds_dwordx4 v[196:197], off
	v_lshl_add_u64 v[196:197], v[224:225], 0, s[26:27]
	s_mov_b32 m0, s85
	s_nop 0
	global_load_lds_dwordx4 v[196:197], off
	s_waitcnt vmcnt(8)
	s_waitcnt lgkmcnt(0)
	s_barrier
	s_cbranch_vccnz .LBB0_1078
	s_setprio 1
	s_waitcnt lgkmcnt(0)
	v_mfma_f32_16x16x32_bf16 v[60:63], v[146:149], v[186:189], v[60:63]
	v_mfma_f32_16x16x32_bf16 v[52:55], v[154:157], v[186:189], v[52:55]
	v_mfma_f32_16x16x32_bf16 v[44:47], v[146:149], v[178:181], v[44:47]
	v_mfma_f32_16x16x32_bf16 v[36:39], v[154:157], v[178:181], v[36:39]
	v_mfma_f32_16x16x32_bf16 v[28:31], v[146:149], v[170:173], v[28:31]
	v_mfma_f32_16x16x32_bf16 v[20:23], v[154:157], v[170:173], v[20:23]
	v_mfma_f32_16x16x32_bf16 v[12:15], v[146:149], v[162:165], v[12:15]
	v_mfma_f32_16x16x32_bf16 v[4:7], v[154:157], v[162:165], v[4:7]
	v_mfma_f32_16x16x32_bf16 v[60:63], v[150:153], v[190:193], v[60:63]
	v_mfma_f32_16x16x32_bf16 v[52:55], v[158:161], v[190:193], v[52:55]
	v_mfma_f32_16x16x32_bf16 v[44:47], v[150:153], v[182:185], v[44:47]
	v_mfma_f32_16x16x32_bf16 v[36:39], v[158:161], v[182:185], v[36:39]
	v_mfma_f32_16x16x32_bf16 v[28:31], v[150:153], v[174:177], v[28:31]
	v_mfma_f32_16x16x32_bf16 v[20:23], v[158:161], v[174:177], v[20:23]
	v_mfma_f32_16x16x32_bf16 v[12:15], v[150:153], v[166:169], v[12:15]
	v_mfma_f32_16x16x32_bf16 v[4:7], v[158:161], v[166:169], v[4:7]
	v_mfma_f32_16x16x32_bf16 v[56:59], v[130:133], v[186:189], v[56:59]
	v_mfma_f32_16x16x32_bf16 v[48:51], v[138:141], v[186:189], v[48:51]
	v_mfma_f32_16x16x32_bf16 v[40:43], v[130:133], v[178:181], v[40:43]
	v_mfma_f32_16x16x32_bf16 v[32:35], v[138:141], v[178:181], v[32:35]
	v_mfma_f32_16x16x32_bf16 v[24:27], v[130:133], v[170:173], v[24:27]
	v_mfma_f32_16x16x32_bf16 v[16:19], v[138:141], v[170:173], v[16:19]
	v_mfma_f32_16x16x32_bf16 v[8:11], v[130:133], v[162:165], v[8:11]
	v_mfma_f32_16x16x32_bf16 v[0:3], v[138:141], v[162:165], v[0:3]
	v_mfma_f32_16x16x32_bf16 v[56:59], v[134:137], v[190:193], v[56:59]
	v_mfma_f32_16x16x32_bf16 v[48:51], v[142:145], v[190:193], v[48:51]
	v_mfma_f32_16x16x32_bf16 v[40:43], v[134:137], v[182:185], v[40:43]
	v_mfma_f32_16x16x32_bf16 v[32:35], v[142:145], v[182:185], v[32:35]
	v_mfma_f32_16x16x32_bf16 v[24:27], v[134:137], v[174:177], v[24:27]
	v_mfma_f32_16x16x32_bf16 v[16:19], v[142:145], v[174:177], v[16:19]
	v_mfma_f32_16x16x32_bf16 v[8:11], v[134:137], v[166:169], v[8:11]
	v_mfma_f32_16x16x32_bf16 v[0:3], v[142:145], v[166:169], v[0:3]
	s_setprio 0
	s_branch .LBB0_1078

; #define PG8_STAGE(bufoff, gbase, voff) do { _Pragma("unroll") for (int _i = 0; _i < 2; ++_i) \
;         __builtin_amdgcn_global_load_lds((const unsigned*)((const char*)(gbase) + (voff)[_i]), (PG8_LAS unsigned*)(lds + (bufoff) + ldsw + _i * 8192), 16, 0, 0); } while (0)
; #define PG8_LDA(dst, b, h) do { _Pragma("unroll") for (int m = 0; m < 4; ++m) _Pragma("unroll") for (int k = 0; k < 2; ++k) dst[m][k] = *(const PG8_LAS bf16x8*)(lds + PG8_SA(b, h) + aoff + m * 2048 + k * 1024); } while (0)
; #define PG8_LDB(dst, b, h) do { _Pragma("unroll") for (int n = 0; n < 2; ++n) _Pragma("unroll") for (int k = 0; k < 2; ++k) dst[n][k] = *(const PG8_LAS bf16x8*)(lds + PG8_SB(b, h) + boff + n * 2048 + k * 1024); } while (0)
; #define PG8_WAIT_V(n) asm volatile("s_waitcnt vmcnt(" #n ")" ::: "memory")
; #define PG8_WAIT_L(n) asm volatile("s_waitcnt lgkmcnt(" #n ")" ::: "memory")
; #define PG8_BAR __builtin_amdgcn_s_barrier()
; #define PG8_SCHED __builtin_amdgcn_sched_barrier(0)
; template <class Epi, class Sched, bool ALIGN_EPI = false, bool SP2 = false>
; __device__ __forceinline__ void gemm_phase(PG8_LAS unsigned char* lds, const Gemm g, const Sched& S, const Epi& E) {
;     ...
;         const char* nA = has_next ? (const char*)g.A + (size_t)nxt.pm * tstep + (size_t)nxt.k0 * kstep : cA; const char* nB = has_next ? (const char*)g.Bt + (size_t)nxt.pn * tstep + (size_t)nxt.k0 * kstep : cB;
;         const int ntu = cur.nt;
;         for (int t = 0; t < ntu; t += 2) {
;             const bool last = (t == ntu - 2);
;             const char* a1 = cA + (size_t)(t + 1) * kstep;
;             const char* a2 = last ? nA : cA + (size_t)(t + 2) * kstep; const char* b2 = last ? nB : cB + (size_t)(t + 2) * kstep;
;             const char* a3 = a2 + kstep; const char* b3 = b2 + kstep;
;             if (last && has_next) S.a_ready(nxt);
;             if constexpr (SP2) {
;             PG8_LDB(B0, 0, 0); PG8_LDB(B1, 0, 1); PG8_SCHED; PG8_LDA(At, 0, 0); PG8_STAGE(PG8_SA(1, 1), a1 + hstep, voffA);
;             PG8_WAIT_V(8); PG8_WAIT_L(0); PG8_BAR; PG8_MMA(0, 0, At, B0); PG8_MMA(0, 1, At, B1); PG8_BAR; PG8_SCHED;
;             PG8_LDA(At, 0, 1); PG8_STAGE(PG8_SB(0, 0), b2, voffB); PG8_STAGE(PG8_SB(0, 1), b2 + hstep, voffB); PG8_STAGE(PG8_SA(0, 0), a2, voffA);
;             PG8_WAIT_V(8); PG8_WAIT_L(0); PG8_BAR; if (full) { PG8_MMA(1, 0, At, B0); PG8_MMA(1, 1, At, B1); } PG8_BAR; PG8_SCHED;
.LBB0_1171:
	s_mov_b64 s[38:39], s[80:81]
	s_add_u32 s80, s38, 0x100
	s_addc_u32 s81, s39, 0
	s_add_i32 s2, 0, 0x10000
	s_cmp_eq_u32 s94, s95
	s_cselect_b32 s35, s77, s81
	s_cselect_b32 s34, s76, s80
	v_add_u32_e32 v128, s2, v195
	s_cselect_b32 s29, s79, s51
	s_cselect_b32 s28, s78, s50
	s_add_i32 s4, 0, 0x14000
	ds_read_b128 v[146:149], v128
	ds_read_b128 v[150:153], v128 offset:1024
	ds_read_b128 v[154:157], v128 offset:2048
	ds_read_b128 v[158:161], v128 offset:3072
	v_add_u32_e32 v128, s4, v195
	ds_read_b128 v[130:133], v128
	ds_read_b128 v[134:137], v128 offset:1024
	ds_read_b128 v[138:141], v128 offset:2048
	ds_read_b128 v[142:145], v128 offset:3072
	v_lshl_add_u64 v[196:197], s[38:39], 0, v[218:219]
	s_add_i32 m0, s70, 0xc000
	s_waitcnt lgkmcnt(7)
	ds_read_b128 v[162:165], v242
	ds_read_b128 v[166:169], v242 offset:1024
	ds_read_b128 v[170:173], v242 offset:2048
	ds_read_b128 v[174:177], v242 offset:3072
	ds_read_b128 v[178:181], v242 offset:4096
	ds_read_b128 v[182:185], v242 offset:5120
	ds_read_b128 v[186:189], v242 offset:6144
	ds_read_b128 v[190:193], v242 offset:7168
	global_load_lds_dwordx4 v[196:197], off
	v_lshl_add_u64 v[196:197], s[38:39], 0, v[220:221]
	s_add_i32 m0, s70, 0xe000
	s_nop 0
	global_load_lds_dwordx4 v[196:197], off
	s_waitcnt vmcnt(8)
	s_waitcnt lgkmcnt(0)
	s_barrier
	s_setprio 1
	s_waitcnt lgkmcnt(0)
	v_mfma_f32_16x16x32_bf16 v[124:127], v[146:149], v[162:165], v[124:127]
	v_mfma_f32_16x16x32_bf16 v[120:123], v[154:157], v[162:165], v[120:123]
	v_mfma_f32_16x16x32_bf16 v[116:119], v[146:149], v[170:173], v[116:119]
	v_mfma_f32_16x16x32_bf16 v[112:115], v[154:157], v[170:173], v[112:115]
	v_mfma_f32_16x16x32_bf16 v[104:107], v[146:149], v[178:181], v[104:107]
	v_mfma_f32_16x16x32_bf16 v[96:99], v[154:157], v[178:181], v[96:99]
	v_mfma_f32_16x16x32_bf16 v[88:91], v[146:149], v[186:189], v[88:91]
	v_mfma_f32_16x16x32_bf16 v[80:83], v[154:157], v[186:189], v[80:83]
	v_mfma_f32_16x16x32_bf16 v[124:127], v[150:153], v[166:169], v[124:127]
	v_mfma_f32_16x16x32_bf16 v[120:123], v[158:161], v[166:169], v[120:123]
	v_mfma_f32_16x16x32_bf16 v[116:119], v[150:153], v[174:177], v[116:119]
	v_mfma_f32_16x16x32_bf16 v[112:115], v[158:161], v[174:177], v[112:115]
	v_mfma_f32_16x16x32_bf16 v[104:107], v[150:153], v[182:185], v[104:107]
	v_mfma_f32_16x16x32_bf16 v[96:99], v[158:161], v[182:185], v[96:99]
	v_mfma_f32_16x16x32_bf16 v[88:91], v[150:153], v[190:193], v[88:91]
	v_mfma_f32_16x16x32_bf16 v[80:83], v[158:161], v[190:193], v[80:83]
	v_mfma_f32_16x16x32_bf16 v[108:111], v[130:133], v[162:165], v[108:111]
	v_mfma_f32_16x16x32_bf16 v[100:103], v[138:141], v[162:165], v[100:103]
	v_mfma_f32_16x16x32_bf16 v[92:95], v[130:133], v[170:173], v[92:95]
	v_mfma_f32_16x16x32_bf16 v[84:87], v[138:141], v[170:173], v[84:87]
	v_mfma_f32_16x16x32_bf16 v[76:79], v[130:133], v[178:181], v[76:79]
	v_mfma_f32_16x16x32_bf16 v[72:75], v[138:141], v[178:181], v[72:75]
	v_mfma_f32_16x16x32_bf16 v[68:71], v[130:133], v[186:189], v[68:71]
	v_mfma_f32_16x16x32_bf16 v[56:59], v[138:141], v[186:189], v[56:59]
	v_mfma_f32_16x16x32_bf16 v[108:111], v[134:137], v[166:169], v[108:111]
	v_mfma_f32_16x16x32_bf16 v[100:103], v[142:145], v[166:169], v[100:103]
	v_mfma_f32_16x16x32_bf16 v[92:95], v[134:137], v[174:177], v[92:95]
	v_mfma_f32_16x16x32_bf16 v[84:87], v[142:145], v[174:177], v[84:87]
	v_mfma_f32_16x16x32_bf16 v[76:79], v[134:137], v[182:185], v[76:79]
	v_mfma_f32_16x16x32_bf16 v[72:75], v[142:145], v[182:185], v[72:75]
	v_mfma_f32_16x16x32_bf16 v[68:71], v[134:137], v[190:193], v[68:71]
	v_mfma_f32_16x16x32_bf16 v[56:59], v[142:145], v[190:193], v[56:59]
	s_setprio 0
	s_barrier
	s_add_i32 s2, s2, s65
	v_lshl_add_u64 v[222:223], s[28:29], 0, v[208:209]
	s_mov_b32 m0, s2
	ds_read_b128 v[186:189], v242 offset:16384
	ds_read_b128 v[190:193], v242 offset:17408
	ds_read_b128 v[178:181], v242 offset:18432
	ds_read_b128 v[182:185], v242 offset:19456
	ds_read_b128 v[170:173], v242 offset:20480
	ds_read_b128 v[174:177], v242 offset:21504
	ds_read_b128 v[162:165], v242 offset:22528
	ds_read_b128 v[166:169], v242 offset:23552
	global_load_lds_dwordx4 v[222:223], off
	s_add_i32 m0, s2, 0x2000
	s_add_u32 s2, s28, 0xb0000
	v_lshl_add_u64 v[224:225], s[28:29], 0, v[212:213]
	s_addc_u32 s3, s29, 0
	s_add_i32 s4, s4, s65
	global_load_lds_dwordx4 v[224:225], off
	v_lshl_add_u64 v[196:197], s[2:3], 0, v[208:209]
	s_mov_b32 m0, s4
	v_lshl_add_u64 v[226:227], s[34:35], 0, v[206:207]
	global_load_lds_dwordx4 v[196:197], off
	v_lshl_add_u64 v[196:197], s[2:3], 0, v[212:213]
	s_add_i32 m0, s4, 0x2000
	v_lshl_add_u64 v[228:229], s[34:35], 0, v[210:211]
	global_load_lds_dwordx4 v[196:197], off
	s_mov_b32 m0, s70
	v_cndmask_b32_e64 v128, 0, 1, s[48:49]
	global_load_lds_dwordx4 v[226:227], off
	s_mov_b32 m0, s71
	v_cmp_ne_u32_e64 s[38:39], 1, v128
	global_load_lds_dwordx4 v[228:229], off
	s_waitcnt vmcnt(8)
	s_waitcnt lgkmcnt(0)
	s_andn2_b64 vcc, exec, s[48:49]
	s_barrier
	s_cbranch_vccnz .LBB0_1173
; #define PG8_MMA(ai, bj, At, Bt) do { __builtin_amdgcn_s_setprio(1); _Pragma("unroll") for (int m = 0; m < 4; ++m) _Pragma("unroll") for (int n = 0; n < 2; ++n) _Pragma("unroll") for (int k = 0; k < 2; ++k) \
;         acc[ai][bj][m][n] = __builtin_amdgcn_mfma_f32_16x16x32_bf16(Bt[n][k], At[m][k], acc[ai][bj][m][n], 0, 0, 0); __builtin_amdgcn_s_setprio(0); } while (0)
; #define PG8_WAIT_V(n) asm volatile("s_waitcnt vmcnt(" #n ")" ::: "memory")
; #define PG8_WAIT_L(n) asm volatile("s_waitcnt lgkmcnt(" #n ")" ::: "memory")
; #define PG8_BAR __builtin_amdgcn_s_barrier()
; #define PG8_SCHED __builtin_amdgcn_sched_barrier(0)
; template <class Epi, class Sched, bool ALIGN_EPI = false, bool SP2 = false>
; __device__ __forceinline__ void gemm_phase(PG8_LAS unsigned char* lds, const Gemm g, const Sched& S, const Epi& E) {
;     ...
;             PG8_WAIT_V(8); PG8_WAIT_L(0); PG8_BAR; if (full) { PG8_MMA(1, 0, At, B0); PG8_MMA(1, 1, At, B1); } PG8_BAR; PG8_SCHED;
	s_setprio 1
	s_waitcnt lgkmcnt(0)
	v_mfma_f32_16x16x32_bf16 v[64:67], v[146:149], v[186:189], v[64:67]
	v_mfma_f32_16x16x32_bf16 v[60:63], v[154:157], v[186:189], v[60:63]
	v_mfma_f32_16x16x32_bf16 v[44:47], v[146:149], v[178:181], v[44:47]
	v_mfma_f32_16x16x32_bf16 v[40:43], v[154:157], v[178:181], v[40:43]
	v_mfma_f32_16x16x32_bf16 v[28:31], v[146:149], v[170:173], v[28:31]
	v_mfma_f32_16x16x32_bf16 v[24:27], v[154:157], v[170:173], v[24:27]
	v_mfma_f32_16x16x32_bf16 v[12:15], v[146:149], v[162:165], v[12:15]
	v_mfma_f32_16x16x32_bf16 v[8:11], v[154:157], v[162:165], v[8:11]
	v_mfma_f32_16x16x32_bf16 v[64:67], v[150:153], v[190:193], v[64:67]
	v_mfma_f32_16x16x32_bf16 v[60:63], v[158:161], v[190:193], v[60:63]
	v_mfma_f32_16x16x32_bf16 v[44:47], v[150:153], v[182:185], v[44:47]
	v_mfma_f32_16x16x32_bf16 v[40:43], v[158:161], v[182:185], v[40:43]
	v_mfma_f32_16x16x32_bf16 v[28:31], v[150:153], v[174:177], v[28:31]
	v_mfma_f32_16x16x32_bf16 v[24:27], v[158:161], v[174:177], v[24:27]
	v_mfma_f32_16x16x32_bf16 v[12:15], v[150:153], v[166:169], v[12:15]
	v_mfma_f32_16x16x32_bf16 v[8:11], v[158:161], v[166:169], v[8:11]
	v_mfma_f32_16x16x32_bf16 v[52:55], v[130:133], v[186:189], v[52:55]
	v_mfma_f32_16x16x32_bf16 v[48:51], v[138:141], v[186:189], v[48:51]
	v_mfma_f32_16x16x32_bf16 v[36:39], v[130:133], v[178:181], v[36:39]
	v_mfma_f32_16x16x32_bf16 v[32:35], v[138:141], v[178:181], v[32:35]
	v_mfma_f32_16x16x32_bf16 v[20:23], v[130:133], v[170:173], v[20:23]
	v_mfma_f32_16x16x32_bf16 v[16:19], v[138:141], v[170:173], v[16:19]
	v_mfma_f32_16x16x32_bf16 v[4:7], v[130:133], v[162:165], v[4:7]
	v_mfma_f32_16x16x32_bf16 v[0:3], v[138:141], v[162:165], v[0:3]
	v_mfma_f32_16x16x32_bf16 v[52:55], v[134:137], v[190:193], v[52:55]
	v_mfma_f32_16x16x32_bf16 v[48:51], v[142:145], v[190:193], v[48:51]
	v_mfma_f32_16x16x32_bf16 v[36:39], v[134:137], v[182:185], v[36:39]
	v_mfma_f32_16x16x32_bf16 v[32:35], v[142:145], v[182:185], v[32:35]
	v_mfma_f32_16x16x32_bf16 v[20:23], v[134:137], v[174:177], v[20:23]
	v_mfma_f32_16x16x32_bf16 v[16:19], v[142:145], v[174:177], v[16:19]
	v_mfma_f32_16x16x32_bf16 v[4:7], v[134:137], v[166:169], v[4:7]
	v_mfma_f32_16x16x32_bf16 v[0:3], v[142:145], v[166:169], v[0:3]
	s_setprio 0
; #define PG8_STAGE(bufoff, gbase, voff) do { _Pragma("unroll") for (int _i = 0; _i < 2; ++_i) \
;         __builtin_amdgcn_global_load_lds((const unsigned*)((const char*)(gbase) + (voff)[_i]), (PG8_LAS unsigned*)(lds + (bufoff) + ldsw + _i * 8192), 16, 0, 0); } while (0)
; #define PG8_LDA(dst, b, h) do { _Pragma("unroll") for (int m = 0; m < 4; ++m) _Pragma("unroll") for (int k = 0; k < 2; ++k) dst[m][k] = *(const PG8_LAS bf16x8*)(lds + PG8_SA(b, h) + aoff + m * 2048 + k * 1024); } while (0)
; #define PG8_LDB(dst, b, h) do { _Pragma("unroll") for (int n = 0; n < 2; ++n) _Pragma("unroll") for (int k = 0; k < 2; ++k) dst[n][k] = *(const PG8_LAS bf16x8*)(lds + PG8_SB(b, h) + boff + n * 2048 + k * 1024); } while (0)
; #define PG8_MMA(ai, bj, At, Bt) do { __builtin_amdgcn_s_setprio(1); _Pragma("unroll") for (int m = 0; m < 4; ++m) _Pragma("unroll") for (int n = 0; n < 2; ++n) _Pragma("unroll") for (int k = 0; k < 2; ++k) \
;         acc[ai][bj][m][n] = __builtin_amdgcn_mfma_f32_16x16x32_bf16(Bt[n][k], At[m][k], acc[ai][bj][m][n], 0, 0, 0); __builtin_amdgcn_s_setprio(0); } while (0)
; #define PG8_WAIT_V(n) asm volatile("s_waitcnt vmcnt(" #n ")" ::: "memory")
; #define PG8_WAIT_L(n) asm volatile("s_waitcnt lgkmcnt(" #n ")" ::: "memory")
; #define PG8_BAR __builtin_amdgcn_s_barrier()
; #define PG8_SCHED __builtin_amdgcn_sched_barrier(0)
; template <class Epi, class Sched, bool ALIGN_EPI = false, bool SP2 = false>
; __device__ __forceinline__ void gemm_phase(PG8_LAS unsigned char* lds, const Gemm g, const Sched& S, const Epi& E) {
;     ...
;             PG8_LDB(B0, 1, 0); PG8_LDB(B1, 1, 1); PG8_SCHED; PG8_LDA(At, 1, 0); PG8_STAGE(PG8_SA(0, 1), a2 + hstep, voffA);
;             PG8_WAIT_V(8); PG8_WAIT_L(0); PG8_BAR; PG8_MMA(0, 0, At, B0); PG8_MMA(0, 1, At, B1); PG8_BAR; PG8_SCHED;
;             PG8_LDA(At, 1, 1); PG8_STAGE(PG8_SB(1, 0), b3, voffB); PG8_STAGE(PG8_SB(1, 1), b3 + hstep, voffB); PG8_STAGE(PG8_SA(1, 0), a3, voffA);
;             PG8_WAIT_V(8); PG8_WAIT_L(0); PG8_BAR; if (full) { PG8_MMA(1, 0, At, B0); PG8_MMA(1, 1, At, B1); } PG8_BAR; PG8_SCHED;
.LBB0_1173:
	s_barrier
	s_add_i32 s4, 0, 0x18000
	v_add_u32_e32 v128, s4, v195
	s_add_i32 s5, 0, 0x1c000
	ds_read_b128 v[146:149], v128
	ds_read_b128 v[150:153], v128 offset:1024
	ds_read_b128 v[154:157], v128 offset:2048
	ds_read_b128 v[158:161], v128 offset:3072
	v_add_u32_e32 v128, s5, v195
	ds_read_b128 v[130:133], v128
	ds_read_b128 v[134:137], v128 offset:1024
	ds_read_b128 v[138:141], v128 offset:2048
	ds_read_b128 v[142:145], v128 offset:3072
	s_add_u32 s2, s34, 0xb0000
	s_addc_u32 s3, s35, 0
	s_mov_b32 m0, s73
	v_lshl_add_u64 v[196:197], s[2:3], 0, v[206:207]
	s_waitcnt lgkmcnt(7)
	ds_read_b128 v[162:165], v242 offset:32768
	ds_read_b128 v[166:169], v242 offset:33792
	ds_read_b128 v[170:173], v242 offset:34816
	ds_read_b128 v[174:177], v242 offset:35840
	ds_read_b128 v[178:181], v242 offset:36864
	ds_read_b128 v[182:185], v242 offset:37888
	ds_read_b128 v[186:189], v242 offset:38912
	ds_read_b128 v[190:193], v242 offset:39936
	global_load_lds_dwordx4 v[196:197], off
	v_lshl_add_u64 v[196:197], s[2:3], 0, v[210:211]
	s_mov_b32 m0, s82
	s_nop 0
	global_load_lds_dwordx4 v[196:197], off
	s_waitcnt vmcnt(8)
	s_waitcnt lgkmcnt(0)
	s_barrier
	s_setprio 1
	s_waitcnt lgkmcnt(0)
	v_mfma_f32_16x16x32_bf16 v[124:127], v[146:149], v[162:165], v[124:127]
	v_mfma_f32_16x16x32_bf16 v[120:123], v[154:157], v[162:165], v[120:123]
	v_mfma_f32_16x16x32_bf16 v[116:119], v[146:149], v[170:173], v[116:119]
	v_mfma_f32_16x16x32_bf16 v[112:115], v[154:157], v[170:173], v[112:115]
	v_mfma_f32_16x16x32_bf16 v[104:107], v[146:149], v[178:181], v[104:107]
	v_mfma_f32_16x16x32_bf16 v[96:99], v[154:157], v[178:181], v[96:99]
	v_mfma_f32_16x16x32_bf16 v[88:91], v[146:149], v[186:189], v[88:91]
	v_mfma_f32_16x16x32_bf16 v[80:83], v[154:157], v[186:189], v[80:83]
	v_mfma_f32_16x16x32_bf16 v[124:127], v[150:153], v[166:169], v[124:127]
	v_mfma_f32_16x16x32_bf16 v[120:123], v[158:161], v[166:169], v[120:123]
	v_mfma_f32_16x16x32_bf16 v[116:119], v[150:153], v[174:177], v[116:119]
	v_mfma_f32_16x16x32_bf16 v[112:115], v[158:161], v[174:177], v[112:115]
	v_mfma_f32_16x16x32_bf16 v[104:107], v[150:153], v[182:185], v[104:107]
	v_mfma_f32_16x16x32_bf16 v[96:99], v[158:161], v[182:185], v[96:99]
	v_mfma_f32_16x16x32_bf16 v[88:91], v[150:153], v[190:193], v[88:91]
	v_mfma_f32_16x16x32_bf16 v[80:83], v[158:161], v[190:193], v[80:83]
	v_mfma_f32_16x16x32_bf16 v[108:111], v[130:133], v[162:165], v[108:111]
	v_mfma_f32_16x16x32_bf16 v[100:103], v[138:141], v[162:165], v[100:103]
	v_mfma_f32_16x16x32_bf16 v[92:95], v[130:133], v[170:173], v[92:95]
	v_mfma_f32_16x16x32_bf16 v[84:87], v[138:141], v[170:173], v[84:87]
	v_mfma_f32_16x16x32_bf16 v[76:79], v[130:133], v[178:181], v[76:79]
	v_mfma_f32_16x16x32_bf16 v[72:75], v[138:141], v[178:181], v[72:75]
	v_mfma_f32_16x16x32_bf16 v[68:71], v[130:133], v[186:189], v[68:71]
	v_mfma_f32_16x16x32_bf16 v[56:59], v[138:141], v[186:189], v[56:59]
	v_mfma_f32_16x16x32_bf16 v[108:111], v[134:137], v[166:169], v[108:111]
	v_mfma_f32_16x16x32_bf16 v[100:103], v[142:145], v[166:169], v[100:103]
	v_mfma_f32_16x16x32_bf16 v[92:95], v[134:137], v[174:177], v[92:95]
	v_mfma_f32_16x16x32_bf16 v[84:87], v[142:145], v[174:177], v[84:87]
	v_mfma_f32_16x16x32_bf16 v[76:79], v[134:137], v[182:185], v[76:79]
	v_mfma_f32_16x16x32_bf16 v[72:75], v[142:145], v[182:185], v[72:75]
	v_mfma_f32_16x16x32_bf16 v[68:71], v[134:137], v[190:193], v[68:71]
	v_mfma_f32_16x16x32_bf16 v[56:59], v[142:145], v[190:193], v[56:59]
	s_setprio 0
	s_barrier
	s_add_i32 s2, s4, s65
	v_lshl_add_u64 v[196:197], v[222:223], 0, s[26:27]
	s_mov_b32 m0, s2
	ds_read_b128 v[186:189], v242 offset:49152
	ds_read_b128 v[190:193], v242 offset:50176
	ds_read_b128 v[178:181], v242 offset:51200
	ds_read_b128 v[182:185], v242 offset:52224
	ds_read_b128 v[170:173], v242 offset:53248
	ds_read_b128 v[174:177], v242 offset:54272
	ds_read_b128 v[162:165], v242 offset:55296
	ds_read_b128 v[166:169], v242 offset:56320
	global_load_lds_dwordx4 v[196:197], off
	s_add_i32 m0, s2, 0x2000
	s_add_u32 s2, s28, 0xb0080
	v_lshl_add_u64 v[196:197], v[224:225], 0, s[26:27]
	s_addc_u32 s3, s29, 0
	s_add_i32 s4, s5, s65
	global_load_lds_dwordx4 v[196:197], off
	v_lshl_add_u64 v[196:197], s[2:3], 0, v[208:209]
	s_mov_b32 m0, s4
	s_and_b64 vcc, exec, s[38:39]
	global_load_lds_dwordx4 v[196:197], off
	v_lshl_add_u64 v[196:197], s[2:3], 0, v[212:213]
	s_add_i32 m0, s4, 0x2000
	s_nop 0
	global_load_lds_dwordx4 v[196:197], off
	v_lshl_add_u64 v[196:197], v[226:227], 0, s[26:27]
	s_mov_b32 m0, s83
	s_nop 0
	global_load_lds_dwordx4 v[196:197], off
	v_lshl_add_u64 v[196:197], v[228:229], 0, s[26:27]
	s_mov_b32 m0, s84
	s_nop 0
	global_load_lds_dwordx4 v[196:197], off
	s_waitcnt vmcnt(8)
	s_waitcnt lgkmcnt(0)
	s_barrier
	s_cbranch_vccnz .LBB0_1170
	s_setprio 1
	s_waitcnt lgkmcnt(0)
	v_mfma_f32_16x16x32_bf16 v[64:67], v[146:149], v[186:189], v[64:67]
	v_mfma_f32_16x16x32_bf16 v[60:63], v[154:157], v[186:189], v[60:63]
	v_mfma_f32_16x16x32_bf16 v[44:47], v[146:149], v[178:181], v[44:47]
	v_mfma_f32_16x16x32_bf16 v[40:43], v[154:157], v[178:181], v[40:43]
	v_mfma_f32_16x16x32_bf16 v[28:31], v[146:149], v[170:173], v[28:31]
	v_mfma_f32_16x16x32_bf16 v[24:27], v[154:157], v[170:173], v[24:27]
	v_mfma_f32_16x16x32_bf16 v[12:15], v[146:149], v[162:165], v[12:15]
	v_mfma_f32_16x16x32_bf16 v[8:11], v[154:157], v[162:165], v[8:11]
	v_mfma_f32_16x16x32_bf16 v[64:67], v[150:153], v[190:193], v[64:67]
	v_mfma_f32_16x16x32_bf16 v[60:63], v[158:161], v[190:193], v[60:63]
	v_mfma_f32_16x16x32_bf16 v[44:47], v[150:153], v[182:185], v[44:47]
	v_mfma_f32_16x16x32_bf16 v[40:43], v[158:161], v[182:185], v[40:43]
	v_mfma_f32_16x16x32_bf16 v[28:31], v[150:153], v[174:177], v[28:31]
	v_mfma_f32_16x16x32_bf16 v[24:27], v[158:161], v[174:177], v[24:27]
	v_mfma_f32_16x16x32_bf16 v[12:15], v[150:153], v[166:169], v[12:15]
	v_mfma_f32_16x16x32_bf16 v[8:11], v[158:161], v[166:169], v[8:11]
	v_mfma_f32_16x16x32_bf16 v[52:55], v[130:133], v[186:189], v[52:55]
	v_mfma_f32_16x16x32_bf16 v[48:51], v[138:141], v[186:189], v[48:51]
	v_mfma_f32_16x16x32_bf16 v[36:39], v[130:133], v[178:181], v[36:39]
	v_mfma_f32_16x16x32_bf16 v[32:35], v[138:141], v[178:181], v[32:35]
	v_mfma_f32_16x16x32_bf16 v[20:23], v[130:133], v[170:173], v[20:23]
	v_mfma_f32_16x16x32_bf16 v[16:19], v[138:141], v[170:173], v[16:19]
	v_mfma_f32_16x16x32_bf16 v[4:7], v[130:133], v[162:165], v[4:7]
	v_mfma_f32_16x16x32_bf16 v[0:3], v[138:141], v[162:165], v[0:3]
	v_mfma_f32_16x16x32_bf16 v[52:55], v[134:137], v[190:193], v[52:55]
	v_mfma_f32_16x16x32_bf16 v[48:51], v[142:145], v[190:193], v[48:51]
	v_mfma_f32_16x16x32_bf16 v[36:39], v[134:137], v[182:185], v[36:39]
	v_mfma_f32_16x16x32_bf16 v[32:35], v[142:145], v[182:185], v[32:35]
	v_mfma_f32_16x16x32_bf16 v[20:23], v[134:137], v[174:177], v[20:23]
	v_mfma_f32_16x16x32_bf16 v[16:19], v[142:145], v[174:177], v[16:19]
	v_mfma_f32_16x16x32_bf16 v[4:7], v[134:137], v[166:169], v[4:7]
	v_mfma_f32_16x16x32_bf16 v[0:3], v[142:145], v[166:169], v[0:3]
	s_setprio 0
	s_branch .LBB0_1170
